# K-loop DMA schedule: 6 pieces issued right after the stage barrier, 2 per MFMA group after
# baseline (speedup 1.0000x reference)
; template <int EPI, int MI>
; DI void gemm_tile(const GemmDesc& g, int tm, int tn, char* smem) {
;     ...
;   const int tid = get_tid(), lane = tid & 63, wave = tid >> 6, r = lane & 31, hh = lane >> 5;
;   const int wm = wave >> 1, wn = wave & 1;
;   const int m0 = tm * BM, n0 = tn * 128;
;   const int nk = g.K >> 6;
;   f32x16 acc[MI][2];
; #pragma unroll
;   for (int a = 0; a < MI; ++a)
; #pragma unroll
;     for (int b = 0; b < 2; ++b)
; #pragma unroll
;       for (int i = 0; i < 16; ++i) acc[a][b][i] = 0.f;
;   const int srow = tid >> 3;
;   const int schunk = (tid & 7) ^ ((srow & 7) ^ ((srow >> 3) & 3));
;     ...
;   const int rowA = wm * (32 * MI) + r, rowB = wn * 64 + r;
;   const int hk = hh ^ ((r & 7) ^ ((r >> 3) & 3));
;     ...
;   G_GLDS(0, 0);
;   asm volatile("s_waitcnt vmcnt(0)" ::: "memory");
;   __syncthreads();
; template <int EPI, int MI>
; DI void gemm_phase(const GemmDesc& g, char* smem, int vb, int nvb) {
;     ...
;   for (int q = start; q < local; q += step) {
;     const int mg = q / per;
;     const int rem = q - mg * per;
;     const int tn = rem / PM;
;     const int tm = mbase + mg * PM + (rem - tn * PM);
;     gemm_tile<EPI, MI>(g, tm, tn, smem);
.LBB0_202:
	s_abs_i32 s1, s5
	v_readlane_b32 s15, v219, 45
	s_mul_hi_u32 s15, s1, s15
	v_readlane_b32 s18, v219, 44
	s_mul_i32 s16, s15, s18
	s_sub_i32 s1, s1, s16
	s_ashr_i32 s0, s5, 31
	s_add_i32 s16, s15, 1
	s_sub_i32 s17, s1, s18
	s_cmp_ge_u32 s1, s18
	s_cselect_b32 s15, s16, s15
	s_cselect_b32 s1, s17, s1
	s_add_i32 s16, s15, 1
	s_cmp_ge_u32 s1, s18
	s_cselect_b32 s1, s16, s15
	s_xor_b32 s1, s1, s0
	s_sub_i32 s15, s1, s0
	s_mul_i32 s16, s15, s18
	s_sub_i32 s16, s5, s16
	s_abs_i32 s18, s16
	v_readlane_b32 s19, v219, 46
	s_mul_hi_u32 s19, s18, s19
	v_readlane_b32 s42, v218, 32
	s_mul_i32 s38, s19, s42
	s_sub_i32 s18, s18, s38
	s_ashr_i32 s17, s16, 31
	s_add_i32 s38, s19, 1
	s_sub_i32 s39, s18, s42
	s_cmp_ge_u32 s18, s42
	s_cselect_b32 s19, s38, s19
	s_cselect_b32 s18, s39, s18
	s_add_i32 s38, s19, 1
	s_cmp_ge_u32 s18, s42
	s_cselect_b32 s18, s38, s19
	s_xor_b32 s18, s18, s17
	s_sub_i32 s39, s18, s17
	s_sub_i32 s15, s15, s39
	v_mov_b32_e32 v4, v132
	s_mul_i32 s15, s15, s42
	s_add_i32 s16, s16, s54
	s_add_i32 s38, s16, s15
	v_ashrrev_i32_e32 v97, 3, v4
	v_ashrrev_i32_e32 v120, 7, v4
	v_bfe_u32 v0, v4, 6, 2
	v_xor_b32_e32 v1, v97, v4
	s_mulk_i32 s38, 0xc0
	v_and_b32_e32 v121, 31, v4
	v_bitop3_b32 v2, v1, v0, 7 bitop3:0x6c
	v_mul_lo_u32 v0, v120, s6
	v_and_b32_e32 v115, 7, v4
	v_or_b32_e32 v5, v0, v121
	v_lshrrev_b32_e32 v0, 3, v4
	s_waitcnt vmcnt(10)
	v_add_u32_e32 v98, s38, v97
	v_bfe_u32 v122, v4, 5, 1
	v_bitop3_b32 v0, v0, v115, 3 bitop3:0x6c
	v_ashrrev_i32_e32 v99, 31, v98
	v_xor_b32_e32 v6, v0, v122
	v_lshlrev_b64 v[0:1], 11, v[98:99]
	v_readlane_b32 s42, v223, 59
	v_lshlrev_b32_e32 v99, 4, v4
	v_readlane_b32 s43, v223, 60
	v_lshlrev_b32_e32 v100, 4, v2
	v_lshl_add_u32 v2, s39, 7, v97
	v_add_u32_e32 v124, 0, v99
	v_lshl_add_u64 v[0:1], s[42:43], 0, v[0:1]
	v_mov_b32_e32 v101, v96
	v_ashrrev_i32_e32 v3, 31, v2
	v_readfirstlane_b32 s15, v124
	v_add_u32_e32 v125, 0x1000, v124
	v_lshl_add_u64 v[0:1], v[0:1], 0, v[100:101]
	v_lshlrev_b64 v[2:3], 11, v[2:3]
	s_mov_b32 m0, s15
	s_mov_b64 s[42:43], 0x10000
	v_readfirstlane_b32 s15, v125
	v_add_u32_e32 v126, 0x2000, v124
	s_waitcnt vmcnt(9)
	v_lshl_add_u64 v[102:103], s[70:71], 0, v[2:3]
	global_load_lds_dwordx4 v[0:1], off
	v_lshl_add_u64 v[2:3], v[0:1], 0, s[42:43]
	s_mov_b32 m0, s15
	s_mov_b64 s[44:45], 0x20000
	v_readfirstlane_b32 s15, v126
	v_add_u32_e32 v127, 0x3000, v124
	global_load_lds_dwordx4 v[2:3], off
	v_lshl_add_u64 v[2:3], v[0:1], 0, s[44:45]
	s_mov_b32 m0, s15
	s_mov_b64 s[46:47], 0x30000
	v_readfirstlane_b32 s15, v127
	v_add_u32_e32 v128, 0x4000, v124
	global_load_lds_dwordx4 v[2:3], off
	v_lshl_add_u64 v[2:3], v[0:1], 0, s[46:47]
	s_mov_b32 m0, s15
	s_mov_b64 s[52:53], 0x40000
	v_readfirstlane_b32 s15, v128
	v_add_u32_e32 v129, 0x5000, v124
	global_load_lds_dwordx4 v[2:3], off
	v_lshl_add_u64 v[2:3], v[0:1], 0, s[52:53]
	s_mov_b32 m0, s15
	s_mov_b64 s[52:53], 0x50000
	v_readfirstlane_b32 s15, v129
	v_add_u32_e32 v130, 0xc000, v124
	global_load_lds_dwordx4 v[2:3], off
	v_lshl_add_u64 v[0:1], v[0:1], 0, s[52:53]
	s_mov_b32 m0, s15
	v_readfirstlane_b32 s15, v130
	v_add_u32_e32 v131, 0xd000, v124
	global_load_lds_dwordx4 v[0:1], off
	v_lshl_add_u64 v[0:1], v[102:103], 0, v[100:101]
	s_mov_b32 m0, s15
	v_readfirstlane_b32 s15, v131
	v_add_u32_e32 v153, 0xe000, v124
	global_load_lds_dwordx4 v[0:1], off
	v_lshl_add_u64 v[2:3], v[0:1], 0, s[42:43]
	s_mov_b32 m0, s15
	v_readfirstlane_b32 s15, v153
	v_add_u32_e32 v154, 0xf000, v124
	global_load_lds_dwordx4 v[2:3], off
	v_lshl_add_u64 v[2:3], v[0:1], 0, s[44:45]
	s_mov_b32 m0, s15
	v_readfirstlane_b32 s15, v154
	global_load_lds_dwordx4 v[2:3], off
	v_lshl_add_u64 v[0:1], v[0:1], 0, s[46:47]
	s_mov_b32 m0, s15
	s_mul_i32 s0, s0, 43
	global_load_lds_dwordx4 v[0:1], off
	s_add_i32 s17, s17, s0
	s_sub_i32 s0, s17, s18
	s_mul_i32 s1, s1, 43
	s_sub_i32 s0, s0, s1
	v_readlane_b32 s1, v218, 33
	v_bfe_u32 v123, v4, 6, 1
	v_lshlrev_b32_e32 v0, 7, v121
	s_mul_i32 s0, s1, s0
	v_lshl_or_b32 v0, v123, 13, v0
	s_add_i32 s0, s0, s4
	v_add_u32_e32 v156, 0, v0
	v_add_u32_e32 v158, s10, v0
	v_add_u32_e32 v0, s0, v97
	v_ashrrev_i32_e32 v1, 31, v0
	s_waitcnt vmcnt(0)
	v_lshlrev_b64 v[0:1], 11, v[0:1]
	v_lshlrev_b32_e32 v157, 4, v6
	v_lshl_add_u64 v[104:105], s[70:71], 0, v[0:1]
	v_mov_b32_e32 v0, 0
	v_lshl_add_u32 v155, v5, 7, 0
	s_mov_b32 s15, 0
	v_mov_b32_e32 v1, v0
	v_mov_b32_e32 v2, v0
	v_mov_b32_e32 v3, v0
	v_mov_b32_e32 v4, v0
	v_mov_b32_e32 v5, v0
	v_mov_b32_e32 v6, v0
	v_mov_b32_e32 v7, v0
	v_mov_b32_e32 v8, v0
	v_mov_b32_e32 v9, v0
	v_mov_b32_e32 v10, v0
	v_mov_b32_e32 v11, v0
	v_mov_b32_e32 v12, v0
	v_mov_b32_e32 v13, v0
	v_mov_b32_e32 v14, v0
	v_mov_b32_e32 v15, v0
	v_mov_b32_e32 v16, v0
	v_mov_b32_e32 v17, v0
	v_mov_b32_e32 v18, v0
	v_mov_b32_e32 v19, v0
	v_mov_b32_e32 v20, v0
	v_mov_b32_e32 v21, v0
	v_mov_b32_e32 v22, v0
	v_mov_b32_e32 v23, v0
	v_mov_b32_e32 v24, v0
	v_mov_b32_e32 v25, v0
	v_mov_b32_e32 v26, v0
	v_mov_b32_e32 v27, v0
	v_mov_b32_e32 v28, v0
	v_mov_b32_e32 v29, v0
	v_mov_b32_e32 v30, v0
	v_mov_b32_e32 v31, v0
	v_mov_b32_e32 v32, v0
	v_mov_b32_e32 v33, v0
	v_mov_b32_e32 v34, v0
	v_mov_b32_e32 v35, v0
	v_mov_b32_e32 v36, v0
	v_mov_b32_e32 v37, v0
	v_mov_b32_e32 v38, v0
	v_mov_b32_e32 v39, v0
	v_mov_b32_e32 v40, v0
	v_mov_b32_e32 v41, v0
	v_mov_b32_e32 v42, v0
	v_mov_b32_e32 v43, v0
	v_mov_b32_e32 v44, v0
	v_mov_b32_e32 v45, v0
	v_mov_b32_e32 v46, v0
	v_mov_b32_e32 v47, v0
	v_mov_b32_e32 v48, v0
	s_waitcnt vmcnt(0)
; template <int EPI, int MI>
; DI void gemm_tile(const GemmDesc& g, int tm, int tn, char* smem) {
;     ...
;   f32x16 acc[MI][2];
; #pragma unroll
;   for (int a = 0; a < MI; ++a)
; #pragma unroll
;     for (int b = 0; b < 2; ++b)
; #pragma unroll
;       for (int i = 0; i < 16; ++i) acc[a][b][i] = 0.f;
;   const int srow = tid >> 3;
;   const int schunk = (tid & 7) ^ ((srow & 7) ^ ((srow >> 3) & 3));
;     ...
;   const int rowA = wm * (32 * MI) + r, rowB = wn * 64 + r;
;   const int hk = hh ^ ((r & 7) ^ ((r >> 3) & 3));
;     ...
;   G_GLDS(0, 0);
;   asm volatile("s_waitcnt vmcnt(0)" ::: "memory");
;   __syncthreads();
;   for (int kt = 0; kt < nk; kt += 2) {
;     if (kt + 1 < nk) G_GLDS(kt + 1, 1);
;     G_COMPUTE(0);
;     asm volatile("s_waitcnt vmcnt(0)" ::: "memory");
;     __syncthreads();
;     if (kt + 1 < nk) {
;       if (kt + 2 < nk) G_GLDS(kt + 2, 0);
;       G_COMPUTE(1);
;       asm volatile("s_waitcnt vmcnt(0)" ::: "memory");
;       __syncthreads();
;     }
;   }
	v_mov_b32_e32 v49, v0
	v_mov_b32_e32 v50, v0
	v_mov_b32_e32 v51, v0
	v_mov_b32_e32 v52, v0
	v_mov_b32_e32 v53, v0
	v_mov_b32_e32 v54, v0
	v_mov_b32_e32 v55, v0
	v_mov_b32_e32 v56, v0
	v_mov_b32_e32 v57, v0
	v_mov_b32_e32 v58, v0
	v_mov_b32_e32 v59, v0
	v_mov_b32_e32 v60, v0
	v_mov_b32_e32 v61, v0
	v_mov_b32_e32 v62, v0
	v_mov_b32_e32 v63, v0
	v_mov_b32_e32 v64, v0
	v_mov_b32_e32 v65, v0
	v_mov_b32_e32 v66, v0
	v_mov_b32_e32 v67, v0
	v_mov_b32_e32 v68, v0
	v_mov_b32_e32 v69, v0
	v_mov_b32_e32 v70, v0
	v_mov_b32_e32 v71, v0
	v_mov_b32_e32 v72, v0
	v_mov_b32_e32 v73, v0
	v_mov_b32_e32 v74, v0
	v_mov_b32_e32 v75, v0
	v_mov_b32_e32 v76, v0
	v_mov_b32_e32 v77, v0
	v_mov_b32_e32 v78, v0
	v_mov_b32_e32 v79, v0
	v_mov_b32_e32 v80, v0
	v_mov_b32_e32 v81, v0
	v_mov_b32_e32 v82, v0
	v_mov_b32_e32 v83, v0
	v_mov_b32_e32 v84, v0
	v_mov_b32_e32 v85, v0
	v_mov_b32_e32 v86, v0
	v_mov_b32_e32 v87, v0
	v_mov_b32_e32 v88, v0
	v_mov_b32_e32 v89, v0
	v_mov_b32_e32 v90, v0
	v_mov_b32_e32 v91, v0
	v_mov_b32_e32 v92, v0
	v_mov_b32_e32 v93, v0
	v_mov_b32_e32 v94, v0
	v_mov_b32_e32 v95, v0
	v_xor_b32_e32 v159, 32, v157
	v_xor_b32_e32 v160, 64, v157
	v_xor_b32_e32 v161, 0x60, v157
	s_mov_b64 s[18:19], 0x80
	s_mov_b64 s[42:43], 0x10080
	v_add_u32_e32 v162, v155, v157
	v_add_u32_e32 v163, v155, v159
	v_add_u32_e32 v164, v155, v160
	v_add_u32_e32 v165, v155, v161
	v_add_u32_e32 v166, v156, v157
	v_add_u32_e32 v167, v156, v159
	v_add_u32_e32 v168, v156, v160
	v_add_u32_e32 v169, v156, v161
	v_add_u32_e32 v170, v158, v157
	v_add_u32_e32 v171, v158, v159
	v_add_u32_e32 v172, v158, v160
	v_add_u32_e32 v173, v158, v161
	v_lshl_add_u64 v[174:175], v[104:105], 0, v[100:101]
	v_lshl_add_u64 v[176:177], v[102:103], 0, v[100:101]
	v_readfirstlane_b32 s100, v124
	s_waitcnt vmcnt(0) lgkmcnt(0)
	s_barrier
	s_add_u32 m0, s100, 0x6000
	v_lshl_add_u64 v[106:107], v[174:175], 0, s[96:97]
	global_load_lds_dwordx4 v[106:107], off
	s_add_u32 m0, s100, 0x7000
	v_lshl_add_u64 v[106:107], v[174:175], 0, s[50:51]
	global_load_lds_dwordx4 v[106:107], off
	s_add_u32 m0, s100, 0x8000
	v_lshl_add_u64 v[106:107], v[174:175], 0, s[24:25]
	global_load_lds_dwordx4 v[106:107], off
	s_add_u32 m0, s100, 0x9000
	v_lshl_add_u64 v[106:107], v[174:175], 0, s[26:27]
	global_load_lds_dwordx4 v[106:107], off
	s_add_u32 m0, s100, 0xa000
	v_lshl_add_u64 v[106:107], v[174:175], 0, s[28:29]
	global_load_lds_dwordx4 v[106:107], off
	s_add_u32 m0, s100, 0xb000
	v_lshl_add_u64 v[106:107], v[174:175], 0, s[30:31]
	global_load_lds_dwordx4 v[106:107], off
	v_lshl_add_u64 v[174:175], v[174:175], 0, s[18:19]
	ds_read_b128 v[236:239], v166 offset:49152
	ds_read_b128 v[240:243], v166 offset:53248
	ds_read_b128 v[224:227], v162
	ds_read_b128 v[228:231], v162 offset:4096
	s_mov_b32 s15, 0
.Lga_loop:
	ds_read_b128 v[232:235], v162 offset:8192
	s_waitcnt lgkmcnt(2)
	v_mfma_f32_32x32x16_bf16 v[80:95], v[224:227], v[236:239], v[80:95]
	v_mfma_f32_32x32x16_bf16 v[64:79], v[224:227], v[240:243], v[64:79]
	s_add_u32 m0, s100, 0x10000
	v_lshl_add_u64 v[106:107], v[176:177], 0, s[18:19]
	global_load_lds_dwordx4 v[106:107], off
	s_add_u32 m0, s100, 0x11000
	v_lshl_add_u64 v[106:107], v[176:177], 0, s[42:43]
	global_load_lds_dwordx4 v[106:107], off
	ds_read_b128 v[244:247], v167 offset:49152
	ds_read_b128 v[248:251], v167 offset:53248
	ds_read_b128 v[224:227], v163
	s_waitcnt lgkmcnt(4)
	v_mfma_f32_32x32x16_bf16 v[48:63], v[228:231], v[236:239], v[48:63]
	v_mfma_f32_32x32x16_bf16 v[32:47], v[228:231], v[240:243], v[32:47]
	s_mov_b64 s[16:17], 0x20080
	s_add_u32 m0, s100, 0x12000
	v_lshl_add_u64 v[106:107], v[176:177], 0, s[16:17]
	global_load_lds_dwordx4 v[106:107], off
	s_mov_b64 s[16:17], 0x30080
	s_add_u32 m0, s100, 0x13000
	v_lshl_add_u64 v[106:107], v[176:177], 0, s[16:17]
	global_load_lds_dwordx4 v[106:107], off
	v_lshl_add_u64 v[176:177], v[176:177], 0, s[18:19]
	ds_read_b128 v[228:231], v163 offset:4096
	s_waitcnt lgkmcnt(4)
	v_mfma_f32_32x32x16_bf16 v[16:31], v[232:235], v[236:239], v[16:31]
	v_mfma_f32_32x32x16_bf16 v[0:15], v[232:235], v[240:243], v[0:15]
	ds_read_b128 v[232:235], v163 offset:8192
	s_waitcnt lgkmcnt(2)
	v_mfma_f32_32x32x16_bf16 v[80:95], v[224:227], v[244:247], v[80:95]
	v_mfma_f32_32x32x16_bf16 v[64:79], v[224:227], v[248:251], v[64:79]
	ds_read_b128 v[236:239], v168 offset:49152
	ds_read_b128 v[240:243], v168 offset:53248
	ds_read_b128 v[224:227], v164
	s_waitcnt lgkmcnt(4)
	v_mfma_f32_32x32x16_bf16 v[48:63], v[228:231], v[244:247], v[48:63]
	v_mfma_f32_32x32x16_bf16 v[32:47], v[228:231], v[248:251], v[32:47]
	ds_read_b128 v[228:231], v164 offset:4096
	s_waitcnt lgkmcnt(4)
	v_mfma_f32_32x32x16_bf16 v[16:31], v[232:235], v[244:247], v[16:31]
	v_mfma_f32_32x32x16_bf16 v[0:15], v[232:235], v[248:251], v[0:15]
	ds_read_b128 v[232:235], v164 offset:8192
	s_waitcnt lgkmcnt(2)
	v_mfma_f32_32x32x16_bf16 v[80:95], v[224:227], v[236:239], v[80:95]
	v_mfma_f32_32x32x16_bf16 v[64:79], v[224:227], v[240:243], v[64:79]
	ds_read_b128 v[244:247], v169 offset:49152
	ds_read_b128 v[248:251], v169 offset:53248
	ds_read_b128 v[224:227], v165
	s_waitcnt lgkmcnt(4)
	v_mfma_f32_32x32x16_bf16 v[48:63], v[228:231], v[236:239], v[48:63]
	v_mfma_f32_32x32x16_bf16 v[32:47], v[228:231], v[240:243], v[32:47]
	ds_read_b128 v[228:231], v165 offset:4096
	s_waitcnt lgkmcnt(4)
	v_mfma_f32_32x32x16_bf16 v[16:31], v[232:235], v[236:239], v[16:31]
	v_mfma_f32_32x32x16_bf16 v[0:15], v[232:235], v[240:243], v[0:15]
	ds_read_b128 v[232:235], v165 offset:8192
	s_waitcnt lgkmcnt(2)
	v_mfma_f32_32x32x16_bf16 v[80:95], v[224:227], v[244:247], v[80:95]
	v_mfma_f32_32x32x16_bf16 v[64:79], v[224:227], v[248:251], v[64:79]
	s_waitcnt lgkmcnt(0)
	s_waitcnt vmcnt(0)
	s_barrier
	s_cmp_eq_u32 s15, 14
	s_cbranch_scc1 .Lga_noearly
	s_mov_b32 m0, s100
	v_lshl_add_u64 v[106:107], v[174:175], 0, s[96:97]
	global_load_lds_dwordx4 v[106:107], off
	s_add_u32 m0, s100, 0x1000
	v_lshl_add_u64 v[106:107], v[174:175], 0, s[50:51]
	global_load_lds_dwordx4 v[106:107], off
	s_add_u32 m0, s100, 0x2000
	v_lshl_add_u64 v[106:107], v[174:175], 0, s[24:25]
	global_load_lds_dwordx4 v[106:107], off
	s_add_u32 m0, s100, 0x3000
	v_lshl_add_u64 v[106:107], v[174:175], 0, s[26:27]
	global_load_lds_dwordx4 v[106:107], off
	s_add_u32 m0, s100, 0x4000
	v_lshl_add_u64 v[106:107], v[174:175], 0, s[28:29]
	global_load_lds_dwordx4 v[106:107], off
	s_add_u32 m0, s100, 0x5000
	v_lshl_add_u64 v[106:107], v[174:175], 0, s[30:31]
	global_load_lds_dwordx4 v[106:107], off
	v_lshl_add_u64 v[174:175], v[174:175], 0, s[18:19]
; template <int EPI, int MI>
; DI void gemm_tile(const GemmDesc& g, int tm, int tn, char* smem) {
;     ...
;   const int rowA = wm * (32 * MI) + r, rowB = wn * 64 + r;
;   const int hk = hh ^ ((r & 7) ^ ((r >> 3) & 3));
;     ...
;   G_GLDS(0, 0);
;   asm volatile("s_waitcnt vmcnt(0)" ::: "memory");
;   __syncthreads();
;   for (int kt = 0; kt < nk; kt += 2) {
;     if (kt + 1 < nk) G_GLDS(kt + 1, 1);
;     G_COMPUTE(0);
;     asm volatile("s_waitcnt vmcnt(0)" ::: "memory");
;     __syncthreads();
;     if (kt + 1 < nk) {
;       if (kt + 2 < nk) G_GLDS(kt + 2, 0);
;       G_COMPUTE(1);
;       asm volatile("s_waitcnt vmcnt(0)" ::: "memory");
;       __syncthreads();
;     }
;   }
.Lga_noearly:
	ds_read_b128 v[236:239], v170
	ds_read_b128 v[240:243], v170 offset:4096
	ds_read_b128 v[224:227], v162 offset:24576
	v_mfma_f32_32x32x16_bf16 v[48:63], v[228:231], v[244:247], v[48:63]
	v_mfma_f32_32x32x16_bf16 v[32:47], v[228:231], v[248:251], v[32:47]
	ds_read_b128 v[228:231], v162 offset:28672
	v_mfma_f32_32x32x16_bf16 v[16:31], v[232:235], v[244:247], v[16:31]
	v_mfma_f32_32x32x16_bf16 v[0:15], v[232:235], v[248:251], v[0:15]
	s_cmp_eq_u32 s15, 14
	s_cbranch_scc1 .Lga_last
	ds_read_b128 v[232:235], v162 offset:32768
	s_waitcnt lgkmcnt(2)
	v_mfma_f32_32x32x16_bf16 v[80:95], v[224:227], v[236:239], v[80:95]
	v_mfma_f32_32x32x16_bf16 v[64:79], v[224:227], v[240:243], v[64:79]
	s_add_u32 m0, s100, 0xc000
	v_lshl_add_u64 v[106:107], v[176:177], 0, s[18:19]
	global_load_lds_dwordx4 v[106:107], off
	s_add_u32 m0, s100, 0xd000
	v_lshl_add_u64 v[106:107], v[176:177], 0, s[42:43]
	global_load_lds_dwordx4 v[106:107], off
	ds_read_b128 v[244:247], v171
	ds_read_b128 v[248:251], v171 offset:4096
	ds_read_b128 v[224:227], v163 offset:24576
	s_waitcnt lgkmcnt(4)
	v_mfma_f32_32x32x16_bf16 v[48:63], v[228:231], v[236:239], v[48:63]
	v_mfma_f32_32x32x16_bf16 v[32:47], v[228:231], v[240:243], v[32:47]
	s_mov_b64 s[16:17], 0x20080
	s_add_u32 m0, s100, 0xe000
	v_lshl_add_u64 v[106:107], v[176:177], 0, s[16:17]
	global_load_lds_dwordx4 v[106:107], off
	s_mov_b64 s[16:17], 0x30080
	s_add_u32 m0, s100, 0xf000
	v_lshl_add_u64 v[106:107], v[176:177], 0, s[16:17]
	global_load_lds_dwordx4 v[106:107], off
	v_lshl_add_u64 v[176:177], v[176:177], 0, s[18:19]
	ds_read_b128 v[228:231], v163 offset:28672
	s_waitcnt lgkmcnt(4)
	v_mfma_f32_32x32x16_bf16 v[16:31], v[232:235], v[236:239], v[16:31]
	v_mfma_f32_32x32x16_bf16 v[0:15], v[232:235], v[240:243], v[0:15]
	ds_read_b128 v[232:235], v163 offset:32768
	s_waitcnt lgkmcnt(2)
	v_mfma_f32_32x32x16_bf16 v[80:95], v[224:227], v[244:247], v[80:95]
	v_mfma_f32_32x32x16_bf16 v[64:79], v[224:227], v[248:251], v[64:79]
	ds_read_b128 v[236:239], v172
	ds_read_b128 v[240:243], v172 offset:4096
	ds_read_b128 v[224:227], v164 offset:24576
	s_waitcnt lgkmcnt(4)
	v_mfma_f32_32x32x16_bf16 v[48:63], v[228:231], v[244:247], v[48:63]
	v_mfma_f32_32x32x16_bf16 v[32:47], v[228:231], v[248:251], v[32:47]
	ds_read_b128 v[228:231], v164 offset:28672
	s_waitcnt lgkmcnt(4)
	v_mfma_f32_32x32x16_bf16 v[16:31], v[232:235], v[244:247], v[16:31]
	v_mfma_f32_32x32x16_bf16 v[0:15], v[232:235], v[248:251], v[0:15]
	ds_read_b128 v[232:235], v164 offset:32768
	s_waitcnt lgkmcnt(2)
	v_mfma_f32_32x32x16_bf16 v[80:95], v[224:227], v[236:239], v[80:95]
	v_mfma_f32_32x32x16_bf16 v[64:79], v[224:227], v[240:243], v[64:79]
	ds_read_b128 v[244:247], v173
	ds_read_b128 v[248:251], v173 offset:4096
	ds_read_b128 v[224:227], v165 offset:24576
	s_waitcnt lgkmcnt(4)
	v_mfma_f32_32x32x16_bf16 v[48:63], v[228:231], v[236:239], v[48:63]
	v_mfma_f32_32x32x16_bf16 v[32:47], v[228:231], v[240:243], v[32:47]
	ds_read_b128 v[228:231], v165 offset:28672
	s_waitcnt lgkmcnt(4)
	v_mfma_f32_32x32x16_bf16 v[16:31], v[232:235], v[236:239], v[16:31]
	v_mfma_f32_32x32x16_bf16 v[0:15], v[232:235], v[240:243], v[0:15]
	ds_read_b128 v[232:235], v165 offset:32768
	s_waitcnt lgkmcnt(2)
	v_mfma_f32_32x32x16_bf16 v[80:95], v[224:227], v[244:247], v[80:95]
	v_mfma_f32_32x32x16_bf16 v[64:79], v[224:227], v[248:251], v[64:79]
	s_waitcnt lgkmcnt(0)
	s_waitcnt vmcnt(0)
	s_barrier
	s_add_u32 m0, s100, 0x6000
	v_lshl_add_u64 v[106:107], v[174:175], 0, s[96:97]
	global_load_lds_dwordx4 v[106:107], off
	s_add_u32 m0, s100, 0x7000
	v_lshl_add_u64 v[106:107], v[174:175], 0, s[50:51]
	global_load_lds_dwordx4 v[106:107], off
	s_add_u32 m0, s100, 0x8000
	v_lshl_add_u64 v[106:107], v[174:175], 0, s[24:25]
	global_load_lds_dwordx4 v[106:107], off
	s_add_u32 m0, s100, 0x9000
	v_lshl_add_u64 v[106:107], v[174:175], 0, s[26:27]
	global_load_lds_dwordx4 v[106:107], off
	s_add_u32 m0, s100, 0xa000
	v_lshl_add_u64 v[106:107], v[174:175], 0, s[28:29]
	global_load_lds_dwordx4 v[106:107], off
	s_add_u32 m0, s100, 0xb000
	v_lshl_add_u64 v[106:107], v[174:175], 0, s[30:31]
	global_load_lds_dwordx4 v[106:107], off
	v_lshl_add_u64 v[174:175], v[174:175], 0, s[18:19]
	ds_read_b128 v[236:239], v166 offset:49152
	ds_read_b128 v[240:243], v166 offset:53248
	ds_read_b128 v[224:227], v162
	v_mfma_f32_32x32x16_bf16 v[48:63], v[228:231], v[244:247], v[48:63]
	v_mfma_f32_32x32x16_bf16 v[32:47], v[228:231], v[248:251], v[32:47]
	ds_read_b128 v[228:231], v162 offset:4096
	v_mfma_f32_32x32x16_bf16 v[16:31], v[232:235], v[244:247], v[16:31]
	v_mfma_f32_32x32x16_bf16 v[0:15], v[232:235], v[248:251], v[0:15]
	s_add_u32 s15, s15, 2
	s_branch .Lga_loop

; template <int EPI, int MI>
; DI void gemm_tile(const GemmDesc& g, int tm, int tn, char* smem) {
;     ...
;   const int tid = get_tid(), lane = tid & 63, wave = tid >> 6, r = lane & 31, hh = lane >> 5;
;   const int wm = wave >> 1, wn = wave & 1;
;   const int m0 = tm * BM, n0 = tn * 128;
;   const int nk = g.K >> 6;
;   f32x16 acc[MI][2];
; #pragma unroll
;   for (int a = 0; a < MI; ++a)
; #pragma unroll
;     for (int b = 0; b < 2; ++b)
; #pragma unroll
;       for (int i = 0; i < 16; ++i) acc[a][b][i] = 0.f;
;   const int srow = tid >> 3;
;   const int schunk = (tid & 7) ^ ((srow & 7) ^ ((srow >> 3) & 3));
;     ...
;   const int rowA = wm * (32 * MI) + r, rowB = wn * 64 + r;
;   const int hk = hh ^ ((r & 7) ^ ((r >> 3) & 3));
;     ...
;   G_GLDS(0, 0);
;   asm volatile("s_waitcnt vmcnt(0)" ::: "memory");
;   __syncthreads();
; template <int EPI, int MI>
; DI void gemm_phase(const GemmDesc& g, char* smem, int vb, int nvb) {
;     ...
;   for (int q = start; q < local; q += step) {
;     const int mg = q / per;
;     const int rem = q - mg * per;
;     const int tn = rem / PM;
;     const int tm = mbase + mg * PM + (rem - tn * PM);
.LBB0_254:
	s_abs_i32 s0, s42
	v_readlane_b32 s1, v219, 48
	s_mul_hi_u32 s1, s0, s1
	v_readlane_b32 s17, v219, 47
	s_mul_i32 s4, s1, s17
	s_sub_i32 s0, s0, s4
	s_ashr_i32 s15, s42, 31
	s_add_i32 s4, s1, 1
	s_sub_i32 s5, s0, s17
	s_cmp_ge_u32 s0, s17
	s_cselect_b32 s1, s4, s1
	s_cselect_b32 s0, s5, s0
	s_add_i32 s4, s1, 1
	s_cmp_ge_u32 s0, s17
	s_cselect_b32 s0, s4, s1
	s_xor_b32 s16, s0, s15
	s_sub_i32 s0, s16, s15
	s_mul_i32 s1, s0, s17
	s_sub_i32 s1, s42, s1
	s_abs_i32 s4, s1
	v_readlane_b32 s5, v219, 46
	s_mul_hi_u32 s5, s4, s5
	v_readlane_b32 s43, v218, 32
	s_mul_i32 s18, s5, s43
	s_sub_i32 s4, s4, s18
	s_ashr_i32 s17, s1, 31
	s_add_i32 s18, s5, 1
	s_sub_i32 s19, s4, s43
	s_cmp_ge_u32 s4, s43
	s_cselect_b32 s5, s18, s5
	s_cselect_b32 s4, s19, s4
	s_add_i32 s18, s5, 1
	s_cmp_ge_u32 s4, s43
	s_cselect_b32 s4, s18, s5
	s_xor_b32 s18, s4, s17
	v_mov_b32_e32 v97, v132
	s_sub_i32 s4, s18, s17
	s_mul_i32 s0, s0, s43
	v_ashrrev_i32_e32 v6, 3, v97
	s_mul_i32 s5, s4, s43
	s_waitcnt vmcnt(8)
	v_ashrrev_i32_e32 v109, 7, v97
	v_bfe_u32 v1, v97, 6, 2
	v_xor_b32_e32 v2, v6, v97
	s_add_i32 s0, s0, s54
	s_sub_i32 s1, s1, s5
	v_and_b32_e32 v108, 31, v97
	v_bitop3_b32 v2, v2, v1, 7 bitop3:0x6c
	v_mul_lo_u32 v1, v109, s6
	s_add_i32 s1, s0, s1
	s_lshl_b32 s0, s4, 7
	v_and_b32_e32 v0, 7, v97
	v_or_b32_e32 v7, v1, v108
	v_lshrrev_b32_e32 v1, 3, v97
	v_readlane_b32 s4, v221, 5
	s_mul_i32 s43, s1, 0xc0
	v_bfe_u32 v115, v97, 5, 1
	v_bitop3_b32 v0, v1, v0, 3 bitop3:0x6c
	v_readlane_b32 s5, v221, 6
	v_xor_b32_e32 v8, v0, v115
	v_add_u32_e32 v3, s43, v6
	v_mov_b64_e32 v[0:1], s[4:5]
	s_movk_i32 s19, 0x1600
	v_mad_i64_i32 v[0:1], s[4:5], v3, s19, v[0:1]
	v_readlane_b32 s4, v221, 10
	v_readlane_b32 s5, v221, 11
	v_lshlrev_b32_e32 v98, 4, v2
	v_add_u32_e32 v9, s0, v6
	v_mov_b64_e32 v[2:3], s[4:5]
	v_lshlrev_b32_e32 v120, 4, v97
	v_mad_i64_i32 v[2:3], s[4:5], v9, s19, v[2:3]
	v_add_u32_e32 v121, 0, v120
	v_mov_b32_e32 v99, v96
	v_readfirstlane_b32 s4, v121
	v_add_u32_e32 v122, 0x1000, v121
	v_lshl_add_u64 v[0:1], v[0:1], 0, v[98:99]
	s_mov_b32 m0, s4
	s_mov_b64 s[44:45], 0x2c000
	v_readfirstlane_b32 s4, v122
	v_add_u32_e32 v123, 0x2000, v121
	global_load_lds_dwordx4 v[0:1], off
	v_lshl_add_u64 v[4:5], v[0:1], 0, s[44:45]
	s_mov_b32 m0, s4
	s_mov_b64 s[46:47], 0x58000
	v_readfirstlane_b32 s4, v123
	v_add_u32_e32 v124, 0x3000, v121
	global_load_lds_dwordx4 v[4:5], off
	v_lshl_add_u64 v[4:5], v[0:1], 0, s[46:47]
	s_mov_b32 m0, s4
	s_mov_b64 s[52:53], 0x84000
	v_readfirstlane_b32 s4, v124
	global_load_lds_dwordx4 v[4:5], off
	v_lshl_add_u64 v[4:5], v[0:1], 0, s[52:53]
	s_mov_b32 m0, s4
	s_mov_b64 s[4:5], 0xb0000
	v_add_u32_e32 v125, 0x4000, v121
	global_load_lds_dwordx4 v[4:5], off
	v_lshl_add_u64 v[4:5], v[0:1], 0, s[4:5]
	v_readfirstlane_b32 s4, v125
	s_mov_b32 m0, s4
	s_mov_b64 s[4:5], 0xdc000
	v_add_u32_e32 v126, 0x5000, v121
	v_lshl_add_u64 v[0:1], v[0:1], 0, s[4:5]
	v_readfirstlane_b32 s4, v126
	v_add_u32_e32 v127, 0xc000, v121
	global_load_lds_dwordx4 v[4:5], off
	s_mov_b32 m0, s4
	v_readfirstlane_b32 s4, v127
	v_add_u32_e32 v128, 0xd000, v121
	global_load_lds_dwordx4 v[0:1], off
	v_lshl_add_u64 v[0:1], v[2:3], 0, v[98:99]
	s_mov_b32 m0, s4
	v_readfirstlane_b32 s4, v128
	v_add_u32_e32 v129, 0xe000, v121
	global_load_lds_dwordx4 v[0:1], off
	v_lshl_add_u64 v[2:3], v[0:1], 0, s[44:45]
	s_mov_b32 m0, s4
	v_readfirstlane_b32 s4, v129
	v_add_u32_e32 v130, 0xf000, v121
	global_load_lds_dwordx4 v[2:3], off
	v_lshl_add_u64 v[2:3], v[0:1], 0, s[46:47]
	s_mov_b32 m0, s4
	v_readfirstlane_b32 s4, v130
	global_load_lds_dwordx4 v[2:3], off
	v_lshl_add_u64 v[0:1], v[0:1], 0, s[52:53]
	s_mov_b32 m0, s4
	s_mul_i32 s15, s15, 7
	global_load_lds_dwordx4 v[0:1], off
	s_add_i32 s17, s17, s15
	s_sub_i32 s4, s17, s18
	s_mul_i32 s16, s16, 7
	s_sub_i32 s4, s4, s16
	v_readlane_b32 s5, v218, 33
	v_lshlrev_b32_e32 v0, 7, v97
	s_mul_i32 s4, s5, s4
	v_and_b32_e32 v0, 0x2f80, v0
	s_add_i32 s4, s4, s39
	s_waitcnt vmcnt(0)
	v_add_u32_e32 v153, 0, v0
	v_add_u32_e32 v155, s10, v0
	v_add_u32_e32 v2, s4, v6
	v_mov_b64_e32 v[0:1], s[70:71]
	v_lshlrev_b32_e32 v154, 4, v8
	v_mad_i64_i32 v[100:101], s[4:5], v2, s19, v[0:1]
	v_mad_i64_i32 v[102:103], s[4:5], v9, s19, v[0:1]
	v_mov_b32_e32 v0, 0
	v_lshl_add_u32 v131, v7, 7, 0
	v_xor_b32_e32 v156, 32, v154
	v_xor_b32_e32 v157, 64, v154
	v_xor_b32_e32 v158, 0x60, v154
	s_mov_b32 s15, 0
	v_mov_b32_e32 v1, v0
	v_mov_b32_e32 v2, v0
	v_mov_b32_e32 v3, v0
	v_mov_b32_e32 v4, v0
	v_mov_b32_e32 v5, v0
	v_mov_b32_e32 v6, v0
	v_mov_b32_e32 v7, v0
	v_mov_b32_e32 v8, v0
	v_mov_b32_e32 v9, v0
	v_mov_b32_e32 v10, v0
	v_mov_b32_e32 v11, v0
	v_mov_b32_e32 v12, v0
	v_mov_b32_e32 v13, v0
	v_mov_b32_e32 v14, v0
	v_mov_b32_e32 v15, v0
	v_mov_b32_e32 v16, v0
	v_mov_b32_e32 v17, v0
	v_mov_b32_e32 v18, v0
	v_mov_b32_e32 v19, v0
	v_mov_b32_e32 v20, v0
	v_mov_b32_e32 v21, v0
	v_mov_b32_e32 v22, v0
	v_mov_b32_e32 v23, v0
	v_mov_b32_e32 v24, v0
	v_mov_b32_e32 v25, v0
	v_mov_b32_e32 v26, v0
	v_mov_b32_e32 v27, v0
	v_mov_b32_e32 v28, v0
	v_mov_b32_e32 v29, v0
	v_mov_b32_e32 v30, v0
	v_mov_b32_e32 v31, v0
	v_mov_b32_e32 v32, v0
	v_mov_b32_e32 v33, v0
	v_mov_b32_e32 v34, v0
	v_mov_b32_e32 v35, v0
	v_mov_b32_e32 v36, v0
	v_mov_b32_e32 v37, v0
	v_mov_b32_e32 v38, v0
	v_mov_b32_e32 v39, v0
	v_mov_b32_e32 v40, v0
	v_mov_b32_e32 v41, v0
	v_mov_b32_e32 v42, v0
	v_mov_b32_e32 v43, v0
	v_mov_b32_e32 v44, v0
	v_mov_b32_e32 v45, v0
	v_mov_b32_e32 v46, v0
	v_mov_b32_e32 v47, v0
	v_mov_b32_e32 v48, v0
	s_waitcnt vmcnt(0)
; template <int EPI, int MI>
; DI void gemm_tile(const GemmDesc& g, int tm, int tn, char* smem) {
;     ...
;   f32x16 acc[MI][2];
; #pragma unroll
;   for (int a = 0; a < MI; ++a)
; #pragma unroll
;     for (int b = 0; b < 2; ++b)
; #pragma unroll
;       for (int i = 0; i < 16; ++i) acc[a][b][i] = 0.f;
;   const int srow = tid >> 3;
;   const int schunk = (tid & 7) ^ ((srow & 7) ^ ((srow >> 3) & 3));
;     ...
;   const int rowA = wm * (32 * MI) + r, rowB = wn * 64 + r;
;   const int hk = hh ^ ((r & 7) ^ ((r >> 3) & 3));
;     ...
;   G_GLDS(0, 0);
;   asm volatile("s_waitcnt vmcnt(0)" ::: "memory");
;   __syncthreads();
;   for (int kt = 0; kt < nk; kt += 2) {
;     if (kt + 1 < nk) G_GLDS(kt + 1, 1);
;     G_COMPUTE(0);
;     asm volatile("s_waitcnt vmcnt(0)" ::: "memory");
;     __syncthreads();
;     if (kt + 1 < nk) {
;       if (kt + 2 < nk) G_GLDS(kt + 2, 0);
;       G_COMPUTE(1);
;       asm volatile("s_waitcnt vmcnt(0)" ::: "memory");
;       __syncthreads();
;     }
;   }
	v_mov_b32_e32 v49, v0
	v_mov_b32_e32 v50, v0
	v_mov_b32_e32 v51, v0
	v_mov_b32_e32 v52, v0
	v_mov_b32_e32 v53, v0
	v_mov_b32_e32 v54, v0
	v_mov_b32_e32 v55, v0
	v_mov_b32_e32 v56, v0
	v_mov_b32_e32 v57, v0
	v_mov_b32_e32 v58, v0
	v_mov_b32_e32 v59, v0
	v_mov_b32_e32 v60, v0
	v_mov_b32_e32 v61, v0
	v_mov_b32_e32 v62, v0
	v_mov_b32_e32 v63, v0
	v_mov_b32_e32 v64, v0
	v_mov_b32_e32 v65, v0
	v_mov_b32_e32 v66, v0
	v_mov_b32_e32 v67, v0
	v_mov_b32_e32 v68, v0
	v_mov_b32_e32 v69, v0
	v_mov_b32_e32 v70, v0
	v_mov_b32_e32 v71, v0
	v_mov_b32_e32 v72, v0
	v_mov_b32_e32 v73, v0
	v_mov_b32_e32 v74, v0
	v_mov_b32_e32 v75, v0
	v_mov_b32_e32 v76, v0
	v_mov_b32_e32 v77, v0
	v_mov_b32_e32 v78, v0
	v_mov_b32_e32 v79, v0
	v_mov_b32_e32 v80, v0
	v_mov_b32_e32 v81, v0
	v_mov_b32_e32 v82, v0
	v_mov_b32_e32 v83, v0
	v_mov_b32_e32 v84, v0
	v_mov_b32_e32 v85, v0
	v_mov_b32_e32 v86, v0
	v_mov_b32_e32 v87, v0
	v_mov_b32_e32 v88, v0
	v_mov_b32_e32 v89, v0
	v_mov_b32_e32 v90, v0
	v_mov_b32_e32 v91, v0
	v_mov_b32_e32 v92, v0
	v_mov_b32_e32 v93, v0
	v_mov_b32_e32 v94, v0
	v_mov_b32_e32 v95, v0
	v_add_u32_e32 v162, v131, v154
	v_add_u32_e32 v163, v131, v156
	v_add_u32_e32 v164, v131, v157
	v_add_u32_e32 v165, v131, v158
	v_add_u32_e32 v166, v153, v154
	v_add_u32_e32 v167, v153, v156
	v_add_u32_e32 v168, v153, v157
	v_add_u32_e32 v169, v153, v158
	v_add_u32_e32 v170, v155, v154
	v_add_u32_e32 v171, v155, v156
	v_add_u32_e32 v172, v155, v157
	v_add_u32_e32 v173, v155, v158
	v_lshl_add_u64 v[252:253], v[100:101], 0, v[98:99]
	v_lshl_add_u64 v[254:255], v[102:103], 0, v[98:99]
	v_readfirstlane_b32 s100, v121
	s_mov_b64 s[4:5], 0x80
	s_waitcnt vmcnt(0) lgkmcnt(0)
	s_barrier
	s_mov_b64 s[16:17], 0x5872080
	s_add_u32 m0, s100, 0x6000
	v_lshl_add_u64 v[106:107], v[252:253], 0, s[16:17]
	global_load_lds_dwordx4 v[106:107], off
	s_mov_b64 s[16:17], 0x589e080
	s_add_u32 m0, s100, 0x7000
	v_lshl_add_u64 v[106:107], v[252:253], 0, s[16:17]
	global_load_lds_dwordx4 v[106:107], off
	s_mov_b64 s[16:17], 0x58ca080
	s_add_u32 m0, s100, 0x8000
	v_lshl_add_u64 v[106:107], v[252:253], 0, s[16:17]
	global_load_lds_dwordx4 v[106:107], off
	s_mov_b64 s[16:17], 0x58f6080
	s_add_u32 m0, s100, 0x9000
	v_lshl_add_u64 v[106:107], v[252:253], 0, s[16:17]
	global_load_lds_dwordx4 v[106:107], off
	s_mov_b64 s[16:17], 0x5922080
	s_add_u32 m0, s100, 0xa000
	v_lshl_add_u64 v[106:107], v[252:253], 0, s[16:17]
	global_load_lds_dwordx4 v[106:107], off
	s_mov_b64 s[16:17], 0x594e080
	s_add_u32 m0, s100, 0xb000
	v_lshl_add_u64 v[106:107], v[252:253], 0, s[16:17]
	global_load_lds_dwordx4 v[106:107], off
	v_lshl_add_u64 v[252:253], v[252:253], 0, s[4:5]
	ds_read_b128 v[236:239], v166 offset:49152
	ds_read_b128 v[240:243], v166 offset:53248
	ds_read_b128 v[224:227], v162
	ds_read_b128 v[228:231], v162 offset:4096
	s_mov_b32 s15, 0
.Lgd_loop:
	ds_read_b128 v[232:235], v162 offset:8192
	s_waitcnt lgkmcnt(2)
	v_mfma_f32_32x32x16_bf16 v[80:95], v[224:227], v[236:239], v[80:95]
	v_mfma_f32_32x32x16_bf16 v[64:79], v[224:227], v[240:243], v[64:79]
	s_mov_b64 s[16:17], 0x1600080
	s_add_u32 m0, s100, 0x10000
	v_lshl_add_u64 v[106:107], v[254:255], 0, s[16:17]
	global_load_lds_dwordx4 v[106:107], off
	s_mov_b64 s[16:17], 0x162c080
	s_add_u32 m0, s100, 0x11000
	v_lshl_add_u64 v[106:107], v[254:255], 0, s[16:17]
	global_load_lds_dwordx4 v[106:107], off
	ds_read_b128 v[244:247], v167 offset:49152
	ds_read_b128 v[248:251], v167 offset:53248
	ds_read_b128 v[224:227], v163
	s_waitcnt lgkmcnt(4)
	v_mfma_f32_32x32x16_bf16 v[48:63], v[228:231], v[236:239], v[48:63]
	v_mfma_f32_32x32x16_bf16 v[32:47], v[228:231], v[240:243], v[32:47]
	s_mov_b64 s[16:17], 0x1658080
	s_add_u32 m0, s100, 0x12000
	v_lshl_add_u64 v[106:107], v[254:255], 0, s[16:17]
	global_load_lds_dwordx4 v[106:107], off
	s_mov_b64 s[16:17], 0x1684080
	s_add_u32 m0, s100, 0x13000
	v_lshl_add_u64 v[106:107], v[254:255], 0, s[16:17]
	global_load_lds_dwordx4 v[106:107], off
	v_lshl_add_u64 v[254:255], v[254:255], 0, s[4:5]
	ds_read_b128 v[228:231], v163 offset:4096
	s_waitcnt lgkmcnt(4)
	v_mfma_f32_32x32x16_bf16 v[16:31], v[232:235], v[236:239], v[16:31]
	v_mfma_f32_32x32x16_bf16 v[0:15], v[232:235], v[240:243], v[0:15]
	ds_read_b128 v[232:235], v163 offset:8192
	s_waitcnt lgkmcnt(2)
	v_mfma_f32_32x32x16_bf16 v[80:95], v[224:227], v[244:247], v[80:95]
	v_mfma_f32_32x32x16_bf16 v[64:79], v[224:227], v[248:251], v[64:79]
	ds_read_b128 v[236:239], v168 offset:49152
	ds_read_b128 v[240:243], v168 offset:53248
	ds_read_b128 v[224:227], v164
	s_waitcnt lgkmcnt(4)
	v_mfma_f32_32x32x16_bf16 v[48:63], v[228:231], v[244:247], v[48:63]
	v_mfma_f32_32x32x16_bf16 v[32:47], v[228:231], v[248:251], v[32:47]
	ds_read_b128 v[228:231], v164 offset:4096
	s_waitcnt lgkmcnt(4)
	v_mfma_f32_32x32x16_bf16 v[16:31], v[232:235], v[244:247], v[16:31]
	v_mfma_f32_32x32x16_bf16 v[0:15], v[232:235], v[248:251], v[0:15]
	ds_read_b128 v[232:235], v164 offset:8192
	s_waitcnt lgkmcnt(2)
	v_mfma_f32_32x32x16_bf16 v[80:95], v[224:227], v[236:239], v[80:95]
	v_mfma_f32_32x32x16_bf16 v[64:79], v[224:227], v[240:243], v[64:79]
	ds_read_b128 v[244:247], v169 offset:49152
	ds_read_b128 v[248:251], v169 offset:53248
	ds_read_b128 v[224:227], v165
	s_waitcnt lgkmcnt(4)
	v_mfma_f32_32x32x16_bf16 v[48:63], v[228:231], v[236:239], v[48:63]
	v_mfma_f32_32x32x16_bf16 v[32:47], v[228:231], v[240:243], v[32:47]
	ds_read_b128 v[228:231], v165 offset:4096
	s_waitcnt lgkmcnt(4)
	v_mfma_f32_32x32x16_bf16 v[16:31], v[232:235], v[236:239], v[16:31]
	v_mfma_f32_32x32x16_bf16 v[0:15], v[232:235], v[240:243], v[0:15]
	ds_read_b128 v[232:235], v165 offset:8192
	s_waitcnt lgkmcnt(2)
	v_mfma_f32_32x32x16_bf16 v[80:95], v[224:227], v[244:247], v[80:95]
	v_mfma_f32_32x32x16_bf16 v[64:79], v[224:227], v[248:251], v[64:79]
	s_waitcnt lgkmcnt(0)
	s_waitcnt vmcnt(0)
	s_barrier
	s_cmp_eq_u32 s15, 42
	s_cbranch_scc1 .Lgd_noearly
	s_mov_b64 s[16:17], 0x5872080
	s_mov_b32 m0, s100
	v_lshl_add_u64 v[106:107], v[252:253], 0, s[16:17]
	global_load_lds_dwordx4 v[106:107], off
	s_mov_b64 s[16:17], 0x589e080
	s_add_u32 m0, s100, 0x1000
	v_lshl_add_u64 v[106:107], v[252:253], 0, s[16:17]
	global_load_lds_dwordx4 v[106:107], off
	s_mov_b64 s[16:17], 0x58ca080
	s_add_u32 m0, s100, 0x2000
	v_lshl_add_u64 v[106:107], v[252:253], 0, s[16:17]
	global_load_lds_dwordx4 v[106:107], off
	s_mov_b64 s[16:17], 0x58f6080
	s_add_u32 m0, s100, 0x3000
	v_lshl_add_u64 v[106:107], v[252:253], 0, s[16:17]
	global_load_lds_dwordx4 v[106:107], off
	s_mov_b64 s[16:17], 0x5922080
	s_add_u32 m0, s100, 0x4000
	v_lshl_add_u64 v[106:107], v[252:253], 0, s[16:17]
	global_load_lds_dwordx4 v[106:107], off
	s_mov_b64 s[16:17], 0x594e080
	s_add_u32 m0, s100, 0x5000
	v_lshl_add_u64 v[106:107], v[252:253], 0, s[16:17]
	global_load_lds_dwordx4 v[106:107], off
	v_lshl_add_u64 v[252:253], v[252:253], 0, s[4:5]
; template <int EPI, int MI>
; DI void gemm_tile(const GemmDesc& g, int tm, int tn, char* smem) {
;     ...
;   const int rowA = wm * (32 * MI) + r, rowB = wn * 64 + r;
;   const int hk = hh ^ ((r & 7) ^ ((r >> 3) & 3));
;     ...
;   G_GLDS(0, 0);
;   asm volatile("s_waitcnt vmcnt(0)" ::: "memory");
;   __syncthreads();
;   for (int kt = 0; kt < nk; kt += 2) {
;     if (kt + 1 < nk) G_GLDS(kt + 1, 1);
;     G_COMPUTE(0);
;     asm volatile("s_waitcnt vmcnt(0)" ::: "memory");
;     __syncthreads();
;     if (kt + 1 < nk) {
;       if (kt + 2 < nk) G_GLDS(kt + 2, 0);
;       G_COMPUTE(1);
;       asm volatile("s_waitcnt vmcnt(0)" ::: "memory");
;       __syncthreads();
;     }
;   }
.Lgd_noearly:
	ds_read_b128 v[236:239], v170
	ds_read_b128 v[240:243], v170 offset:4096
	ds_read_b128 v[224:227], v162 offset:24576
	v_mfma_f32_32x32x16_bf16 v[48:63], v[228:231], v[244:247], v[48:63]
	v_mfma_f32_32x32x16_bf16 v[32:47], v[228:231], v[248:251], v[32:47]
	ds_read_b128 v[228:231], v162 offset:28672
	v_mfma_f32_32x32x16_bf16 v[16:31], v[232:235], v[244:247], v[16:31]
	v_mfma_f32_32x32x16_bf16 v[0:15], v[232:235], v[248:251], v[0:15]
	s_cmp_eq_u32 s15, 42
	s_cbranch_scc1 .Lgd_last
	ds_read_b128 v[232:235], v162 offset:32768
	s_waitcnt lgkmcnt(2)
	v_mfma_f32_32x32x16_bf16 v[80:95], v[224:227], v[236:239], v[80:95]
	v_mfma_f32_32x32x16_bf16 v[64:79], v[224:227], v[240:243], v[64:79]
	s_mov_b64 s[16:17], 0x1600080
	s_add_u32 m0, s100, 0xc000
	v_lshl_add_u64 v[106:107], v[254:255], 0, s[16:17]
	global_load_lds_dwordx4 v[106:107], off
	s_mov_b64 s[16:17], 0x162c080
	s_add_u32 m0, s100, 0xd000
	v_lshl_add_u64 v[106:107], v[254:255], 0, s[16:17]
	global_load_lds_dwordx4 v[106:107], off
	ds_read_b128 v[244:247], v171
	ds_read_b128 v[248:251], v171 offset:4096
	ds_read_b128 v[224:227], v163 offset:24576
	s_waitcnt lgkmcnt(4)
	v_mfma_f32_32x32x16_bf16 v[48:63], v[228:231], v[236:239], v[48:63]
	v_mfma_f32_32x32x16_bf16 v[32:47], v[228:231], v[240:243], v[32:47]
	s_mov_b64 s[16:17], 0x1658080
	s_add_u32 m0, s100, 0xe000
	v_lshl_add_u64 v[106:107], v[254:255], 0, s[16:17]
	global_load_lds_dwordx4 v[106:107], off
	s_mov_b64 s[16:17], 0x1684080
	s_add_u32 m0, s100, 0xf000
	v_lshl_add_u64 v[106:107], v[254:255], 0, s[16:17]
	global_load_lds_dwordx4 v[106:107], off
	v_lshl_add_u64 v[254:255], v[254:255], 0, s[4:5]
	ds_read_b128 v[228:231], v163 offset:28672
	s_waitcnt lgkmcnt(4)
	v_mfma_f32_32x32x16_bf16 v[16:31], v[232:235], v[236:239], v[16:31]
	v_mfma_f32_32x32x16_bf16 v[0:15], v[232:235], v[240:243], v[0:15]
	ds_read_b128 v[232:235], v163 offset:32768
	s_waitcnt lgkmcnt(2)
	v_mfma_f32_32x32x16_bf16 v[80:95], v[224:227], v[244:247], v[80:95]
	v_mfma_f32_32x32x16_bf16 v[64:79], v[224:227], v[248:251], v[64:79]
	ds_read_b128 v[236:239], v172
	ds_read_b128 v[240:243], v172 offset:4096
	ds_read_b128 v[224:227], v164 offset:24576
	s_waitcnt lgkmcnt(4)
	v_mfma_f32_32x32x16_bf16 v[48:63], v[228:231], v[244:247], v[48:63]
	v_mfma_f32_32x32x16_bf16 v[32:47], v[228:231], v[248:251], v[32:47]
	ds_read_b128 v[228:231], v164 offset:28672
	s_waitcnt lgkmcnt(4)
	v_mfma_f32_32x32x16_bf16 v[16:31], v[232:235], v[244:247], v[16:31]
	v_mfma_f32_32x32x16_bf16 v[0:15], v[232:235], v[248:251], v[0:15]
	ds_read_b128 v[232:235], v164 offset:32768
	s_waitcnt lgkmcnt(2)
	v_mfma_f32_32x32x16_bf16 v[80:95], v[224:227], v[236:239], v[80:95]
	v_mfma_f32_32x32x16_bf16 v[64:79], v[224:227], v[240:243], v[64:79]
	ds_read_b128 v[244:247], v173
	ds_read_b128 v[248:251], v173 offset:4096
	ds_read_b128 v[224:227], v165 offset:24576
	s_waitcnt lgkmcnt(4)
	v_mfma_f32_32x32x16_bf16 v[48:63], v[228:231], v[236:239], v[48:63]
	v_mfma_f32_32x32x16_bf16 v[32:47], v[228:231], v[240:243], v[32:47]
	ds_read_b128 v[228:231], v165 offset:28672
	s_waitcnt lgkmcnt(4)
	v_mfma_f32_32x32x16_bf16 v[16:31], v[232:235], v[236:239], v[16:31]
	v_mfma_f32_32x32x16_bf16 v[0:15], v[232:235], v[240:243], v[0:15]
	ds_read_b128 v[232:235], v165 offset:32768
	s_waitcnt lgkmcnt(2)
	v_mfma_f32_32x32x16_bf16 v[80:95], v[224:227], v[244:247], v[80:95]
	v_mfma_f32_32x32x16_bf16 v[64:79], v[224:227], v[248:251], v[64:79]
	s_waitcnt lgkmcnt(0)
	s_waitcnt vmcnt(0)
	s_barrier
	s_mov_b64 s[16:17], 0x5872080
	s_add_u32 m0, s100, 0x6000
	v_lshl_add_u64 v[106:107], v[252:253], 0, s[16:17]
	global_load_lds_dwordx4 v[106:107], off
	s_mov_b64 s[16:17], 0x589e080
	s_add_u32 m0, s100, 0x7000
	v_lshl_add_u64 v[106:107], v[252:253], 0, s[16:17]
	global_load_lds_dwordx4 v[106:107], off
	s_mov_b64 s[16:17], 0x58ca080
	s_add_u32 m0, s100, 0x8000
	v_lshl_add_u64 v[106:107], v[252:253], 0, s[16:17]
	global_load_lds_dwordx4 v[106:107], off
	s_mov_b64 s[16:17], 0x58f6080
	s_add_u32 m0, s100, 0x9000
	v_lshl_add_u64 v[106:107], v[252:253], 0, s[16:17]
	global_load_lds_dwordx4 v[106:107], off
	s_mov_b64 s[16:17], 0x5922080
	s_add_u32 m0, s100, 0xa000
	v_lshl_add_u64 v[106:107], v[252:253], 0, s[16:17]
	global_load_lds_dwordx4 v[106:107], off
	s_mov_b64 s[16:17], 0x594e080
	s_add_u32 m0, s100, 0xb000
	v_lshl_add_u64 v[106:107], v[252:253], 0, s[16:17]
	global_load_lds_dwordx4 v[106:107], off
	v_lshl_add_u64 v[252:253], v[252:253], 0, s[4:5]
	ds_read_b128 v[236:239], v166 offset:49152
	ds_read_b128 v[240:243], v166 offset:53248
	ds_read_b128 v[224:227], v162
	v_mfma_f32_32x32x16_bf16 v[48:63], v[228:231], v[244:247], v[48:63]
	v_mfma_f32_32x32x16_bf16 v[32:47], v[228:231], v[248:251], v[32:47]
	ds_read_b128 v[228:231], v162 offset:4096
	v_mfma_f32_32x32x16_bf16 v[16:31], v[232:235], v[244:247], v[16:31]
	v_mfma_f32_32x32x16_bf16 v[0:15], v[232:235], v[248:251], v[0:15]
	s_add_u32 s15, s15, 2
	s_branch .Lgd_loop

; template <int EPI, int MI>
; DI void gemm_tile(const GemmDesc& g, int tm, int tn, char* smem) {
;     ...
;   const int tid = get_tid(), lane = tid & 63, wave = tid >> 6, r = lane & 31, hh = lane >> 5;
;   const int wm = wave >> 1, wn = wave & 1;
;   const int m0 = tm * BM, n0 = tn * 128;
;   const int nk = g.K >> 6;
;   f32x16 acc[MI][2];
; #pragma unroll
;   for (int a = 0; a < MI; ++a)
; #pragma unroll
;     for (int b = 0; b < 2; ++b)
; #pragma unroll
;       for (int i = 0; i < 16; ++i) acc[a][b][i] = 0.f;
;   const int srow = tid >> 3;
;   const int schunk = (tid & 7) ^ ((srow & 7) ^ ((srow >> 3) & 3));
;     ...
;   const int rowA = wm * (32 * MI) + r, rowB = wn * 64 + r;
;   const int hk = hh ^ ((r & 7) ^ ((r >> 3) & 3));
;     ...
;   G_GLDS(0, 0);
;   asm volatile("s_waitcnt vmcnt(0)" ::: "memory");
;   __syncthreads();
; template <int EPI, int MI>
; DI void gemm_phase(const GemmDesc& g, char* smem, int vb, int nvb) {
;     ...
;   for (int q = start; q < local; q += step) {
;     const int mg = q / per;
;     const int rem = q - mg * per;
;     const int tn = rem / PM;
;     const int tm = mbase + mg * PM + (rem - tn * PM);
.LBB0_371:
	s_abs_i32 s1, s47
	s_mul_hi_u32 s4, s1, s45
	s_mul_i32 s5, s4, s43
	s_sub_i32 s1, s1, s5
	s_ashr_i32 s0, s47, 31
	s_add_i32 s5, s4, 1
	s_sub_i32 s15, s1, s43
	s_cmp_ge_u32 s1, s43
	s_cselect_b32 s4, s5, s4
	s_cselect_b32 s1, s15, s1
	s_add_i32 s5, s4, 1
	s_cmp_ge_u32 s1, s43
	s_cselect_b32 s1, s5, s4
	s_xor_b32 s1, s1, s0
	s_sub_i32 s4, s1, s0
	s_mul_i32 s5, s4, s43
	s_sub_i32 s5, s47, s5
	s_abs_i32 s16, s5
	v_readlane_b32 s17, v219, 46
	s_mul_hi_u32 s17, s16, s17
	v_readlane_b32 s38, v218, 32
	s_mul_i32 s18, s17, s38
	s_sub_i32 s16, s16, s18
	s_ashr_i32 s15, s5, 31
	s_add_i32 s18, s17, 1
	s_sub_i32 s19, s16, s38
	s_cmp_ge_u32 s16, s38
	s_cselect_b32 s17, s18, s17
	s_cselect_b32 s16, s19, s16
	s_add_i32 s18, s17, 1
	s_cmp_ge_u32 s16, s38
	s_cselect_b32 s16, s18, s17
	s_xor_b32 s16, s16, s15
	s_sub_i32 s17, s16, s15
	s_sub_i32 s18, s4, s17
	v_mov_b32_e32 v97, v132
	s_mul_i32 s18, s18, s38
	s_add_i32 s5, s5, s54
	s_add_i32 s48, s5, s18
	v_ashrrev_i32_e32 v0, 7, v97
	v_and_b32_e32 v1, 7, v97
	v_mul_lo_u32 v115, v0, s6
	v_lshrrev_b32_e32 v0, 3, v97
	s_mulk_i32 s48, 0xc0
	s_waitcnt vmcnt(8)
	v_bfe_u32 v109, v97, 5, 1
	v_ashrrev_i32_e32 v8, 3, v97
	v_bitop3_b32 v0, v0, v1, 3 bitop3:0x6c
	v_bfe_u32 v2, v97, 6, 2
	v_xor_b32_e32 v3, v8, v97
	v_xor_b32_e32 v10, v0, v109
	v_add_u32_e32 v0, s48, v8
	s_lshl_b32 s49, s17, 7
	v_bitop3_b32 v2, v3, v2, 7 bitop3:0x6c
	v_ashrrev_i32_e32 v1, 31, v0
	v_readlane_b32 s18, v223, 59
	v_lshlrev_b64 v[0:1], 11, v[0:1]
	v_readlane_b32 s19, v223, 60
	v_lshlrev_b32_e32 v98, 4, v2
	v_add_u32_e32 v2, s49, v8
	v_lshlrev_b32_e32 v120, 4, v97
	v_lshl_add_u64 v[0:1], s[18:19], 0, v[0:1]
	v_ashrrev_i32_e32 v3, 31, v2
	v_readlane_b32 s18, v221, 16
	v_add_u32_e32 v121, 0, v120
	v_mov_b32_e32 v99, v96
	v_lshlrev_b64 v[2:3], 11, v[2:3]
	v_readlane_b32 s19, v221, 17
	v_readfirstlane_b32 s5, v121
	v_add_u32_e32 v122, 0x1000, v121
	v_lshl_add_u64 v[0:1], v[0:1], 0, v[98:99]
	v_lshl_add_u64 v[4:5], s[18:19], 0, v[2:3]
	s_mov_b32 m0, s5
	s_mov_b64 s[18:19], 0x10000
	v_readfirstlane_b32 s5, v122
	v_add_u32_e32 v123, 0x2000, v121
	global_load_lds_dwordx4 v[0:1], off
	v_lshl_add_u64 v[6:7], v[0:1], 0, s[18:19]
	s_mov_b32 m0, s5
	s_mov_b64 s[38:39], 0x20000
	v_readfirstlane_b32 s5, v123
	v_add_u32_e32 v124, 0x3000, v121
	global_load_lds_dwordx4 v[6:7], off
	v_lshl_add_u64 v[6:7], v[0:1], 0, s[38:39]
	s_mov_b32 m0, s5
	s_mov_b64 s[52:53], 0x30000
	v_readfirstlane_b32 s5, v124
	v_add_u32_e32 v125, 0x4000, v121
	global_load_lds_dwordx4 v[6:7], off
	v_lshl_add_u64 v[6:7], v[0:1], 0, s[52:53]
	s_mov_b32 m0, s5
	s_mov_b64 s[72:73], 0x40000
	v_readfirstlane_b32 s5, v125
	v_add_u32_e32 v126, 0x5000, v121
	global_load_lds_dwordx4 v[6:7], off
	v_lshl_add_u64 v[6:7], v[0:1], 0, s[72:73]
	s_mov_b32 m0, s5
	s_mov_b64 s[72:73], 0x50000
	v_readfirstlane_b32 s5, v126
	v_add_u32_e32 v127, 0xc000, v121
	global_load_lds_dwordx4 v[6:7], off
	v_lshl_add_u64 v[0:1], v[0:1], 0, s[72:73]
	s_mov_b32 m0, s5
	v_readfirstlane_b32 s5, v127
	v_add_u32_e32 v128, 0xd000, v121
	global_load_lds_dwordx4 v[0:1], off
	v_lshl_add_u64 v[0:1], v[4:5], 0, v[98:99]
	s_mov_b32 m0, s5
	v_readfirstlane_b32 s5, v128
	v_add_u32_e32 v129, 0xe000, v121
	global_load_lds_dwordx4 v[0:1], off
	v_lshl_add_u64 v[4:5], v[0:1], 0, s[18:19]
	s_mov_b32 m0, s5
	v_readfirstlane_b32 s5, v129
	v_add_u32_e32 v130, 0xf000, v121
	global_load_lds_dwordx4 v[4:5], off
	v_lshl_add_u64 v[4:5], v[0:1], 0, s[38:39]
	s_mov_b32 m0, s5
	v_readfirstlane_b32 s5, v130
	global_load_lds_dwordx4 v[4:5], off
	v_lshl_add_u64 v[0:1], v[0:1], 0, s[52:53]
	s_mov_b32 m0, s5
	s_add_i32 s1, s1, s15
	global_load_lds_dwordx4 v[0:1], off
	s_mul_i32 s4, s20, s4
	s_sub_i32 s1, s1, s4
	s_sub_i32 s1, s1, s16
	s_sub_i32 s0, s1, s0
	v_readlane_b32 s1, v218, 33
	v_lshlrev_b32_e32 v0, 7, v97
	s_mul_i32 s0, s1, s0
	v_and_b32_e32 v0, 0x2f80, v0
	s_add_i32 s0, s0, s46
	v_add_u32_e32 v153, 0, v0
	v_add_u32_e32 v155, s10, v0
	v_add_u32_e32 v0, s0, v8
	v_ashrrev_i32_e32 v1, 31, v0
	v_and_b32_e32 v108, 31, v97
	s_waitcnt vmcnt(0)
	v_lshlrev_b64 v[0:1], 11, v[0:1]
	v_or_b32_e32 v9, v115, v108
	v_lshlrev_b32_e32 v154, 4, v10
	v_lshl_add_u64 v[102:103], s[70:71], 0, v[0:1]
	v_mov_b32_e32 v0, 0
	v_lshl_add_u32 v131, v9, 7, 0
	v_xor_b32_e32 v156, 32, v154
	v_xor_b32_e32 v157, 64, v154
	v_xor_b32_e32 v158, 0x60, v154
	v_lshl_add_u64 v[100:101], s[70:71], 0, v[2:3]
	s_mov_b32 s4, 0
	v_mov_b32_e32 v1, v0
	v_mov_b32_e32 v2, v0
	v_mov_b32_e32 v3, v0
	v_mov_b32_e32 v4, v0
	v_mov_b32_e32 v5, v0
	v_mov_b32_e32 v6, v0
	v_mov_b32_e32 v7, v0
	v_mov_b32_e32 v8, v0
	v_mov_b32_e32 v9, v0
	v_mov_b32_e32 v10, v0
	v_mov_b32_e32 v11, v0
	v_mov_b32_e32 v12, v0
	v_mov_b32_e32 v13, v0
	v_mov_b32_e32 v14, v0
	v_mov_b32_e32 v15, v0
	v_mov_b32_e32 v16, v0
	v_mov_b32_e32 v17, v0
	v_mov_b32_e32 v18, v0
	v_mov_b32_e32 v19, v0
	v_mov_b32_e32 v20, v0
	v_mov_b32_e32 v21, v0
	v_mov_b32_e32 v22, v0
	v_mov_b32_e32 v23, v0
	v_mov_b32_e32 v24, v0
	v_mov_b32_e32 v25, v0
	v_mov_b32_e32 v26, v0
	v_mov_b32_e32 v27, v0
	v_mov_b32_e32 v28, v0
	v_mov_b32_e32 v29, v0
	v_mov_b32_e32 v30, v0
	v_mov_b32_e32 v31, v0
	v_mov_b32_e32 v32, v0
	v_mov_b32_e32 v33, v0
	v_mov_b32_e32 v34, v0
	v_mov_b32_e32 v35, v0
	v_mov_b32_e32 v36, v0
	v_mov_b32_e32 v37, v0
	v_mov_b32_e32 v38, v0
	v_mov_b32_e32 v39, v0
	v_mov_b32_e32 v40, v0
	v_mov_b32_e32 v41, v0
	v_mov_b32_e32 v42, v0
	v_mov_b32_e32 v43, v0
	v_mov_b32_e32 v44, v0
	v_mov_b32_e32 v45, v0
	v_mov_b32_e32 v46, v0
	v_mov_b32_e32 v47, v0
	v_mov_b32_e32 v48, v0
	s_waitcnt vmcnt(0)
; template <int EPI, int MI>
; DI void gemm_tile(const GemmDesc& g, int tm, int tn, char* smem) {
;     ...
;   f32x16 acc[MI][2];
; #pragma unroll
;   for (int a = 0; a < MI; ++a)
; #pragma unroll
;     for (int b = 0; b < 2; ++b)
; #pragma unroll
;       for (int i = 0; i < 16; ++i) acc[a][b][i] = 0.f;
;   const int srow = tid >> 3;
;   const int schunk = (tid & 7) ^ ((srow & 7) ^ ((srow >> 3) & 3));
;     ...
;   const int rowA = wm * (32 * MI) + r, rowB = wn * 64 + r;
;   const int hk = hh ^ ((r & 7) ^ ((r >> 3) & 3));
;     ...
;   G_GLDS(0, 0);
;   asm volatile("s_waitcnt vmcnt(0)" ::: "memory");
;   __syncthreads();
;   for (int kt = 0; kt < nk; kt += 2) {
;     if (kt + 1 < nk) G_GLDS(kt + 1, 1);
;     G_COMPUTE(0);
;     asm volatile("s_waitcnt vmcnt(0)" ::: "memory");
;     __syncthreads();
;     if (kt + 1 < nk) {
;       if (kt + 2 < nk) G_GLDS(kt + 2, 0);
;       G_COMPUTE(1);
;       asm volatile("s_waitcnt vmcnt(0)" ::: "memory");
;       __syncthreads();
;     }
;   }
	v_mov_b32_e32 v49, v0
	v_mov_b32_e32 v50, v0
	v_mov_b32_e32 v51, v0
	v_mov_b32_e32 v52, v0
	v_mov_b32_e32 v53, v0
	v_mov_b32_e32 v54, v0
	v_mov_b32_e32 v55, v0
	v_mov_b32_e32 v56, v0
	v_mov_b32_e32 v57, v0
	v_mov_b32_e32 v58, v0
	v_mov_b32_e32 v59, v0
	v_mov_b32_e32 v60, v0
	v_mov_b32_e32 v61, v0
	v_mov_b32_e32 v62, v0
	v_mov_b32_e32 v63, v0
	v_mov_b32_e32 v64, v0
	v_mov_b32_e32 v65, v0
	v_mov_b32_e32 v66, v0
	v_mov_b32_e32 v67, v0
	v_mov_b32_e32 v68, v0
	v_mov_b32_e32 v69, v0
	v_mov_b32_e32 v70, v0
	v_mov_b32_e32 v71, v0
	v_mov_b32_e32 v72, v0
	v_mov_b32_e32 v73, v0
	v_mov_b32_e32 v74, v0
	v_mov_b32_e32 v75, v0
	v_mov_b32_e32 v76, v0
	v_mov_b32_e32 v77, v0
	v_mov_b32_e32 v78, v0
	v_mov_b32_e32 v79, v0
	v_mov_b32_e32 v80, v0
	v_mov_b32_e32 v81, v0
	v_mov_b32_e32 v82, v0
	v_mov_b32_e32 v83, v0
	v_mov_b32_e32 v84, v0
	v_mov_b32_e32 v85, v0
	v_mov_b32_e32 v86, v0
	v_mov_b32_e32 v87, v0
	v_mov_b32_e32 v88, v0
	v_mov_b32_e32 v89, v0
	v_mov_b32_e32 v90, v0
	v_mov_b32_e32 v91, v0
	v_mov_b32_e32 v92, v0
	v_mov_b32_e32 v93, v0
	v_mov_b32_e32 v94, v0
	v_mov_b32_e32 v95, v0
	v_add_u32_e32 v162, v131, v154
	v_add_u32_e32 v163, v131, v156
	v_add_u32_e32 v164, v131, v157
	v_add_u32_e32 v165, v131, v158
	v_add_u32_e32 v166, v153, v154
	v_add_u32_e32 v167, v153, v156
	v_add_u32_e32 v168, v153, v157
	v_add_u32_e32 v169, v153, v158
	v_add_u32_e32 v170, v155, v154
	v_add_u32_e32 v171, v155, v156
	v_add_u32_e32 v172, v155, v157
	v_add_u32_e32 v173, v155, v158
	v_lshl_add_u64 v[252:253], v[102:103], 0, v[98:99]
	v_lshl_add_u64 v[254:255], v[100:101], 0, v[98:99]
	v_readfirstlane_b32 s100, v121
	s_mov_b64 s[0:1], 0x80
	s_waitcnt vmcnt(0) lgkmcnt(0)
	s_barrier
	s_add_u32 m0, s100, 0x6000
	v_lshl_add_u64 v[106:107], v[252:253], 0, s[96:97]
	global_load_lds_dwordx4 v[106:107], off
	s_add_u32 m0, s100, 0x7000
	v_lshl_add_u64 v[106:107], v[252:253], 0, s[50:51]
	global_load_lds_dwordx4 v[106:107], off
	s_add_u32 m0, s100, 0x8000
	v_lshl_add_u64 v[106:107], v[252:253], 0, s[24:25]
	global_load_lds_dwordx4 v[106:107], off
	s_add_u32 m0, s100, 0x9000
	v_lshl_add_u64 v[106:107], v[252:253], 0, s[26:27]
	global_load_lds_dwordx4 v[106:107], off
	s_add_u32 m0, s100, 0xa000
	v_lshl_add_u64 v[106:107], v[252:253], 0, s[28:29]
	global_load_lds_dwordx4 v[106:107], off
	s_add_u32 m0, s100, 0xb000
	v_lshl_add_u64 v[106:107], v[252:253], 0, s[30:31]
	global_load_lds_dwordx4 v[106:107], off
	v_lshl_add_u64 v[252:253], v[252:253], 0, s[0:1]
	ds_read_b128 v[236:239], v166 offset:49152
	ds_read_b128 v[240:243], v166 offset:53248
	ds_read_b128 v[224:227], v162
	ds_read_b128 v[228:231], v162 offset:4096
	s_mov_b32 s101, 0
.Lgw_loop:
	ds_read_b128 v[232:235], v162 offset:8192
	s_waitcnt lgkmcnt(2)
	v_mfma_f32_32x32x16_bf16 v[80:95], v[224:227], v[236:239], v[80:95]
	v_mfma_f32_32x32x16_bf16 v[64:79], v[224:227], v[240:243], v[64:79]
	s_mov_b64 s[16:17], 0x2100080
	s_add_u32 m0, s100, 0x10000
	v_lshl_add_u64 v[106:107], v[254:255], 0, s[16:17]
	global_load_lds_dwordx4 v[106:107], off
	s_mov_b64 s[16:17], 0x2110080
	s_add_u32 m0, s100, 0x11000
	v_lshl_add_u64 v[106:107], v[254:255], 0, s[16:17]
	global_load_lds_dwordx4 v[106:107], off
	ds_read_b128 v[244:247], v167 offset:49152
	ds_read_b128 v[248:251], v167 offset:53248
	ds_read_b128 v[224:227], v163
	s_waitcnt lgkmcnt(4)
	v_mfma_f32_32x32x16_bf16 v[48:63], v[228:231], v[236:239], v[48:63]
	v_mfma_f32_32x32x16_bf16 v[32:47], v[228:231], v[240:243], v[32:47]
	s_mov_b64 s[16:17], 0x2120080
	s_add_u32 m0, s100, 0x12000
	v_lshl_add_u64 v[106:107], v[254:255], 0, s[16:17]
	global_load_lds_dwordx4 v[106:107], off
	s_mov_b64 s[16:17], 0x2130080
	s_add_u32 m0, s100, 0x13000
	v_lshl_add_u64 v[106:107], v[254:255], 0, s[16:17]
	global_load_lds_dwordx4 v[106:107], off
	v_lshl_add_u64 v[254:255], v[254:255], 0, s[0:1]
	ds_read_b128 v[228:231], v163 offset:4096
	s_waitcnt lgkmcnt(4)
	v_mfma_f32_32x32x16_bf16 v[16:31], v[232:235], v[236:239], v[16:31]
	v_mfma_f32_32x32x16_bf16 v[0:15], v[232:235], v[240:243], v[0:15]
	ds_read_b128 v[232:235], v163 offset:8192
	s_waitcnt lgkmcnt(2)
	v_mfma_f32_32x32x16_bf16 v[80:95], v[224:227], v[244:247], v[80:95]
	v_mfma_f32_32x32x16_bf16 v[64:79], v[224:227], v[248:251], v[64:79]
	ds_read_b128 v[236:239], v168 offset:49152
	ds_read_b128 v[240:243], v168 offset:53248
	ds_read_b128 v[224:227], v164
	s_waitcnt lgkmcnt(4)
	v_mfma_f32_32x32x16_bf16 v[48:63], v[228:231], v[244:247], v[48:63]
	v_mfma_f32_32x32x16_bf16 v[32:47], v[228:231], v[248:251], v[32:47]
	ds_read_b128 v[228:231], v164 offset:4096
	s_waitcnt lgkmcnt(4)
	v_mfma_f32_32x32x16_bf16 v[16:31], v[232:235], v[244:247], v[16:31]
	v_mfma_f32_32x32x16_bf16 v[0:15], v[232:235], v[248:251], v[0:15]
	ds_read_b128 v[232:235], v164 offset:8192
	s_waitcnt lgkmcnt(2)
	v_mfma_f32_32x32x16_bf16 v[80:95], v[224:227], v[236:239], v[80:95]
	v_mfma_f32_32x32x16_bf16 v[64:79], v[224:227], v[240:243], v[64:79]
	ds_read_b128 v[244:247], v169 offset:49152
	ds_read_b128 v[248:251], v169 offset:53248
	ds_read_b128 v[224:227], v165
	s_waitcnt lgkmcnt(4)
	v_mfma_f32_32x32x16_bf16 v[48:63], v[228:231], v[236:239], v[48:63]
	v_mfma_f32_32x32x16_bf16 v[32:47], v[228:231], v[240:243], v[32:47]
	ds_read_b128 v[228:231], v165 offset:4096
	s_waitcnt lgkmcnt(4)
	v_mfma_f32_32x32x16_bf16 v[16:31], v[232:235], v[236:239], v[16:31]
	v_mfma_f32_32x32x16_bf16 v[0:15], v[232:235], v[240:243], v[0:15]
	ds_read_b128 v[232:235], v165 offset:8192
	s_waitcnt lgkmcnt(2)
	v_mfma_f32_32x32x16_bf16 v[80:95], v[224:227], v[244:247], v[80:95]
	v_mfma_f32_32x32x16_bf16 v[64:79], v[224:227], v[248:251], v[64:79]
	s_waitcnt lgkmcnt(0)
	s_waitcnt vmcnt(0)
	s_barrier
	s_cmp_eq_u32 s101, 14
	s_cbranch_scc1 .Lgw_noearly
	s_mov_b32 m0, s100
	v_lshl_add_u64 v[106:107], v[252:253], 0, s[96:97]
	global_load_lds_dwordx4 v[106:107], off
	s_add_u32 m0, s100, 0x1000
	v_lshl_add_u64 v[106:107], v[252:253], 0, s[50:51]
	global_load_lds_dwordx4 v[106:107], off
	s_add_u32 m0, s100, 0x2000
	v_lshl_add_u64 v[106:107], v[252:253], 0, s[24:25]
	global_load_lds_dwordx4 v[106:107], off
	s_add_u32 m0, s100, 0x3000
	v_lshl_add_u64 v[106:107], v[252:253], 0, s[26:27]
	global_load_lds_dwordx4 v[106:107], off
	s_add_u32 m0, s100, 0x4000
	v_lshl_add_u64 v[106:107], v[252:253], 0, s[28:29]
	global_load_lds_dwordx4 v[106:107], off
	s_add_u32 m0, s100, 0x5000
	v_lshl_add_u64 v[106:107], v[252:253], 0, s[30:31]
	global_load_lds_dwordx4 v[106:107], off
	v_lshl_add_u64 v[252:253], v[252:253], 0, s[0:1]
; template <int EPI, int MI>
; DI void gemm_tile(const GemmDesc& g, int tm, int tn, char* smem) {
;     ...
;   const int rowA = wm * (32 * MI) + r, rowB = wn * 64 + r;
;   const int hk = hh ^ ((r & 7) ^ ((r >> 3) & 3));
;     ...
;   G_GLDS(0, 0);
;   asm volatile("s_waitcnt vmcnt(0)" ::: "memory");
;   __syncthreads();
;   for (int kt = 0; kt < nk; kt += 2) {
;     if (kt + 1 < nk) G_GLDS(kt + 1, 1);
;     G_COMPUTE(0);
;     asm volatile("s_waitcnt vmcnt(0)" ::: "memory");
;     __syncthreads();
;     if (kt + 1 < nk) {
;       if (kt + 2 < nk) G_GLDS(kt + 2, 0);
;       G_COMPUTE(1);
;       asm volatile("s_waitcnt vmcnt(0)" ::: "memory");
;       __syncthreads();
;     }
;   }
.Lgw_noearly:
	ds_read_b128 v[236:239], v170
	ds_read_b128 v[240:243], v170 offset:4096
	ds_read_b128 v[224:227], v162 offset:24576
	v_mfma_f32_32x32x16_bf16 v[48:63], v[228:231], v[244:247], v[48:63]
	v_mfma_f32_32x32x16_bf16 v[32:47], v[228:231], v[248:251], v[32:47]
	ds_read_b128 v[228:231], v162 offset:28672
	v_mfma_f32_32x32x16_bf16 v[16:31], v[232:235], v[244:247], v[16:31]
	v_mfma_f32_32x32x16_bf16 v[0:15], v[232:235], v[248:251], v[0:15]
	s_cmp_eq_u32 s101, 14
	s_cbranch_scc1 .Lgw_last
	ds_read_b128 v[232:235], v162 offset:32768
	s_waitcnt lgkmcnt(2)
	v_mfma_f32_32x32x16_bf16 v[80:95], v[224:227], v[236:239], v[80:95]
	v_mfma_f32_32x32x16_bf16 v[64:79], v[224:227], v[240:243], v[64:79]
	s_mov_b64 s[16:17], 0x2100080
	s_add_u32 m0, s100, 0xc000
	v_lshl_add_u64 v[106:107], v[254:255], 0, s[16:17]
	global_load_lds_dwordx4 v[106:107], off
	s_mov_b64 s[16:17], 0x2110080
	s_add_u32 m0, s100, 0xd000
	v_lshl_add_u64 v[106:107], v[254:255], 0, s[16:17]
	global_load_lds_dwordx4 v[106:107], off
	ds_read_b128 v[244:247], v171
	ds_read_b128 v[248:251], v171 offset:4096
	ds_read_b128 v[224:227], v163 offset:24576
	s_waitcnt lgkmcnt(4)
	v_mfma_f32_32x32x16_bf16 v[48:63], v[228:231], v[236:239], v[48:63]
	v_mfma_f32_32x32x16_bf16 v[32:47], v[228:231], v[240:243], v[32:47]
	s_mov_b64 s[16:17], 0x2120080
	s_add_u32 m0, s100, 0xe000
	v_lshl_add_u64 v[106:107], v[254:255], 0, s[16:17]
	global_load_lds_dwordx4 v[106:107], off
	s_mov_b64 s[16:17], 0x2130080
	s_add_u32 m0, s100, 0xf000
	v_lshl_add_u64 v[106:107], v[254:255], 0, s[16:17]
	global_load_lds_dwordx4 v[106:107], off
	v_lshl_add_u64 v[254:255], v[254:255], 0, s[0:1]
	ds_read_b128 v[228:231], v163 offset:28672
	s_waitcnt lgkmcnt(4)
	v_mfma_f32_32x32x16_bf16 v[16:31], v[232:235], v[236:239], v[16:31]
	v_mfma_f32_32x32x16_bf16 v[0:15], v[232:235], v[240:243], v[0:15]
	ds_read_b128 v[232:235], v163 offset:32768
	s_waitcnt lgkmcnt(2)
	v_mfma_f32_32x32x16_bf16 v[80:95], v[224:227], v[244:247], v[80:95]
	v_mfma_f32_32x32x16_bf16 v[64:79], v[224:227], v[248:251], v[64:79]
	ds_read_b128 v[236:239], v172
	ds_read_b128 v[240:243], v172 offset:4096
	ds_read_b128 v[224:227], v164 offset:24576
	s_waitcnt lgkmcnt(4)
	v_mfma_f32_32x32x16_bf16 v[48:63], v[228:231], v[244:247], v[48:63]
	v_mfma_f32_32x32x16_bf16 v[32:47], v[228:231], v[248:251], v[32:47]
	ds_read_b128 v[228:231], v164 offset:28672
	s_waitcnt lgkmcnt(4)
	v_mfma_f32_32x32x16_bf16 v[16:31], v[232:235], v[244:247], v[16:31]
	v_mfma_f32_32x32x16_bf16 v[0:15], v[232:235], v[248:251], v[0:15]
	ds_read_b128 v[232:235], v164 offset:32768
	s_waitcnt lgkmcnt(2)
	v_mfma_f32_32x32x16_bf16 v[80:95], v[224:227], v[236:239], v[80:95]
	v_mfma_f32_32x32x16_bf16 v[64:79], v[224:227], v[240:243], v[64:79]
	ds_read_b128 v[244:247], v173
	ds_read_b128 v[248:251], v173 offset:4096
	ds_read_b128 v[224:227], v165 offset:24576
	s_waitcnt lgkmcnt(4)
	v_mfma_f32_32x32x16_bf16 v[48:63], v[228:231], v[236:239], v[48:63]
	v_mfma_f32_32x32x16_bf16 v[32:47], v[228:231], v[240:243], v[32:47]
	ds_read_b128 v[228:231], v165 offset:28672
	s_waitcnt lgkmcnt(4)
	v_mfma_f32_32x32x16_bf16 v[16:31], v[232:235], v[236:239], v[16:31]
	v_mfma_f32_32x32x16_bf16 v[0:15], v[232:235], v[240:243], v[0:15]
	ds_read_b128 v[232:235], v165 offset:32768
	s_waitcnt lgkmcnt(2)
	v_mfma_f32_32x32x16_bf16 v[80:95], v[224:227], v[244:247], v[80:95]
	v_mfma_f32_32x32x16_bf16 v[64:79], v[224:227], v[248:251], v[64:79]
	s_waitcnt lgkmcnt(0)
	s_waitcnt vmcnt(0)
	s_barrier
	s_add_u32 m0, s100, 0x6000
	v_lshl_add_u64 v[106:107], v[252:253], 0, s[96:97]
	global_load_lds_dwordx4 v[106:107], off
	s_add_u32 m0, s100, 0x7000
	v_lshl_add_u64 v[106:107], v[252:253], 0, s[50:51]
	global_load_lds_dwordx4 v[106:107], off
	s_add_u32 m0, s100, 0x8000
	v_lshl_add_u64 v[106:107], v[252:253], 0, s[24:25]
	global_load_lds_dwordx4 v[106:107], off
	s_add_u32 m0, s100, 0x9000
	v_lshl_add_u64 v[106:107], v[252:253], 0, s[26:27]
	global_load_lds_dwordx4 v[106:107], off
	s_add_u32 m0, s100, 0xa000
	v_lshl_add_u64 v[106:107], v[252:253], 0, s[28:29]
	global_load_lds_dwordx4 v[106:107], off
	s_add_u32 m0, s100, 0xb000
	v_lshl_add_u64 v[106:107], v[252:253], 0, s[30:31]
	global_load_lds_dwordx4 v[106:107], off
	v_lshl_add_u64 v[252:253], v[252:253], 0, s[0:1]
	ds_read_b128 v[236:239], v166 offset:49152
	ds_read_b128 v[240:243], v166 offset:53248
	ds_read_b128 v[224:227], v162
	v_mfma_f32_32x32x16_bf16 v[48:63], v[228:231], v[244:247], v[48:63]
	v_mfma_f32_32x32x16_bf16 v[32:47], v[228:231], v[248:251], v[32:47]
	ds_read_b128 v[228:231], v162 offset:4096
	v_mfma_f32_32x32x16_bf16 v[16:31], v[232:235], v[244:247], v[16:31]
	v_mfma_f32_32x32x16_bf16 v[0:15], v[232:235], v[248:251], v[0:15]
	s_add_u32 s101, s101, 2
	s_branch .Lgw_loop

; template <int EPI, int MI>
; DI void gemm_tile(const GemmDesc& g, int tm, int tn, char* smem) {
;     ...
;   const int tid = get_tid(), lane = tid & 63, wave = tid >> 6, r = lane & 31, hh = lane >> 5;
;   const int wm = wave >> 1, wn = wave & 1;
;   const int m0 = tm * BM, n0 = tn * 128;
;   const int nk = g.K >> 6;
;   f32x16 acc[MI][2];
; #pragma unroll
;   for (int a = 0; a < MI; ++a)
; #pragma unroll
;     for (int b = 0; b < 2; ++b)
; #pragma unroll
;       for (int i = 0; i < 16; ++i) acc[a][b][i] = 0.f;
;   const int srow = tid >> 3;
;   const int schunk = (tid & 7) ^ ((srow & 7) ^ ((srow >> 3) & 3));
;     ...
;   const int rowA = wm * (32 * MI) + r, rowB = wn * 64 + r;
;   const int hk = hh ^ ((r & 7) ^ ((r >> 3) & 3));
;     ...
;   G_GLDS(0, 0);
;   asm volatile("s_waitcnt vmcnt(0)" ::: "memory");
;   __syncthreads();
;   for (int kt = 0; kt < nk; kt += 2) {
;     if (kt + 1 < nk) G_GLDS(kt + 1, 1);
; template <int EPI, int MI>
; DI void gemm_phase(const GemmDesc& g, char* smem, int vb, int nvb) {
;     ...
;   for (int q = start; q < local; q += step) {
;     const int mg = q / per;
;     const int rem = q - mg * per;
;     const int tn = rem / PM;
;     const int tm = mbase + mg * PM + (rem - tn * PM);
.LBB0_1410:
	s_abs_i32 s1, s39
	s_mul_hi_u32 s40, s1, s17
	s_mul_i32 s41, s40, s15
	s_sub_i32 s1, s1, s41
	s_ashr_i32 s0, s39, 31
	s_add_i32 s41, s40, 1
	s_sub_i32 s42, s1, s15
	s_cmp_ge_u32 s1, s15
	s_cselect_b32 s40, s41, s40
	s_cselect_b32 s1, s42, s1
	s_add_i32 s41, s40, 1
	s_cmp_ge_u32 s1, s15
	s_cselect_b32 s1, s41, s40
	s_xor_b32 s1, s1, s0
	s_sub_i32 s40, s1, s0
	s_mul_i32 s41, s40, s15
	s_sub_i32 s42, s39, s41
	s_abs_i32 s41, s42
	s_mul_hi_u32 s44, s41, s18
	s_mul_i32 s45, s44, s4
	s_sub_i32 s41, s41, s45
	s_ashr_i32 s43, s42, 31
	s_add_i32 s45, s44, 1
	s_sub_i32 s46, s41, s4
	s_cmp_ge_u32 s41, s4
	s_cselect_b32 s44, s45, s44
	s_cselect_b32 s41, s46, s41
	s_add_i32 s45, s44, 1
	s_cmp_ge_u32 s41, s4
	s_cselect_b32 s41, s45, s44
	s_xor_b32 s44, s41, s43
	s_sub_i32 s41, s44, s43
	s_sub_i32 s40, s40, s41
	v_mov_b32_e32 v6, v132
	s_mul_i32 s40, s40, s4
	s_add_i32 s42, s42, s16
	s_add_i32 s42, s42, s40
	v_ashrrev_i32_e32 v76, 3, v6
	v_bfe_u32 v0, v6, 6, 2
	v_xor_b32_e32 v1, v76, v6
	s_lshl_b32 s40, s42, 7
	v_bitop3_b32 v2, v1, v0, 7 bitop3:0x6c
	v_ashrrev_i32_e32 v0, 1, v6
	v_and_b32_e32 v77, 7, v6
	v_and_b32_e32 v79, 0xffffffc0, v0
	v_lshrrev_b32_e32 v0, 3, v6
	v_add_u32_e32 v64, s40, v76
	v_bfe_u32 v78, v6, 5, 1
	v_bitop3_b32 v0, v0, v77, 3 bitop3:0x6c
	v_ashrrev_i32_e32 v65, 31, v64
	v_readlane_b32 s46, v223, 59
	v_and_b32_e32 v80, 31, v6
	v_bfe_u32 v81, v6, 6, 1
	v_xor_b32_e32 v9, v0, v78
	v_lshlrev_b64 v[0:1], 11, v[64:65]
	v_readlane_b32 s47, v223, 60
	v_lshlrev_b32_e32 v66, 4, v2
	v_lshl_add_u32 v2, s41, 7, v76
	v_lshlrev_b32_e32 v6, 4, v6
	v_lshl_add_u64 v[0:1], s[46:47], 0, v[0:1]
	v_ashrrev_i32_e32 v3, 31, v2
	v_readlane_b32 s46, v220, 54
	v_add_u32_e32 v65, 0, v6
	v_mov_b32_e32 v67, v96
	v_lshlrev_b64 v[2:3], 11, v[2:3]
	v_readlane_b32 s47, v220, 55
	v_readfirstlane_b32 s42, v65
	v_add_u32_e32 v82, 0x1000, v65
	v_lshl_add_u64 v[0:1], v[0:1], 0, v[66:67]
	v_lshl_add_u64 v[4:5], s[46:47], 0, v[2:3]
	s_mov_b32 m0, s42
	s_mov_b64 s[46:47], 0x10000
	v_readfirstlane_b32 s42, v82
	v_add_u32_e32 v83, 0x2000, v65
	global_load_lds_dwordx4 v[0:1], off
	v_lshl_add_u64 v[6:7], v[0:1], 0, s[46:47]
	s_mov_b32 m0, s42
	s_mov_b64 s[52:53], 0x20000
	v_readfirstlane_b32 s42, v83
	v_add_u32_e32 v84, 0x3000, v65
	global_load_lds_dwordx4 v[6:7], off
	v_lshl_add_u64 v[6:7], v[0:1], 0, s[52:53]
	s_mov_b32 m0, s42
	s_mov_b64 s[72:73], 0x30000
	v_readfirstlane_b32 s42, v84
	v_add_u32_e32 v85, 0x8000, v65
	global_load_lds_dwordx4 v[6:7], off
	v_lshl_add_u64 v[0:1], v[0:1], 0, s[72:73]
	s_mov_b32 m0, s42
	v_readfirstlane_b32 s42, v85
	v_add_u32_e32 v86, 0x9000, v65
	global_load_lds_dwordx4 v[0:1], off
	v_lshl_add_u64 v[0:1], v[4:5], 0, v[66:67]
	s_mov_b32 m0, s42
	v_readfirstlane_b32 s42, v86
	v_add_u32_e32 v87, 0xa000, v65
	global_load_lds_dwordx4 v[0:1], off
	v_lshl_add_u64 v[4:5], v[0:1], 0, s[46:47]
	s_mov_b32 m0, s42
	v_readfirstlane_b32 s42, v87
	v_add_u32_e32 v88, 0xb000, v65
	global_load_lds_dwordx4 v[4:5], off
	v_lshl_add_u64 v[4:5], v[0:1], 0, s[52:53]
	s_mov_b32 m0, s42
	v_readfirstlane_b32 s42, v88
	global_load_lds_dwordx4 v[4:5], off
	v_lshl_add_u64 v[0:1], v[0:1], 0, s[72:73]
	s_mov_b32 m0, s42
	s_mul_i32 s0, s0, 43
	global_load_lds_dwordx4 v[0:1], off
	s_add_i32 s43, s43, s0
	s_sub_i32 s0, s43, s44
	s_mul_i32 s1, s1, 43
	s_sub_i32 s0, s0, s1
	v_lshlrev_b32_e32 v0, 7, v80
	s_mul_i32 s0, s38, s0
	v_lshl_or_b32 v0, v81, 13, v0
	s_add_i32 s0, s0, s19
	v_add_u32_e32 v90, 0, v0
	v_add_u32_e32 v0, s0, v76
	v_ashrrev_i32_e32 v1, 31, v0
	s_waitcnt vmcnt(0)
	v_lshlrev_b64 v[0:1], 11, v[0:1]
	v_or_b32_e32 v8, v79, v80
	v_lshlrev_b32_e32 v91, 4, v9
	v_lshl_add_u64 v[68:69], s[70:71], 0, v[0:1]
	v_mov_b32_e32 v0, 0
	v_lshl_add_u32 v89, v8, 7, 0
	v_xor_b32_e32 v92, 32, v91
	v_xor_b32_e32 v93, 64, v91
	v_xor_b32_e32 v94, 0x60, v91
	v_lshl_add_u64 v[70:71], s[70:71], 0, v[2:3]
	s_mov_b32 s42, 0
	v_mov_b32_e32 v1, v0
	v_mov_b32_e32 v2, v0
	v_mov_b32_e32 v3, v0
	v_mov_b32_e32 v4, v0
	v_mov_b32_e32 v5, v0
	v_mov_b32_e32 v6, v0
	v_mov_b32_e32 v7, v0
	v_mov_b32_e32 v8, v0
	v_mov_b32_e32 v9, v0
	v_mov_b32_e32 v10, v0
	v_mov_b32_e32 v11, v0
	v_mov_b32_e32 v12, v0
	v_mov_b32_e32 v13, v0
	v_mov_b32_e32 v14, v0
	v_mov_b32_e32 v15, v0
	v_mov_b32_e32 v16, v0
	v_mov_b32_e32 v17, v0
	v_mov_b32_e32 v18, v0
	v_mov_b32_e32 v19, v0
	v_mov_b32_e32 v20, v0
	v_mov_b32_e32 v21, v0
	v_mov_b32_e32 v22, v0
	v_mov_b32_e32 v23, v0
	v_mov_b32_e32 v24, v0
	v_mov_b32_e32 v25, v0
	v_mov_b32_e32 v26, v0
	v_mov_b32_e32 v27, v0
	v_mov_b32_e32 v28, v0
	v_mov_b32_e32 v29, v0
	v_mov_b32_e32 v30, v0
	v_mov_b32_e32 v31, v0
	v_mov_b32_e32 v32, v0
	v_mov_b32_e32 v33, v0
	v_mov_b32_e32 v34, v0
	v_mov_b32_e32 v35, v0
	v_mov_b32_e32 v36, v0
	v_mov_b32_e32 v37, v0
	v_mov_b32_e32 v38, v0
	v_mov_b32_e32 v39, v0
	v_mov_b32_e32 v40, v0
	v_mov_b32_e32 v41, v0
	v_mov_b32_e32 v42, v0
	v_mov_b32_e32 v43, v0
	v_mov_b32_e32 v44, v0
	v_mov_b32_e32 v45, v0
	v_mov_b32_e32 v46, v0
	v_mov_b32_e32 v47, v0
	v_mov_b32_e32 v48, v0
	v_mov_b32_e32 v49, v0
	v_mov_b32_e32 v50, v0
	v_mov_b32_e32 v51, v0
	v_mov_b32_e32 v52, v0
	v_mov_b32_e32 v53, v0
	v_mov_b32_e32 v54, v0
	v_mov_b32_e32 v55, v0
	v_mov_b32_e32 v56, v0
	v_mov_b32_e32 v57, v0
	v_mov_b32_e32 v58, v0
	v_mov_b32_e32 v59, v0
	v_mov_b32_e32 v60, v0
	v_mov_b32_e32 v61, v0
	v_mov_b32_e32 v62, v0
	v_mov_b32_e32 v63, v0
	v_add_u32_e32 v98, v89, v91
	v_add_u32_e32 v99, v89, v92
	v_add_u32_e32 v100, v89, v93
	v_add_u32_e32 v101, v89, v94
	v_add_u32_e32 v102, v90, v91
	v_add_u32_e32 v103, v90, v92
	v_add_u32_e32 v104, v90, v93
	v_add_u32_e32 v105, v90, v94
	v_lshl_add_u64 v[72:73], v[68:69], 0, v[66:67]
	v_lshl_add_u64 v[74:75], v[70:71], 0, v[66:67]
	v_readfirstlane_b32 s100, v65
	s_mov_b64 s[44:45], 0x80
	s_waitcnt vmcnt(0) lgkmcnt(0)
	s_barrier
	s_add_u32 m0, s100, 0x4000
	v_lshl_add_u64 v[106:107], v[72:73], 0, s[96:97]
	global_load_lds_dwordx4 v[106:107], off
	s_add_u32 m0, s100, 0x5000
	v_lshl_add_u64 v[106:107], v[72:73], 0, s[50:51]
	global_load_lds_dwordx4 v[106:107], off
	s_add_u32 m0, s100, 0x6000
	v_lshl_add_u64 v[106:107], v[72:73], 0, s[24:25]
	global_load_lds_dwordx4 v[106:107], off
	s_add_u32 m0, s100, 0x7000
	v_lshl_add_u64 v[106:107], v[72:73], 0, s[26:27]
	global_load_lds_dwordx4 v[106:107], off
	v_lshl_add_u64 v[72:73], v[72:73], 0, s[44:45]
	s_mov_b64 s[0:1], 0xb00080
	s_add_u32 m0, s100, 0xc000
	v_lshl_add_u64 v[106:107], v[74:75], 0, s[0:1]
	global_load_lds_dwordx4 v[106:107], off
	s_mov_b64 s[0:1], 0xb10080
	s_add_u32 m0, s100, 0xd000
	v_lshl_add_u64 v[106:107], v[74:75], 0, s[0:1]
	global_load_lds_dwordx4 v[106:107], off
	ds_read_b128 v[240:243], v102 offset:32768
	ds_read_b128 v[244:247], v102 offset:36864
	ds_read_b128 v[224:227], v98
	ds_read_b128 v[228:231], v98 offset:4096
	s_mov_b32 s101, 0
; template <int EPI, int MI>
; DI void gemm_tile(const GemmDesc& g, int tm, int tn, char* smem) {
;     ...
;   const int rowA = wm * (32 * MI) + r, rowB = wn * 64 + r;
;   const int hk = hh ^ ((r & 7) ^ ((r >> 3) & 3));
;     ...
;   G_GLDS(0, 0);
;   asm volatile("s_waitcnt vmcnt(0)" ::: "memory");
;   __syncthreads();
;   for (int kt = 0; kt < nk; kt += 2) {
;     if (kt + 1 < nk) G_GLDS(kt + 1, 1);
;     G_COMPUTE(0);
;     asm volatile("s_waitcnt vmcnt(0)" ::: "memory");
;     __syncthreads();
;     if (kt + 1 < nk) {
;       if (kt + 2 < nk) G_GLDS(kt + 2, 0);
;       G_COMPUTE(1);
;       asm volatile("s_waitcnt vmcnt(0)" ::: "memory");
;       __syncthreads();
;     }
;   }
.Lgc_loop:
	ds_read_b128 v[248:251], v103 offset:32768
	ds_read_b128 v[252:255], v103 offset:36864
	ds_read_b128 v[232:235], v99
	s_waitcnt lgkmcnt(4)
	v_mfma_f32_32x32x16_bf16 v[48:63], v[224:227], v[240:243], v[48:63]
	v_mfma_f32_32x32x16_bf16 v[32:47], v[224:227], v[244:247], v[32:47]
	s_mov_b64 s[0:1], 0xb20080
	s_add_u32 m0, s100, 0xe000
	v_lshl_add_u64 v[106:107], v[74:75], 0, s[0:1]
	global_load_lds_dwordx4 v[106:107], off
	s_mov_b64 s[0:1], 0xb30080
	s_add_u32 m0, s100, 0xf000
	v_lshl_add_u64 v[106:107], v[74:75], 0, s[0:1]
	global_load_lds_dwordx4 v[106:107], off
	v_lshl_add_u64 v[74:75], v[74:75], 0, s[44:45]
	ds_read_b128 v[236:239], v99 offset:4096
	s_waitcnt lgkmcnt(4)
	v_mfma_f32_32x32x16_bf16 v[16:31], v[228:231], v[240:243], v[16:31]
	v_mfma_f32_32x32x16_bf16 v[0:15], v[228:231], v[244:247], v[0:15]
	ds_read_b128 v[240:243], v104 offset:32768
	ds_read_b128 v[244:247], v104 offset:36864
	ds_read_b128 v[224:227], v100
	s_waitcnt lgkmcnt(4)
	v_mfma_f32_32x32x16_bf16 v[48:63], v[232:235], v[248:251], v[48:63]
	v_mfma_f32_32x32x16_bf16 v[32:47], v[232:235], v[252:255], v[32:47]
	ds_read_b128 v[228:231], v100 offset:4096
	s_waitcnt lgkmcnt(4)
	v_mfma_f32_32x32x16_bf16 v[16:31], v[236:239], v[248:251], v[16:31]
	v_mfma_f32_32x32x16_bf16 v[0:15], v[236:239], v[252:255], v[0:15]
	ds_read_b128 v[248:251], v105 offset:32768
	ds_read_b128 v[252:255], v105 offset:36864
	ds_read_b128 v[232:235], v101
	s_waitcnt lgkmcnt(4)
	v_mfma_f32_32x32x16_bf16 v[48:63], v[224:227], v[240:243], v[48:63]
	v_mfma_f32_32x32x16_bf16 v[32:47], v[224:227], v[244:247], v[32:47]
	ds_read_b128 v[236:239], v101 offset:4096
	s_waitcnt lgkmcnt(4)
	v_mfma_f32_32x32x16_bf16 v[16:31], v[228:231], v[240:243], v[16:31]
	v_mfma_f32_32x32x16_bf16 v[0:15], v[228:231], v[244:247], v[0:15]
	s_waitcnt lgkmcnt(0)
	s_waitcnt vmcnt(0)
	s_barrier
	s_cmp_eq_u32 s101, 14
	s_cbranch_scc1 .Lgc_noearly
	s_mov_b32 m0, s100
	v_lshl_add_u64 v[106:107], v[72:73], 0, s[96:97]
	global_load_lds_dwordx4 v[106:107], off
	s_add_u32 m0, s100, 0x1000
	v_lshl_add_u64 v[106:107], v[72:73], 0, s[50:51]
	global_load_lds_dwordx4 v[106:107], off
	s_add_u32 m0, s100, 0x2000
	v_lshl_add_u64 v[106:107], v[72:73], 0, s[24:25]
	global_load_lds_dwordx4 v[106:107], off
	s_add_u32 m0, s100, 0x3000
	v_lshl_add_u64 v[106:107], v[72:73], 0, s[26:27]
	global_load_lds_dwordx4 v[106:107], off
	v_lshl_add_u64 v[72:73], v[72:73], 0, s[44:45]
	s_mov_b64 s[0:1], 0xb00080
	s_add_u32 m0, s100, 0x8000
	v_lshl_add_u64 v[106:107], v[74:75], 0, s[0:1]
	global_load_lds_dwordx4 v[106:107], off
	s_mov_b64 s[0:1], 0xb10080
	s_add_u32 m0, s100, 0x9000
	v_lshl_add_u64 v[106:107], v[74:75], 0, s[0:1]
	global_load_lds_dwordx4 v[106:107], off
.Lgc_noearly:
	ds_read_b128 v[240:243], v102 offset:49152
	ds_read_b128 v[244:247], v102 offset:53248
	ds_read_b128 v[224:227], v98 offset:16384
	v_mfma_f32_32x32x16_bf16 v[48:63], v[232:235], v[248:251], v[48:63]
	v_mfma_f32_32x32x16_bf16 v[32:47], v[232:235], v[252:255], v[32:47]
	ds_read_b128 v[228:231], v98 offset:20480
	v_mfma_f32_32x32x16_bf16 v[16:31], v[236:239], v[248:251], v[16:31]
	v_mfma_f32_32x32x16_bf16 v[0:15], v[236:239], v[252:255], v[0:15]
	s_cmp_eq_u32 s101, 14
	s_cbranch_scc1 .Lgc_last
	ds_read_b128 v[248:251], v103 offset:49152
	ds_read_b128 v[252:255], v103 offset:53248
	ds_read_b128 v[232:235], v99 offset:16384
	s_waitcnt lgkmcnt(4)
	v_mfma_f32_32x32x16_bf16 v[48:63], v[224:227], v[240:243], v[48:63]
	v_mfma_f32_32x32x16_bf16 v[32:47], v[224:227], v[244:247], v[32:47]
	s_mov_b64 s[0:1], 0xb20080
	s_add_u32 m0, s100, 0xa000
	v_lshl_add_u64 v[106:107], v[74:75], 0, s[0:1]
	global_load_lds_dwordx4 v[106:107], off
	s_mov_b64 s[0:1], 0xb30080
	s_add_u32 m0, s100, 0xb000
	v_lshl_add_u64 v[106:107], v[74:75], 0, s[0:1]
	global_load_lds_dwordx4 v[106:107], off
	v_lshl_add_u64 v[74:75], v[74:75], 0, s[44:45]
	ds_read_b128 v[236:239], v99 offset:20480
	s_waitcnt lgkmcnt(4)
	v_mfma_f32_32x32x16_bf16 v[16:31], v[228:231], v[240:243], v[16:31]
	v_mfma_f32_32x32x16_bf16 v[0:15], v[228:231], v[244:247], v[0:15]
	ds_read_b128 v[240:243], v104 offset:49152
	ds_read_b128 v[244:247], v104 offset:53248
	ds_read_b128 v[224:227], v100 offset:16384
	s_waitcnt lgkmcnt(4)
	v_mfma_f32_32x32x16_bf16 v[48:63], v[232:235], v[248:251], v[48:63]
	v_mfma_f32_32x32x16_bf16 v[32:47], v[232:235], v[252:255], v[32:47]
	ds_read_b128 v[228:231], v100 offset:20480
	s_waitcnt lgkmcnt(4)
	v_mfma_f32_32x32x16_bf16 v[16:31], v[236:239], v[248:251], v[16:31]
	v_mfma_f32_32x32x16_bf16 v[0:15], v[236:239], v[252:255], v[0:15]
	ds_read_b128 v[248:251], v105 offset:49152
	ds_read_b128 v[252:255], v105 offset:53248
	ds_read_b128 v[232:235], v101 offset:16384
	s_waitcnt lgkmcnt(4)
	v_mfma_f32_32x32x16_bf16 v[48:63], v[224:227], v[240:243], v[48:63]
	v_mfma_f32_32x32x16_bf16 v[32:47], v[224:227], v[244:247], v[32:47]
	ds_read_b128 v[236:239], v101 offset:20480
	s_waitcnt lgkmcnt(4)
	v_mfma_f32_32x32x16_bf16 v[16:31], v[228:231], v[240:243], v[16:31]
	v_mfma_f32_32x32x16_bf16 v[0:15], v[228:231], v[244:247], v[0:15]
	s_waitcnt lgkmcnt(0)
	s_waitcnt vmcnt(0)
	s_barrier
	s_add_u32 m0, s100, 0x4000
	v_lshl_add_u64 v[106:107], v[72:73], 0, s[96:97]
	global_load_lds_dwordx4 v[106:107], off
	s_add_u32 m0, s100, 0x5000
	v_lshl_add_u64 v[106:107], v[72:73], 0, s[50:51]
	global_load_lds_dwordx4 v[106:107], off
	s_add_u32 m0, s100, 0x6000
	v_lshl_add_u64 v[106:107], v[72:73], 0, s[24:25]
	global_load_lds_dwordx4 v[106:107], off
	s_add_u32 m0, s100, 0x7000
	v_lshl_add_u64 v[106:107], v[72:73], 0, s[26:27]
	global_load_lds_dwordx4 v[106:107], off
	v_lshl_add_u64 v[72:73], v[72:73], 0, s[44:45]
	s_mov_b64 s[0:1], 0xb00080
	s_add_u32 m0, s100, 0xc000
	v_lshl_add_u64 v[106:107], v[74:75], 0, s[0:1]
	global_load_lds_dwordx4 v[106:107], off
	s_mov_b64 s[0:1], 0xb10080
	s_add_u32 m0, s100, 0xd000
	v_lshl_add_u64 v[106:107], v[74:75], 0, s[0:1]
	global_load_lds_dwordx4 v[106:107], off
	ds_read_b128 v[240:243], v102 offset:32768
	ds_read_b128 v[244:247], v102 offset:36864
	ds_read_b128 v[224:227], v98
	v_mfma_f32_32x32x16_bf16 v[48:63], v[232:235], v[248:251], v[48:63]
	v_mfma_f32_32x32x16_bf16 v[32:47], v[232:235], v[252:255], v[32:47]
	ds_read_b128 v[228:231], v98 offset:4096
	v_mfma_f32_32x32x16_bf16 v[16:31], v[236:239], v[248:251], v[16:31]
	v_mfma_f32_32x32x16_bf16 v[0:15], v[236:239], v[252:255], v[0:15]
	s_add_u32 s101, s101, 2
	s_branch .Lgc_loop

; template <int EPI, int MI>
; DI void gemm_tile(const GemmDesc& g, int tm, int tn, char* smem) {
;     ...
;   const int tid = get_tid(), lane = tid & 63, wave = tid >> 6, r = lane & 31, hh = lane >> 5;
;   const int wm = wave >> 1, wn = wave & 1;
;   const int m0 = tm * BM, n0 = tn * 128;
;   const int nk = g.K >> 6;
;   f32x16 acc[MI][2];
; #pragma unroll
;   for (int a = 0; a < MI; ++a)
; #pragma unroll
;     for (int b = 0; b < 2; ++b)
; #pragma unroll
;       for (int i = 0; i < 16; ++i) acc[a][b][i] = 0.f;
;   const int srow = tid >> 3;
;   const int schunk = (tid & 7) ^ ((srow & 7) ^ ((srow >> 3) & 3));
; template <int EPI, int MI>
; DI void gemm_phase(const GemmDesc& g, char* smem, int vb, int nvb) {
;     ...
;   for (int q = start; q < local; q += step) {
;     const int mg = q / per;
;     const int rem = q - mg * per;
;     const int tn = rem / PM;
;     const int tm = mbase + mg * PM + (rem - tn * PM);
.LBB0_1421:
	s_abs_i32 s1, s5
	v_readlane_b32 s15, v219, 45
	s_mul_hi_u32 s15, s1, s15
	v_readlane_b32 s18, v219, 44
	s_mul_i32 s16, s15, s18
	s_sub_i32 s1, s1, s16
	s_ashr_i32 s0, s5, 31
	s_add_i32 s16, s15, 1
	s_sub_i32 s17, s1, s18
	s_cmp_ge_u32 s1, s18
	s_cselect_b32 s15, s16, s15
	s_cselect_b32 s1, s17, s1
	s_add_i32 s16, s15, 1
	s_cmp_ge_u32 s1, s18
	s_cselect_b32 s1, s16, s15
	s_xor_b32 s1, s1, s0
	s_sub_i32 s15, s1, s0
	s_mul_i32 s16, s15, s18
	s_sub_i32 s16, s5, s16
	s_abs_i32 s18, s16
	v_readlane_b32 s19, v219, 46
	s_mul_hi_u32 s19, s18, s19
	v_readlane_b32 s40, v218, 32
	s_mul_i32 s38, s19, s40
	s_sub_i32 s18, s18, s38
	s_ashr_i32 s17, s16, 31
	s_add_i32 s38, s19, 1
	s_sub_i32 s39, s18, s40
	s_cmp_ge_u32 s18, s40
	s_cselect_b32 s19, s38, s19
	s_cselect_b32 s18, s39, s18
	s_add_i32 s38, s19, 1
	s_cmp_ge_u32 s18, s40
	s_cselect_b32 s18, s38, s19
	s_xor_b32 s18, s18, s17
	s_sub_i32 s39, s18, s17
	s_sub_i32 s15, s15, s39
	v_mov_b32_e32 v6, v132
	s_mul_i32 s15, s15, s40
	s_add_i32 s16, s16, s54
	s_add_i32 s38, s16, s15
	v_ashrrev_i32_e32 v97, 3, v6
	v_ashrrev_i32_e32 v120, 7, v6
	v_bfe_u32 v0, v6, 6, 2
	v_xor_b32_e32 v1, v97, v6
	s_mulk_i32 s38, 0xc0
	v_and_b32_e32 v121, 31, v6
	v_bitop3_b32 v2, v1, v0, 7 bitop3:0x6c
	v_mul_lo_u32 v0, v120, s6
	v_and_b32_e32 v115, 7, v6
	v_or_b32_e32 v8, v0, v121
	v_lshrrev_b32_e32 v0, 3, v6
	s_waitcnt vmcnt(10)
	v_add_u32_e32 v98, s38, v97
	v_bfe_u32 v122, v6, 5, 1
	v_bitop3_b32 v0, v0, v115, 3 bitop3:0x6c
	v_ashrrev_i32_e32 v99, 31, v98
	v_readlane_b32 s40, v223, 59
	v_xor_b32_e32 v9, v0, v122
	v_lshlrev_b64 v[0:1], 11, v[98:99]
	v_readlane_b32 s41, v223, 60
	v_lshlrev_b32_e32 v100, 4, v2
	v_lshl_add_u32 v2, s39, 7, v97
	v_lshlrev_b32_e32 v99, 4, v6
	v_lshl_add_u64 v[0:1], s[40:41], 0, v[0:1]
	v_ashrrev_i32_e32 v3, 31, v2
	v_readlane_b32 s40, v220, 54
	v_add_u32_e32 v124, 0, v99
	v_mov_b32_e32 v101, v96
	v_lshlrev_b64 v[2:3], 11, v[2:3]
	v_readlane_b32 s41, v220, 55
	v_readfirstlane_b32 s15, v124
	v_add_u32_e32 v125, 0x1000, v124
	v_lshl_add_u64 v[0:1], v[0:1], 0, v[100:101]
	v_lshl_add_u64 v[4:5], s[40:41], 0, v[2:3]
	s_mov_b32 m0, s15
	s_mov_b64 s[40:41], 0x10000
	v_readfirstlane_b32 s15, v125
	v_add_u32_e32 v126, 0x2000, v124
	v_bfe_u32 v123, v6, 6, 1
	global_load_lds_dwordx4 v[0:1], off
	v_lshl_add_u64 v[6:7], v[0:1], 0, s[40:41]
	s_mov_b32 m0, s15
	s_mov_b64 s[42:43], 0x20000
	v_readfirstlane_b32 s15, v126
	v_add_u32_e32 v127, 0x3000, v124
	global_load_lds_dwordx4 v[6:7], off
	v_lshl_add_u64 v[6:7], v[0:1], 0, s[42:43]
	s_mov_b32 m0, s15
	s_mov_b64 s[44:45], 0x30000
	v_readfirstlane_b32 s15, v127
	v_add_u32_e32 v128, 0x4000, v124
	global_load_lds_dwordx4 v[6:7], off
	v_lshl_add_u64 v[6:7], v[0:1], 0, s[44:45]
	s_mov_b32 m0, s15
	s_mov_b64 s[46:47], 0x40000
	v_readfirstlane_b32 s15, v128
	v_add_u32_e32 v129, 0x5000, v124
	global_load_lds_dwordx4 v[6:7], off
	v_lshl_add_u64 v[6:7], v[0:1], 0, s[46:47]
	s_mov_b32 m0, s15
	s_mov_b64 s[46:47], 0x50000
	v_readfirstlane_b32 s15, v129
	v_add_u32_e32 v130, 0xc000, v124
	global_load_lds_dwordx4 v[6:7], off
	v_lshl_add_u64 v[0:1], v[0:1], 0, s[46:47]
	s_mov_b32 m0, s15
	v_readfirstlane_b32 s15, v130
	v_add_u32_e32 v131, 0xd000, v124
	global_load_lds_dwordx4 v[0:1], off
	v_lshl_add_u64 v[0:1], v[4:5], 0, v[100:101]
	s_mov_b32 m0, s15
	v_readfirstlane_b32 s15, v131
	v_add_u32_e32 v153, 0xe000, v124
	global_load_lds_dwordx4 v[0:1], off
	v_lshl_add_u64 v[4:5], v[0:1], 0, s[40:41]
	s_mov_b32 m0, s15
	v_readfirstlane_b32 s15, v153
	v_add_u32_e32 v154, 0xf000, v124
	global_load_lds_dwordx4 v[4:5], off
	v_lshl_add_u64 v[4:5], v[0:1], 0, s[42:43]
	s_mov_b32 m0, s15
	v_readfirstlane_b32 s15, v154
	global_load_lds_dwordx4 v[4:5], off
	v_lshl_add_u64 v[0:1], v[0:1], 0, s[44:45]
	s_mov_b32 m0, s15
	s_mul_i32 s0, s0, 43
	global_load_lds_dwordx4 v[0:1], off
	s_add_i32 s17, s17, s0
	s_sub_i32 s0, s17, s18
	s_mul_i32 s1, s1, 43
	s_sub_i32 s0, s0, s1
	v_readlane_b32 s1, v218, 33
	v_lshlrev_b32_e32 v0, 7, v121
	s_mul_i32 s0, s1, s0
	v_lshl_or_b32 v0, v123, 13, v0
	s_add_i32 s0, s0, s4
	v_add_u32_e32 v156, 0, v0
	v_add_u32_e32 v158, s10, v0
	v_add_u32_e32 v0, s0, v97
	v_ashrrev_i32_e32 v1, 31, v0
	s_waitcnt vmcnt(0)
	v_lshlrev_b64 v[0:1], 11, v[0:1]
	v_lshlrev_b32_e32 v157, 4, v9
	s_waitcnt vmcnt(0)
; template <int EPI, int MI>
; DI void gemm_tile(const GemmDesc& g, int tm, int tn, char* smem) {
;     ...
;   f32x16 acc[MI][2];
; #pragma unroll
;   for (int a = 0; a < MI; ++a)
; #pragma unroll
;     for (int b = 0; b < 2; ++b)
; #pragma unroll
;       for (int i = 0; i < 16; ++i) acc[a][b][i] = 0.f;
;   const int srow = tid >> 3;
;   const int schunk = (tid & 7) ^ ((srow & 7) ^ ((srow >> 3) & 3));
;     ...
;   const int rowA = wm * (32 * MI) + r, rowB = wn * 64 + r;
;   const int hk = hh ^ ((r & 7) ^ ((r >> 3) & 3));
;     ...
;   G_GLDS(0, 0);
;   asm volatile("s_waitcnt vmcnt(0)" ::: "memory");
;   __syncthreads();
;   for (int kt = 0; kt < nk; kt += 2) {
;     if (kt + 1 < nk) G_GLDS(kt + 1, 1);
;     G_COMPUTE(0);
;     asm volatile("s_waitcnt vmcnt(0)" ::: "memory");
;     __syncthreads();
;     if (kt + 1 < nk) {
;       if (kt + 2 < nk) G_GLDS(kt + 2, 0);
;       G_COMPUTE(1);
;       asm volatile("s_waitcnt vmcnt(0)" ::: "memory");
;       __syncthreads();
;     }
;   }
	v_lshl_add_u64 v[102:103], s[70:71], 0, v[0:1]
	v_mov_b32_e32 v0, 0
	v_lshl_add_u32 v155, v8, 7, 0
	v_xor_b32_e32 v159, 32, v157
	v_xor_b32_e32 v160, 64, v157
	v_xor_b32_e32 v161, 0x60, v157
	v_lshl_add_u64 v[104:105], s[70:71], 0, v[2:3]
	s_mov_b32 s15, 0
	v_mov_b32_e32 v1, v0
	v_mov_b32_e32 v2, v0
	v_mov_b32_e32 v3, v0
	v_mov_b32_e32 v4, v0
	v_mov_b32_e32 v5, v0
	v_mov_b32_e32 v6, v0
	v_mov_b32_e32 v7, v0
	v_mov_b32_e32 v8, v0
	v_mov_b32_e32 v9, v0
	v_mov_b32_e32 v10, v0
	v_mov_b32_e32 v11, v0
	v_mov_b32_e32 v12, v0
	v_mov_b32_e32 v13, v0
	v_mov_b32_e32 v14, v0
	v_mov_b32_e32 v15, v0
	v_mov_b32_e32 v16, v0
	v_mov_b32_e32 v17, v0
	v_mov_b32_e32 v18, v0
	v_mov_b32_e32 v19, v0
	v_mov_b32_e32 v20, v0
	v_mov_b32_e32 v21, v0
	v_mov_b32_e32 v22, v0
	v_mov_b32_e32 v23, v0
	v_mov_b32_e32 v24, v0
	v_mov_b32_e32 v25, v0
	v_mov_b32_e32 v26, v0
	v_mov_b32_e32 v27, v0
	v_mov_b32_e32 v28, v0
	v_mov_b32_e32 v29, v0
	v_mov_b32_e32 v30, v0
	v_mov_b32_e32 v31, v0
	v_mov_b32_e32 v32, v0
	v_mov_b32_e32 v33, v0
	v_mov_b32_e32 v34, v0
	v_mov_b32_e32 v35, v0
	v_mov_b32_e32 v36, v0
	v_mov_b32_e32 v37, v0
	v_mov_b32_e32 v38, v0
	v_mov_b32_e32 v39, v0
	v_mov_b32_e32 v40, v0
	v_mov_b32_e32 v41, v0
	v_mov_b32_e32 v42, v0
	v_mov_b32_e32 v43, v0
	v_mov_b32_e32 v44, v0
	v_mov_b32_e32 v45, v0
	v_mov_b32_e32 v46, v0
	v_mov_b32_e32 v47, v0
	v_mov_b32_e32 v48, v0
	v_mov_b32_e32 v49, v0
	v_mov_b32_e32 v50, v0
	v_mov_b32_e32 v51, v0
	v_mov_b32_e32 v52, v0
	v_mov_b32_e32 v53, v0
	v_mov_b32_e32 v54, v0
	v_mov_b32_e32 v55, v0
	v_mov_b32_e32 v56, v0
	v_mov_b32_e32 v57, v0
	v_mov_b32_e32 v58, v0
	v_mov_b32_e32 v59, v0
	v_mov_b32_e32 v60, v0
	v_mov_b32_e32 v61, v0
	v_mov_b32_e32 v62, v0
	v_mov_b32_e32 v63, v0
	v_mov_b32_e32 v64, v0
	v_mov_b32_e32 v65, v0
	v_mov_b32_e32 v66, v0
	v_mov_b32_e32 v67, v0
	v_mov_b32_e32 v68, v0
	v_mov_b32_e32 v69, v0
	v_mov_b32_e32 v70, v0
	v_mov_b32_e32 v71, v0
	v_mov_b32_e32 v72, v0
	v_mov_b32_e32 v73, v0
	v_mov_b32_e32 v74, v0
	v_mov_b32_e32 v75, v0
	v_mov_b32_e32 v76, v0
	v_mov_b32_e32 v77, v0
	v_mov_b32_e32 v78, v0
	v_mov_b32_e32 v79, v0
	v_mov_b32_e32 v80, v0
	v_mov_b32_e32 v81, v0
	v_mov_b32_e32 v82, v0
	v_mov_b32_e32 v83, v0
	v_mov_b32_e32 v84, v0
	v_mov_b32_e32 v85, v0
	v_mov_b32_e32 v86, v0
	v_mov_b32_e32 v87, v0
	v_mov_b32_e32 v88, v0
	v_mov_b32_e32 v89, v0
	v_mov_b32_e32 v90, v0
	v_mov_b32_e32 v91, v0
	v_mov_b32_e32 v92, v0
	v_mov_b32_e32 v93, v0
	v_mov_b32_e32 v94, v0
	v_mov_b32_e32 v95, v0
	v_add_u32_e32 v162, v155, v157
	v_add_u32_e32 v163, v155, v159
	v_add_u32_e32 v164, v155, v160
	v_add_u32_e32 v165, v155, v161
	v_add_u32_e32 v166, v156, v157
	v_add_u32_e32 v167, v156, v159
	v_add_u32_e32 v168, v156, v160
	v_add_u32_e32 v169, v156, v161
	v_add_u32_e32 v170, v158, v157
	v_add_u32_e32 v171, v158, v159
	v_add_u32_e32 v172, v158, v160
	v_add_u32_e32 v173, v158, v161
	v_lshl_add_u64 v[252:253], v[102:103], 0, v[100:101]
	v_lshl_add_u64 v[254:255], v[104:105], 0, v[100:101]
	v_readfirstlane_b32 s100, v124
	s_mov_b64 s[0:1], 0x80
	s_waitcnt vmcnt(0) lgkmcnt(0)
	s_barrier
	s_add_u32 m0, s100, 0x6000
	v_lshl_add_u64 v[106:107], v[252:253], 0, s[96:97]
	global_load_lds_dwordx4 v[106:107], off
	s_add_u32 m0, s100, 0x7000
	v_lshl_add_u64 v[106:107], v[252:253], 0, s[50:51]
	global_load_lds_dwordx4 v[106:107], off
	s_add_u32 m0, s100, 0x8000
	v_lshl_add_u64 v[106:107], v[252:253], 0, s[24:25]
	global_load_lds_dwordx4 v[106:107], off
	s_add_u32 m0, s100, 0x9000
	v_lshl_add_u64 v[106:107], v[252:253], 0, s[26:27]
	global_load_lds_dwordx4 v[106:107], off
	s_add_u32 m0, s100, 0xa000
	v_lshl_add_u64 v[106:107], v[252:253], 0, s[28:29]
	global_load_lds_dwordx4 v[106:107], off
	s_add_u32 m0, s100, 0xb000
	v_lshl_add_u64 v[106:107], v[252:253], 0, s[30:31]
	global_load_lds_dwordx4 v[106:107], off
	v_lshl_add_u64 v[252:253], v[252:253], 0, s[0:1]
	ds_read_b128 v[236:239], v166 offset:49152
	ds_read_b128 v[240:243], v166 offset:53248
	ds_read_b128 v[224:227], v162
	ds_read_b128 v[228:231], v162 offset:4096
	s_mov_b32 s101, 0
.Lgb_loop:
	ds_read_b128 v[232:235], v162 offset:8192
	s_waitcnt lgkmcnt(2)
	v_mfma_f32_32x32x16_bf16 v[80:95], v[224:227], v[236:239], v[80:95]
	v_mfma_f32_32x32x16_bf16 v[64:79], v[224:227], v[240:243], v[64:79]
	s_mov_b64 s[16:17], 0xb00080
	s_add_u32 m0, s100, 0x10000
	v_lshl_add_u64 v[106:107], v[254:255], 0, s[16:17]
	global_load_lds_dwordx4 v[106:107], off
	s_mov_b64 s[16:17], 0xb10080
	s_add_u32 m0, s100, 0x11000
	v_lshl_add_u64 v[106:107], v[254:255], 0, s[16:17]
	global_load_lds_dwordx4 v[106:107], off
	ds_read_b128 v[244:247], v167 offset:49152
	ds_read_b128 v[248:251], v167 offset:53248
	ds_read_b128 v[224:227], v163
	s_waitcnt lgkmcnt(4)
	v_mfma_f32_32x32x16_bf16 v[48:63], v[228:231], v[236:239], v[48:63]
	v_mfma_f32_32x32x16_bf16 v[32:47], v[228:231], v[240:243], v[32:47]
	s_mov_b64 s[16:17], 0xb20080
	s_add_u32 m0, s100, 0x12000
	v_lshl_add_u64 v[106:107], v[254:255], 0, s[16:17]
	global_load_lds_dwordx4 v[106:107], off
	s_mov_b64 s[16:17], 0xb30080
	s_add_u32 m0, s100, 0x13000
	v_lshl_add_u64 v[106:107], v[254:255], 0, s[16:17]
	global_load_lds_dwordx4 v[106:107], off
	v_lshl_add_u64 v[254:255], v[254:255], 0, s[0:1]
	ds_read_b128 v[228:231], v163 offset:4096
	s_waitcnt lgkmcnt(4)
	v_mfma_f32_32x32x16_bf16 v[16:31], v[232:235], v[236:239], v[16:31]
	v_mfma_f32_32x32x16_bf16 v[0:15], v[232:235], v[240:243], v[0:15]
	ds_read_b128 v[232:235], v163 offset:8192
	s_waitcnt lgkmcnt(2)
	v_mfma_f32_32x32x16_bf16 v[80:95], v[224:227], v[244:247], v[80:95]
	v_mfma_f32_32x32x16_bf16 v[64:79], v[224:227], v[248:251], v[64:79]
	ds_read_b128 v[236:239], v168 offset:49152
	ds_read_b128 v[240:243], v168 offset:53248
	ds_read_b128 v[224:227], v164
	s_waitcnt lgkmcnt(4)
	v_mfma_f32_32x32x16_bf16 v[48:63], v[228:231], v[244:247], v[48:63]
	v_mfma_f32_32x32x16_bf16 v[32:47], v[228:231], v[248:251], v[32:47]
	ds_read_b128 v[228:231], v164 offset:4096
	s_waitcnt lgkmcnt(4)
	v_mfma_f32_32x32x16_bf16 v[16:31], v[232:235], v[244:247], v[16:31]
	v_mfma_f32_32x32x16_bf16 v[0:15], v[232:235], v[248:251], v[0:15]
	ds_read_b128 v[232:235], v164 offset:8192
	s_waitcnt lgkmcnt(2)
	v_mfma_f32_32x32x16_bf16 v[80:95], v[224:227], v[236:239], v[80:95]
	v_mfma_f32_32x32x16_bf16 v[64:79], v[224:227], v[240:243], v[64:79]
	ds_read_b128 v[244:247], v169 offset:49152
	ds_read_b128 v[248:251], v169 offset:53248
	ds_read_b128 v[224:227], v165
	s_waitcnt lgkmcnt(4)
	v_mfma_f32_32x32x16_bf16 v[48:63], v[228:231], v[236:239], v[48:63]
	v_mfma_f32_32x32x16_bf16 v[32:47], v[228:231], v[240:243], v[32:47]
	ds_read_b128 v[228:231], v165 offset:4096
	s_waitcnt lgkmcnt(4)
	v_mfma_f32_32x32x16_bf16 v[16:31], v[232:235], v[236:239], v[16:31]
	v_mfma_f32_32x32x16_bf16 v[0:15], v[232:235], v[240:243], v[0:15]
	ds_read_b128 v[232:235], v165 offset:8192
	s_waitcnt lgkmcnt(2)
	v_mfma_f32_32x32x16_bf16 v[80:95], v[224:227], v[244:247], v[80:95]
	v_mfma_f32_32x32x16_bf16 v[64:79], v[224:227], v[248:251], v[64:79]
	s_waitcnt lgkmcnt(0)
	s_waitcnt vmcnt(0)
	s_barrier
; template <int EPI, int MI>
; DI void gemm_tile(const GemmDesc& g, int tm, int tn, char* smem) {
;     ...
;   const int rowA = wm * (32 * MI) + r, rowB = wn * 64 + r;
;   const int hk = hh ^ ((r & 7) ^ ((r >> 3) & 3));
;     ...
;   G_GLDS(0, 0);
;   asm volatile("s_waitcnt vmcnt(0)" ::: "memory");
;   __syncthreads();
;   for (int kt = 0; kt < nk; kt += 2) {
;     if (kt + 1 < nk) G_GLDS(kt + 1, 1);
;     G_COMPUTE(0);
;     asm volatile("s_waitcnt vmcnt(0)" ::: "memory");
;     __syncthreads();
;     if (kt + 1 < nk) {
;       if (kt + 2 < nk) G_GLDS(kt + 2, 0);
;       G_COMPUTE(1);
;       asm volatile("s_waitcnt vmcnt(0)" ::: "memory");
;       __syncthreads();
;     }
;   }
	s_cmp_eq_u32 s101, 14
	s_cbranch_scc1 .Lgb_noearly
	s_mov_b32 m0, s100
	v_lshl_add_u64 v[106:107], v[252:253], 0, s[96:97]
	global_load_lds_dwordx4 v[106:107], off
	s_add_u32 m0, s100, 0x1000
	v_lshl_add_u64 v[106:107], v[252:253], 0, s[50:51]
	global_load_lds_dwordx4 v[106:107], off
	s_add_u32 m0, s100, 0x2000
	v_lshl_add_u64 v[106:107], v[252:253], 0, s[24:25]
	global_load_lds_dwordx4 v[106:107], off
	s_add_u32 m0, s100, 0x3000
	v_lshl_add_u64 v[106:107], v[252:253], 0, s[26:27]
	global_load_lds_dwordx4 v[106:107], off
	s_add_u32 m0, s100, 0x4000
	v_lshl_add_u64 v[106:107], v[252:253], 0, s[28:29]
	global_load_lds_dwordx4 v[106:107], off
	s_add_u32 m0, s100, 0x5000
	v_lshl_add_u64 v[106:107], v[252:253], 0, s[30:31]
	global_load_lds_dwordx4 v[106:107], off
	v_lshl_add_u64 v[252:253], v[252:253], 0, s[0:1]
.Lgb_noearly:
	ds_read_b128 v[236:239], v170
	ds_read_b128 v[240:243], v170 offset:4096
	ds_read_b128 v[224:227], v162 offset:24576
	v_mfma_f32_32x32x16_bf16 v[48:63], v[228:231], v[244:247], v[48:63]
	v_mfma_f32_32x32x16_bf16 v[32:47], v[228:231], v[248:251], v[32:47]
	ds_read_b128 v[228:231], v162 offset:28672
	v_mfma_f32_32x32x16_bf16 v[16:31], v[232:235], v[244:247], v[16:31]
	v_mfma_f32_32x32x16_bf16 v[0:15], v[232:235], v[248:251], v[0:15]
	s_cmp_eq_u32 s101, 14
	s_cbranch_scc1 .Lgb_last
	ds_read_b128 v[232:235], v162 offset:32768
	s_waitcnt lgkmcnt(2)
	v_mfma_f32_32x32x16_bf16 v[80:95], v[224:227], v[236:239], v[80:95]
	v_mfma_f32_32x32x16_bf16 v[64:79], v[224:227], v[240:243], v[64:79]
	s_mov_b64 s[16:17], 0xb00080
	s_add_u32 m0, s100, 0xc000
	v_lshl_add_u64 v[106:107], v[254:255], 0, s[16:17]
	global_load_lds_dwordx4 v[106:107], off
	s_mov_b64 s[16:17], 0xb10080
	s_add_u32 m0, s100, 0xd000
	v_lshl_add_u64 v[106:107], v[254:255], 0, s[16:17]
	global_load_lds_dwordx4 v[106:107], off
	ds_read_b128 v[244:247], v171
	ds_read_b128 v[248:251], v171 offset:4096
	ds_read_b128 v[224:227], v163 offset:24576
	s_waitcnt lgkmcnt(4)
	v_mfma_f32_32x32x16_bf16 v[48:63], v[228:231], v[236:239], v[48:63]
	v_mfma_f32_32x32x16_bf16 v[32:47], v[228:231], v[240:243], v[32:47]
	s_mov_b64 s[16:17], 0xb20080
	s_add_u32 m0, s100, 0xe000
	v_lshl_add_u64 v[106:107], v[254:255], 0, s[16:17]
	global_load_lds_dwordx4 v[106:107], off
	s_mov_b64 s[16:17], 0xb30080
	s_add_u32 m0, s100, 0xf000
	v_lshl_add_u64 v[106:107], v[254:255], 0, s[16:17]
	global_load_lds_dwordx4 v[106:107], off
	v_lshl_add_u64 v[254:255], v[254:255], 0, s[0:1]
	ds_read_b128 v[228:231], v163 offset:28672
	s_waitcnt lgkmcnt(4)
	v_mfma_f32_32x32x16_bf16 v[16:31], v[232:235], v[236:239], v[16:31]
	v_mfma_f32_32x32x16_bf16 v[0:15], v[232:235], v[240:243], v[0:15]
	ds_read_b128 v[232:235], v163 offset:32768
	s_waitcnt lgkmcnt(2)
	v_mfma_f32_32x32x16_bf16 v[80:95], v[224:227], v[244:247], v[80:95]
	v_mfma_f32_32x32x16_bf16 v[64:79], v[224:227], v[248:251], v[64:79]
	ds_read_b128 v[236:239], v172
	ds_read_b128 v[240:243], v172 offset:4096
	ds_read_b128 v[224:227], v164 offset:24576
	s_waitcnt lgkmcnt(4)
	v_mfma_f32_32x32x16_bf16 v[48:63], v[228:231], v[244:247], v[48:63]
	v_mfma_f32_32x32x16_bf16 v[32:47], v[228:231], v[248:251], v[32:47]
	ds_read_b128 v[228:231], v164 offset:28672
	s_waitcnt lgkmcnt(4)
	v_mfma_f32_32x32x16_bf16 v[16:31], v[232:235], v[244:247], v[16:31]
	v_mfma_f32_32x32x16_bf16 v[0:15], v[232:235], v[248:251], v[0:15]
	ds_read_b128 v[232:235], v164 offset:32768
	s_waitcnt lgkmcnt(2)
	v_mfma_f32_32x32x16_bf16 v[80:95], v[224:227], v[236:239], v[80:95]
	v_mfma_f32_32x32x16_bf16 v[64:79], v[224:227], v[240:243], v[64:79]
	ds_read_b128 v[244:247], v173
	ds_read_b128 v[248:251], v173 offset:4096
	ds_read_b128 v[224:227], v165 offset:24576
	s_waitcnt lgkmcnt(4)
	v_mfma_f32_32x32x16_bf16 v[48:63], v[228:231], v[236:239], v[48:63]
	v_mfma_f32_32x32x16_bf16 v[32:47], v[228:231], v[240:243], v[32:47]
	ds_read_b128 v[228:231], v165 offset:28672
	s_waitcnt lgkmcnt(4)
	v_mfma_f32_32x32x16_bf16 v[16:31], v[232:235], v[236:239], v[16:31]
	v_mfma_f32_32x32x16_bf16 v[0:15], v[232:235], v[240:243], v[0:15]
	ds_read_b128 v[232:235], v165 offset:32768
	s_waitcnt lgkmcnt(2)
	v_mfma_f32_32x32x16_bf16 v[80:95], v[224:227], v[244:247], v[80:95]
	v_mfma_f32_32x32x16_bf16 v[64:79], v[224:227], v[248:251], v[64:79]
	s_waitcnt lgkmcnt(0)
	s_waitcnt vmcnt(0)
	s_barrier
	s_add_u32 m0, s100, 0x6000
	v_lshl_add_u64 v[106:107], v[252:253], 0, s[96:97]
	global_load_lds_dwordx4 v[106:107], off
	s_add_u32 m0, s100, 0x7000
	v_lshl_add_u64 v[106:107], v[252:253], 0, s[50:51]
	global_load_lds_dwordx4 v[106:107], off
	s_add_u32 m0, s100, 0x8000
	v_lshl_add_u64 v[106:107], v[252:253], 0, s[24:25]
	global_load_lds_dwordx4 v[106:107], off
	s_add_u32 m0, s100, 0x9000
	v_lshl_add_u64 v[106:107], v[252:253], 0, s[26:27]
	global_load_lds_dwordx4 v[106:107], off
	s_add_u32 m0, s100, 0xa000
	v_lshl_add_u64 v[106:107], v[252:253], 0, s[28:29]
	global_load_lds_dwordx4 v[106:107], off
	s_add_u32 m0, s100, 0xb000
	v_lshl_add_u64 v[106:107], v[252:253], 0, s[30:31]
	global_load_lds_dwordx4 v[106:107], off
	v_lshl_add_u64 v[252:253], v[252:253], 0, s[0:1]
	ds_read_b128 v[236:239], v166 offset:49152
	ds_read_b128 v[240:243], v166 offset:53248
	ds_read_b128 v[224:227], v162
	v_mfma_f32_32x32x16_bf16 v[48:63], v[228:231], v[244:247], v[48:63]
	v_mfma_f32_32x32x16_bf16 v[32:47], v[228:231], v[248:251], v[32:47]
	ds_read_b128 v[228:231], v162 offset:4096
	v_mfma_f32_32x32x16_bf16 v[16:31], v[232:235], v[244:247], v[16:31]
	v_mfma_f32_32x32x16_bf16 v[0:15], v[232:235], v[248:251], v[0:15]
	s_add_u32 s101, s101, 2
	s_branch .Lgb_loop

; template <int EPI, int MI>
; DI void gemm_tile(const GemmDesc& g, int tm, int tn, char* smem) {
;     ...
;   const int tid = get_tid(), lane = tid & 63, wave = tid >> 6, r = lane & 31, hh = lane >> 5;
;   const int wm = wave >> 1, wn = wave & 1;
;   const int m0 = tm * BM, n0 = tn * 128;
;   const int nk = g.K >> 6;
;   f32x16 acc[MI][2];
; #pragma unroll
;   for (int a = 0; a < MI; ++a)
; #pragma unroll
;     for (int b = 0; b < 2; ++b)
; #pragma unroll
;       for (int i = 0; i < 16; ++i) acc[a][b][i] = 0.f;
;   const int srow = tid >> 3;
;   const int schunk = (tid & 7) ^ ((srow & 7) ^ ((srow >> 3) & 3));
;     ...
;   const int rowA = wm * (32 * MI) + r, rowB = wn * 64 + r;
;   const int hk = hh ^ ((r & 7) ^ ((r >> 3) & 3));
;     ...
;   G_GLDS(0, 0);
;   asm volatile("s_waitcnt vmcnt(0)" ::: "memory");
;   __syncthreads();
;   for (int kt = 0; kt < nk; kt += 2) {
;     if (kt + 1 < nk) G_GLDS(kt + 1, 1);
; template <int EPI, int MI>
; DI void gemm_phase(const GemmDesc& g, char* smem, int vb, int nvb) {
;     ...
;   for (int q = start; q < local; q += step) {
;     const int mg = q / per;
;     const int rem = q - mg * per;
;     const int tn = rem / PM;
;     const int tm = mbase + mg * PM + (rem - tn * PM);
.LBB0_1478:
	s_abs_i32 s0, s44
	s_mul_hi_u32 s1, s0, s42
	s_mul_i32 s4, s1, s38
	s_sub_i32 s0, s0, s4
	s_ashr_i32 s18, s44, 31
	s_add_i32 s4, s1, 1
	s_sub_i32 s5, s0, s38
	s_cmp_ge_u32 s0, s38
	s_cselect_b32 s1, s4, s1
	s_cselect_b32 s0, s5, s0
	s_add_i32 s4, s1, 1
	s_cmp_ge_u32 s0, s38
	s_cselect_b32 s0, s4, s1
	s_xor_b32 s19, s0, s18
	s_sub_i32 s0, s19, s18
	s_mul_i32 s1, s0, s38
	s_sub_i32 s1, s44, s1
	s_abs_i32 s4, s1
	s_mul_hi_u32 s5, s4, s16
	s_mul_i32 s45, s5, s15
	s_sub_i32 s4, s4, s45
	s_ashr_i32 s46, s1, 31
	s_add_i32 s45, s5, 1
	s_sub_i32 s47, s4, s15
	s_cmp_ge_u32 s4, s15
	s_cselect_b32 s5, s45, s5
	s_cselect_b32 s4, s47, s4
	s_add_i32 s45, s5, 1
	s_cmp_ge_u32 s4, s15
	s_cselect_b32 s4, s45, s5
	s_xor_b32 s47, s4, s46
	s_sub_i32 s4, s47, s46
	v_mov_b32_e32 v75, v132
	s_mul_i32 s0, s0, s15
	s_mul_i32 s5, s4, s15
	s_add_i32 s0, s0, s39
	v_ashrrev_i32_e32 v6, 3, v75
	s_sub_i32 s1, s1, s5
	v_bfe_u32 v1, v75, 6, 2
	v_xor_b32_e32 v2, v6, v75
	s_add_i32 s1, s0, s1
	s_lshl_b32 s0, s4, 7
	v_and_b32_e32 v0, 7, v75
	v_bitop3_b32 v2, v2, v1, 7 bitop3:0x6c
	v_lshrrev_b32_e32 v1, 3, v75
	v_readlane_b32 s4, v221, 5
	s_lshl_b32 s45, s1, 7
	v_bfe_u32 v77, v75, 5, 1
	v_bitop3_b32 v0, v1, v0, 3 bitop3:0x6c
	v_readlane_b32 s5, v221, 6
	v_xor_b32_e32 v7, v0, v77
	v_add_u32_e32 v3, s45, v6
	v_mov_b64_e32 v[0:1], s[4:5]
	s_movk_i32 s52, 0x1600
	v_mad_i64_i32 v[0:1], s[4:5], v3, s52, v[0:1]
	v_readlane_b32 s4, v220, 56
	v_readlane_b32 s5, v220, 57
	v_lshlrev_b32_e32 v64, 4, v2
	v_add_u32_e32 v8, s0, v6
	v_mov_b64_e32 v[2:3], s[4:5]
	v_lshlrev_b32_e32 v4, 4, v75
	v_mad_i64_i32 v[2:3], s[4:5], v8, s52, v[2:3]
	v_add_u32_e32 v78, 0, v4
	v_mov_b32_e32 v65, v96
	v_readfirstlane_b32 s4, v78
	v_add_u32_e32 v79, 0x1000, v78
	v_lshl_add_u64 v[0:1], v[0:1], 0, v[64:65]
	s_mov_b32 m0, s4
	s_mov_b64 s[72:73], 0x2c000
	v_readfirstlane_b32 s4, v79
	v_add_u32_e32 v80, 0x2000, v78
	global_load_lds_dwordx4 v[0:1], off
	v_lshl_add_u64 v[4:5], v[0:1], 0, s[72:73]
	s_mov_b32 m0, s4
	s_mov_b64 s[74:75], 0x58000
	v_readfirstlane_b32 s4, v80
	v_add_u32_e32 v81, 0x3000, v78
	global_load_lds_dwordx4 v[4:5], off
	v_lshl_add_u64 v[4:5], v[0:1], 0, s[74:75]
	s_mov_b32 m0, s4
	s_mov_b64 s[76:77], 0x84000
	v_readfirstlane_b32 s4, v81
	v_add_u32_e32 v82, 0x8000, v78
	global_load_lds_dwordx4 v[4:5], off
	v_lshl_add_u64 v[0:1], v[0:1], 0, s[76:77]
	s_mov_b32 m0, s4
	v_readfirstlane_b32 s4, v82
	v_add_u32_e32 v83, 0x9000, v78
	global_load_lds_dwordx4 v[0:1], off
	v_lshl_add_u64 v[0:1], v[2:3], 0, v[64:65]
	s_mov_b32 m0, s4
	v_readfirstlane_b32 s4, v83
	v_add_u32_e32 v84, 0xa000, v78
	global_load_lds_dwordx4 v[0:1], off
	v_lshl_add_u64 v[2:3], v[0:1], 0, s[72:73]
	s_mov_b32 m0, s4
	v_readfirstlane_b32 s4, v84
	v_add_u32_e32 v85, 0xb000, v78
	global_load_lds_dwordx4 v[2:3], off
	v_lshl_add_u64 v[2:3], v[0:1], 0, s[74:75]
	s_mov_b32 m0, s4
	v_readfirstlane_b32 s4, v85
	global_load_lds_dwordx4 v[2:3], off
	v_lshl_add_u64 v[0:1], v[0:1], 0, s[76:77]
	s_mov_b32 m0, s4
	s_mul_i32 s18, s18, 7
	global_load_lds_dwordx4 v[0:1], off
	v_and_b32_e32 v74, 31, v75
	s_add_i32 s46, s46, s18
	v_ashrrev_i32_e32 v76, 7, v75
	v_lshlrev_b32_e32 v0, 7, v74
	s_sub_i32 s4, s46, s47
	s_mul_i32 s19, s19, 7
	v_lshl_or_b32 v0, v76, 13, v0
	s_sub_i32 s4, s4, s19
	v_add_u32_e32 v86, 0, v0
	v_lshlrev_b32_e32 v0, 7, v75
	s_mul_i32 s4, s43, s4
	v_and_b32_e32 v0, 0x2f80, v0
	s_add_i32 s4, s4, s17
	s_waitcnt vmcnt(0)
	v_add_u32_e32 v87, 0, v0
	v_add_u32_e32 v2, s4, v6
	v_mov_b64_e32 v[0:1], s[70:71]
	s_waitcnt vmcnt(0)
	v_lshlrev_b32_e32 v88, 4, v7
	v_mad_i64_i32 v[66:67], s[4:5], v2, s52, v[0:1]
	v_mad_i64_i32 v[68:69], s[4:5], v8, s52, v[0:1]
	v_mov_b32_e32 v0, 0
	v_xor_b32_e32 v89, 32, v88
	v_xor_b32_e32 v90, 64, v88
	v_xor_b32_e32 v91, 0x60, v88
	s_mov_b32 s18, 0
	v_mov_b32_e32 v1, v0
	v_mov_b32_e32 v2, v0
	v_mov_b32_e32 v3, v0
	v_mov_b32_e32 v4, v0
	v_mov_b32_e32 v5, v0
	v_mov_b32_e32 v6, v0
	v_mov_b32_e32 v7, v0
	v_mov_b32_e32 v8, v0
	v_mov_b32_e32 v9, v0
	v_mov_b32_e32 v10, v0
	v_mov_b32_e32 v11, v0
	v_mov_b32_e32 v12, v0
	v_mov_b32_e32 v13, v0
	v_mov_b32_e32 v14, v0
	v_mov_b32_e32 v15, v0
	v_mov_b32_e32 v16, v0
	v_mov_b32_e32 v17, v0
	v_mov_b32_e32 v18, v0
	v_mov_b32_e32 v19, v0
	v_mov_b32_e32 v20, v0
	v_mov_b32_e32 v21, v0
	v_mov_b32_e32 v22, v0
	v_mov_b32_e32 v23, v0
	v_mov_b32_e32 v24, v0
	v_mov_b32_e32 v25, v0
	v_mov_b32_e32 v26, v0
	v_mov_b32_e32 v27, v0
	v_mov_b32_e32 v28, v0
	v_mov_b32_e32 v29, v0
	v_mov_b32_e32 v30, v0
	v_mov_b32_e32 v31, v0
	v_mov_b32_e32 v32, v0
	v_mov_b32_e32 v33, v0
	v_mov_b32_e32 v34, v0
	v_mov_b32_e32 v35, v0
	v_mov_b32_e32 v36, v0
	v_mov_b32_e32 v37, v0
	v_mov_b32_e32 v38, v0
	v_mov_b32_e32 v39, v0
	v_mov_b32_e32 v40, v0
	v_mov_b32_e32 v41, v0
	v_mov_b32_e32 v42, v0
	v_mov_b32_e32 v43, v0
	v_mov_b32_e32 v44, v0
	v_mov_b32_e32 v45, v0
	v_mov_b32_e32 v46, v0
	v_mov_b32_e32 v47, v0
	v_mov_b32_e32 v48, v0
	v_mov_b32_e32 v49, v0
	v_mov_b32_e32 v50, v0
	v_mov_b32_e32 v51, v0
	v_mov_b32_e32 v52, v0
	v_mov_b32_e32 v53, v0
	v_mov_b32_e32 v54, v0
	v_mov_b32_e32 v55, v0
	v_mov_b32_e32 v56, v0
	v_mov_b32_e32 v57, v0
	v_mov_b32_e32 v58, v0
	v_mov_b32_e32 v59, v0
	v_mov_b32_e32 v60, v0
	v_mov_b32_e32 v61, v0
	v_mov_b32_e32 v62, v0
	v_mov_b32_e32 v63, v0
	v_add_u32_e32 v92, v86, v88
	v_add_u32_e32 v93, v86, v89
	v_add_u32_e32 v94, v86, v90
	v_add_u32_e32 v95, v86, v91
	v_add_u32_e32 v97, v87, v88
	v_add_u32_e32 v98, v87, v89
	v_add_u32_e32 v99, v87, v90
	v_add_u32_e32 v100, v87, v91
	v_lshl_add_u64 v[104:105], v[66:67], 0, v[64:65]
	v_lshl_add_u64 v[106:107], v[68:69], 0, v[64:65]
	v_readfirstlane_b32 s100, v78
	s_mov_b64 s[46:47], 0x80
	s_waitcnt vmcnt(0) lgkmcnt(0)
	s_barrier
	s_mov_b64 s[4:5], 0x5872080
	s_add_u32 m0, s100, 0x4000
	v_lshl_add_u64 v[102:103], v[104:105], 0, s[4:5]
	global_load_lds_dwordx4 v[102:103], off
	s_mov_b64 s[4:5], 0x589e080
	s_add_u32 m0, s100, 0x5000
	v_lshl_add_u64 v[102:103], v[104:105], 0, s[4:5]
	global_load_lds_dwordx4 v[102:103], off
	s_mov_b64 s[4:5], 0x58ca080
	s_add_u32 m0, s100, 0x6000
	v_lshl_add_u64 v[102:103], v[104:105], 0, s[4:5]
	global_load_lds_dwordx4 v[102:103], off
	s_mov_b64 s[4:5], 0x58f6080
	s_add_u32 m0, s100, 0x7000
	v_lshl_add_u64 v[102:103], v[104:105], 0, s[4:5]
	global_load_lds_dwordx4 v[102:103], off
	v_lshl_add_u64 v[104:105], v[104:105], 0, s[46:47]
	s_mov_b64 s[4:5], 0x1b80080
	s_add_u32 m0, s100, 0xc000
	v_lshl_add_u64 v[102:103], v[106:107], 0, s[4:5]
	global_load_lds_dwordx4 v[102:103], off
	s_mov_b64 s[4:5], 0x1bac080
	s_add_u32 m0, s100, 0xd000
	v_lshl_add_u64 v[102:103], v[106:107], 0, s[4:5]
	global_load_lds_dwordx4 v[102:103], off
	ds_read_b128 v[240:243], v97 offset:32768
	ds_read_b128 v[244:247], v97 offset:36864
	ds_read_b128 v[224:227], v92
	ds_read_b128 v[228:231], v92 offset:4096
	s_mov_b32 s101, 0
; template <int EPI, int MI>
; DI void gemm_tile(const GemmDesc& g, int tm, int tn, char* smem) {
;     ...
;   const int rowA = wm * (32 * MI) + r, rowB = wn * 64 + r;
;   const int hk = hh ^ ((r & 7) ^ ((r >> 3) & 3));
;     ...
;   G_GLDS(0, 0);
;   asm volatile("s_waitcnt vmcnt(0)" ::: "memory");
;   __syncthreads();
;   for (int kt = 0; kt < nk; kt += 2) {
;     if (kt + 1 < nk) G_GLDS(kt + 1, 1);
;     G_COMPUTE(0);
;     asm volatile("s_waitcnt vmcnt(0)" ::: "memory");
;     __syncthreads();
;     if (kt + 1 < nk) {
;       if (kt + 2 < nk) G_GLDS(kt + 2, 0);
;       G_COMPUTE(1);
;       asm volatile("s_waitcnt vmcnt(0)" ::: "memory");
;       __syncthreads();
;     }
;   }
.Lgf_loop:
	ds_read_b128 v[248:251], v98 offset:32768
	ds_read_b128 v[252:255], v98 offset:36864
	ds_read_b128 v[232:235], v93
	s_waitcnt lgkmcnt(4)
	v_mfma_f32_32x32x16_bf16 v[48:63], v[224:227], v[240:243], v[48:63]
	v_mfma_f32_32x32x16_bf16 v[32:47], v[224:227], v[244:247], v[32:47]
	s_mov_b64 s[4:5], 0x1bd8080
	s_add_u32 m0, s100, 0xe000
	v_lshl_add_u64 v[102:103], v[106:107], 0, s[4:5]
	global_load_lds_dwordx4 v[102:103], off
	s_mov_b64 s[4:5], 0x1c04080
	s_add_u32 m0, s100, 0xf000
	v_lshl_add_u64 v[102:103], v[106:107], 0, s[4:5]
	global_load_lds_dwordx4 v[102:103], off
	v_lshl_add_u64 v[106:107], v[106:107], 0, s[46:47]
	ds_read_b128 v[236:239], v93 offset:4096
	s_waitcnt lgkmcnt(4)
	v_mfma_f32_32x32x16_bf16 v[16:31], v[228:231], v[240:243], v[16:31]
	v_mfma_f32_32x32x16_bf16 v[0:15], v[228:231], v[244:247], v[0:15]
	ds_read_b128 v[240:243], v99 offset:32768
	ds_read_b128 v[244:247], v99 offset:36864
	ds_read_b128 v[224:227], v94
	s_waitcnt lgkmcnt(4)
	v_mfma_f32_32x32x16_bf16 v[48:63], v[232:235], v[248:251], v[48:63]
	v_mfma_f32_32x32x16_bf16 v[32:47], v[232:235], v[252:255], v[32:47]
	ds_read_b128 v[228:231], v94 offset:4096
	s_waitcnt lgkmcnt(4)
	v_mfma_f32_32x32x16_bf16 v[16:31], v[236:239], v[248:251], v[16:31]
	v_mfma_f32_32x32x16_bf16 v[0:15], v[236:239], v[252:255], v[0:15]
	ds_read_b128 v[248:251], v100 offset:32768
	ds_read_b128 v[252:255], v100 offset:36864
	ds_read_b128 v[232:235], v95
	s_waitcnt lgkmcnt(4)
	v_mfma_f32_32x32x16_bf16 v[48:63], v[224:227], v[240:243], v[48:63]
	v_mfma_f32_32x32x16_bf16 v[32:47], v[224:227], v[244:247], v[32:47]
	ds_read_b128 v[236:239], v95 offset:4096
	s_waitcnt lgkmcnt(4)
	v_mfma_f32_32x32x16_bf16 v[16:31], v[228:231], v[240:243], v[16:31]
	v_mfma_f32_32x32x16_bf16 v[0:15], v[228:231], v[244:247], v[0:15]
	s_waitcnt lgkmcnt(0)
	s_waitcnt vmcnt(0)
	s_barrier
	s_cmp_eq_u32 s101, 42
	s_cbranch_scc1 .Lgf_noearly
	s_mov_b64 s[4:5], 0x5872080
	s_mov_b32 m0, s100
	v_lshl_add_u64 v[102:103], v[104:105], 0, s[4:5]
	global_load_lds_dwordx4 v[102:103], off
	s_mov_b64 s[4:5], 0x589e080
	s_add_u32 m0, s100, 0x1000
	v_lshl_add_u64 v[102:103], v[104:105], 0, s[4:5]
	global_load_lds_dwordx4 v[102:103], off
	s_mov_b64 s[4:5], 0x58ca080
	s_add_u32 m0, s100, 0x2000
	v_lshl_add_u64 v[102:103], v[104:105], 0, s[4:5]
	global_load_lds_dwordx4 v[102:103], off
	s_mov_b64 s[4:5], 0x58f6080
	s_add_u32 m0, s100, 0x3000
	v_lshl_add_u64 v[102:103], v[104:105], 0, s[4:5]
	global_load_lds_dwordx4 v[102:103], off
	v_lshl_add_u64 v[104:105], v[104:105], 0, s[46:47]
	s_mov_b64 s[4:5], 0x1b80080
	s_add_u32 m0, s100, 0x8000
	v_lshl_add_u64 v[102:103], v[106:107], 0, s[4:5]
	global_load_lds_dwordx4 v[102:103], off
	s_mov_b64 s[4:5], 0x1bac080
	s_add_u32 m0, s100, 0x9000
	v_lshl_add_u64 v[102:103], v[106:107], 0, s[4:5]
	global_load_lds_dwordx4 v[102:103], off
.Lgf_noearly:
	ds_read_b128 v[240:243], v97 offset:49152
	ds_read_b128 v[244:247], v97 offset:53248
	ds_read_b128 v[224:227], v92 offset:16384
	v_mfma_f32_32x32x16_bf16 v[48:63], v[232:235], v[248:251], v[48:63]
	v_mfma_f32_32x32x16_bf16 v[32:47], v[232:235], v[252:255], v[32:47]
	ds_read_b128 v[228:231], v92 offset:20480
	v_mfma_f32_32x32x16_bf16 v[16:31], v[236:239], v[248:251], v[16:31]
	v_mfma_f32_32x32x16_bf16 v[0:15], v[236:239], v[252:255], v[0:15]
	s_cmp_eq_u32 s101, 42
	s_cbranch_scc1 .Lgf_last
	ds_read_b128 v[248:251], v98 offset:49152
	ds_read_b128 v[252:255], v98 offset:53248
	ds_read_b128 v[232:235], v93 offset:16384
	s_waitcnt lgkmcnt(4)
	v_mfma_f32_32x32x16_bf16 v[48:63], v[224:227], v[240:243], v[48:63]
	v_mfma_f32_32x32x16_bf16 v[32:47], v[224:227], v[244:247], v[32:47]
	s_mov_b64 s[4:5], 0x1bd8080
	s_add_u32 m0, s100, 0xa000
	v_lshl_add_u64 v[102:103], v[106:107], 0, s[4:5]
	global_load_lds_dwordx4 v[102:103], off
	s_mov_b64 s[4:5], 0x1c04080
	s_add_u32 m0, s100, 0xb000
	v_lshl_add_u64 v[102:103], v[106:107], 0, s[4:5]
	global_load_lds_dwordx4 v[102:103], off
	v_lshl_add_u64 v[106:107], v[106:107], 0, s[46:47]
	ds_read_b128 v[236:239], v93 offset:20480
	s_waitcnt lgkmcnt(4)
	v_mfma_f32_32x32x16_bf16 v[16:31], v[228:231], v[240:243], v[16:31]
	v_mfma_f32_32x32x16_bf16 v[0:15], v[228:231], v[244:247], v[0:15]
	ds_read_b128 v[240:243], v99 offset:49152
	ds_read_b128 v[244:247], v99 offset:53248
	ds_read_b128 v[224:227], v94 offset:16384
	s_waitcnt lgkmcnt(4)
	v_mfma_f32_32x32x16_bf16 v[48:63], v[232:235], v[248:251], v[48:63]
	v_mfma_f32_32x32x16_bf16 v[32:47], v[232:235], v[252:255], v[32:47]
	ds_read_b128 v[228:231], v94 offset:20480
	s_waitcnt lgkmcnt(4)
	v_mfma_f32_32x32x16_bf16 v[16:31], v[236:239], v[248:251], v[16:31]
	v_mfma_f32_32x32x16_bf16 v[0:15], v[236:239], v[252:255], v[0:15]
	ds_read_b128 v[248:251], v100 offset:49152
	ds_read_b128 v[252:255], v100 offset:53248
	ds_read_b128 v[232:235], v95 offset:16384
	s_waitcnt lgkmcnt(4)
	v_mfma_f32_32x32x16_bf16 v[48:63], v[224:227], v[240:243], v[48:63]
	v_mfma_f32_32x32x16_bf16 v[32:47], v[224:227], v[244:247], v[32:47]
	ds_read_b128 v[236:239], v95 offset:20480
	s_waitcnt lgkmcnt(4)
	v_mfma_f32_32x32x16_bf16 v[16:31], v[228:231], v[240:243], v[16:31]
	v_mfma_f32_32x32x16_bf16 v[0:15], v[228:231], v[244:247], v[0:15]
	s_waitcnt lgkmcnt(0)
	s_waitcnt vmcnt(0)
	s_barrier
	s_mov_b64 s[4:5], 0x5872080
	s_add_u32 m0, s100, 0x4000
	v_lshl_add_u64 v[102:103], v[104:105], 0, s[4:5]
	global_load_lds_dwordx4 v[102:103], off
	s_mov_b64 s[4:5], 0x589e080
	s_add_u32 m0, s100, 0x5000
	v_lshl_add_u64 v[102:103], v[104:105], 0, s[4:5]
	global_load_lds_dwordx4 v[102:103], off
	s_mov_b64 s[4:5], 0x58ca080
	s_add_u32 m0, s100, 0x6000
	v_lshl_add_u64 v[102:103], v[104:105], 0, s[4:5]
	global_load_lds_dwordx4 v[102:103], off
	s_mov_b64 s[4:5], 0x58f6080
	s_add_u32 m0, s100, 0x7000
	v_lshl_add_u64 v[102:103], v[104:105], 0, s[4:5]
	global_load_lds_dwordx4 v[102:103], off
	v_lshl_add_u64 v[104:105], v[104:105], 0, s[46:47]
	s_mov_b64 s[4:5], 0x1b80080
	s_add_u32 m0, s100, 0xc000
	v_lshl_add_u64 v[102:103], v[106:107], 0, s[4:5]
	global_load_lds_dwordx4 v[102:103], off
	s_mov_b64 s[4:5], 0x1bac080
	s_add_u32 m0, s100, 0xd000
	v_lshl_add_u64 v[102:103], v[106:107], 0, s[4:5]
	global_load_lds_dwordx4 v[102:103], off
	ds_read_b128 v[240:243], v97 offset:32768
	ds_read_b128 v[244:247], v97 offset:36864
	ds_read_b128 v[224:227], v92
	v_mfma_f32_32x32x16_bf16 v[48:63], v[232:235], v[248:251], v[48:63]
	v_mfma_f32_32x32x16_bf16 v[32:47], v[232:235], v[252:255], v[32:47]
	ds_read_b128 v[228:231], v92 offset:4096
	v_mfma_f32_32x32x16_bf16 v[16:31], v[236:239], v[248:251], v[16:31]
	v_mfma_f32_32x32x16_bf16 v[0:15], v[236:239], v[252:255], v[0:15]
	s_add_u32 s101, s101, 2
	s_branch .Lgf_loop

; template <int EPI, int MI>
; DI void gemm_tile(const GemmDesc& g, int tm, int tn, char* smem) {
;     ...
;   const int tid = get_tid(), lane = tid & 63, wave = tid >> 6, r = lane & 31, hh = lane >> 5;
;   const int wm = wave >> 1, wn = wave & 1;
;   const int m0 = tm * BM, n0 = tn * 128;
;   const int nk = g.K >> 6;
;   f32x16 acc[MI][2];
; #pragma unroll
;   for (int a = 0; a < MI; ++a)
; #pragma unroll
;     for (int b = 0; b < 2; ++b)
; #pragma unroll
;       for (int i = 0; i < 16; ++i) acc[a][b][i] = 0.f;
;   const int srow = tid >> 3;
;   const int schunk = (tid & 7) ^ ((srow & 7) ^ ((srow >> 3) & 3));
;     ...
;   const int rowA = wm * (32 * MI) + r, rowB = wn * 64 + r;
;   const int hk = hh ^ ((r & 7) ^ ((r >> 3) & 3));
;     ...
;   G_GLDS(0, 0);
;   asm volatile("s_waitcnt vmcnt(0)" ::: "memory");
;   __syncthreads();
; template <int EPI, int MI>
; DI void gemm_phase(const GemmDesc& g, char* smem, int vb, int nvb) {
;     ...
;   for (int q = start; q < local; q += step) {
;     const int mg = q / per;
;     const int rem = q - mg * per;
;     const int tn = rem / PM;
;     const int tm = mbase + mg * PM + (rem - tn * PM);
.LBB0_1491:
	s_abs_i32 s0, s40
	v_readlane_b32 s1, v219, 48
	s_mul_hi_u32 s1, s0, s1
	v_readlane_b32 s17, v219, 47
	s_mul_i32 s4, s1, s17
	s_sub_i32 s0, s0, s4
	s_ashr_i32 s15, s40, 31
	s_add_i32 s4, s1, 1
	s_sub_i32 s5, s0, s17
	s_cmp_ge_u32 s0, s17
	s_cselect_b32 s1, s4, s1
	s_cselect_b32 s0, s5, s0
	s_add_i32 s4, s1, 1
	s_cmp_ge_u32 s0, s17
	s_cselect_b32 s0, s4, s1
	s_xor_b32 s16, s0, s15
	s_sub_i32 s0, s16, s15
	s_mul_i32 s1, s0, s17
	s_sub_i32 s1, s40, s1
	s_abs_i32 s4, s1
	v_readlane_b32 s5, v219, 46
	s_mul_hi_u32 s5, s4, s5
	v_readlane_b32 s41, v218, 32
	s_mul_i32 s18, s5, s41
	s_sub_i32 s4, s4, s18
	s_ashr_i32 s17, s1, 31
	s_add_i32 s18, s5, 1
	s_sub_i32 s19, s4, s41
	s_cmp_ge_u32 s4, s41
	s_cselect_b32 s5, s18, s5
	s_cselect_b32 s4, s19, s4
	s_add_i32 s18, s5, 1
	s_cmp_ge_u32 s4, s41
	s_cselect_b32 s4, s18, s5
	s_xor_b32 s18, s4, s17
	v_mov_b32_e32 v97, v132
	s_sub_i32 s4, s18, s17
	s_mul_i32 s0, s0, s41
	v_ashrrev_i32_e32 v6, 3, v97
	s_mul_i32 s5, s4, s41
	s_waitcnt vmcnt(8)
	v_ashrrev_i32_e32 v109, 7, v97
	v_bfe_u32 v1, v97, 6, 2
	v_xor_b32_e32 v2, v6, v97
	s_add_i32 s0, s0, s54
	s_sub_i32 s1, s1, s5
	v_and_b32_e32 v108, 31, v97
	v_bitop3_b32 v2, v2, v1, 7 bitop3:0x6c
	v_mul_lo_u32 v1, v109, s6
	s_add_i32 s1, s0, s1
	s_lshl_b32 s0, s4, 7
	v_and_b32_e32 v0, 7, v97
	v_or_b32_e32 v7, v1, v108
	v_lshrrev_b32_e32 v1, 3, v97
	v_readlane_b32 s4, v221, 5
	s_mul_i32 s41, s1, 0xc0
	v_bfe_u32 v115, v97, 5, 1
	v_bitop3_b32 v0, v1, v0, 3 bitop3:0x6c
	v_readlane_b32 s5, v221, 6
	v_xor_b32_e32 v8, v0, v115
	v_add_u32_e32 v3, s41, v6
	v_mov_b64_e32 v[0:1], s[4:5]
	s_movk_i32 s19, 0x1600
	v_mad_i64_i32 v[0:1], s[4:5], v3, s19, v[0:1]
	v_readlane_b32 s4, v220, 56
	v_readlane_b32 s5, v220, 57
	v_lshlrev_b32_e32 v98, 4, v2
	v_add_u32_e32 v9, s0, v6
	v_mov_b64_e32 v[2:3], s[4:5]
	v_lshlrev_b32_e32 v120, 4, v97
	v_mad_i64_i32 v[2:3], s[4:5], v9, s19, v[2:3]
	v_add_u32_e32 v121, 0, v120
	v_mov_b32_e32 v99, v96
	v_readfirstlane_b32 s4, v121
	v_add_u32_e32 v122, 0x1000, v121
	v_lshl_add_u64 v[0:1], v[0:1], 0, v[98:99]
	s_mov_b32 m0, s4
	s_mov_b64 s[42:43], 0x2c000
	v_readfirstlane_b32 s4, v122
	v_add_u32_e32 v123, 0x2000, v121
	global_load_lds_dwordx4 v[0:1], off
	v_lshl_add_u64 v[4:5], v[0:1], 0, s[42:43]
	s_mov_b32 m0, s4
	s_mov_b64 s[44:45], 0x58000
	v_readfirstlane_b32 s4, v123
	v_add_u32_e32 v124, 0x3000, v121
	global_load_lds_dwordx4 v[4:5], off
	v_lshl_add_u64 v[4:5], v[0:1], 0, s[44:45]
	s_mov_b32 m0, s4
	s_mov_b64 s[46:47], 0x84000
	v_readfirstlane_b32 s4, v124
	global_load_lds_dwordx4 v[4:5], off
	v_lshl_add_u64 v[4:5], v[0:1], 0, s[46:47]
	s_mov_b32 m0, s4
	s_mov_b64 s[4:5], 0xb0000
	v_add_u32_e32 v125, 0x4000, v121
	global_load_lds_dwordx4 v[4:5], off
	v_lshl_add_u64 v[4:5], v[0:1], 0, s[4:5]
	v_readfirstlane_b32 s4, v125
	s_mov_b32 m0, s4
	s_mov_b64 s[4:5], 0xdc000
	v_add_u32_e32 v126, 0x5000, v121
	v_lshl_add_u64 v[0:1], v[0:1], 0, s[4:5]
	v_readfirstlane_b32 s4, v126
	v_add_u32_e32 v127, 0xc000, v121
	global_load_lds_dwordx4 v[4:5], off
	s_mov_b32 m0, s4
	v_readfirstlane_b32 s4, v127
	v_add_u32_e32 v128, 0xd000, v121
	global_load_lds_dwordx4 v[0:1], off
	v_lshl_add_u64 v[0:1], v[2:3], 0, v[98:99]
	s_mov_b32 m0, s4
	v_readfirstlane_b32 s4, v128
	v_add_u32_e32 v129, 0xe000, v121
	global_load_lds_dwordx4 v[0:1], off
	v_lshl_add_u64 v[2:3], v[0:1], 0, s[42:43]
	s_mov_b32 m0, s4
	v_readfirstlane_b32 s4, v129
	v_add_u32_e32 v130, 0xf000, v121
	global_load_lds_dwordx4 v[2:3], off
	v_lshl_add_u64 v[2:3], v[0:1], 0, s[44:45]
	s_mov_b32 m0, s4
	v_readfirstlane_b32 s4, v130
	global_load_lds_dwordx4 v[2:3], off
	v_lshl_add_u64 v[0:1], v[0:1], 0, s[46:47]
	s_mov_b32 m0, s4
	s_mul_i32 s15, s15, 7
	global_load_lds_dwordx4 v[0:1], off
	s_add_i32 s17, s17, s15
	s_sub_i32 s4, s17, s18
	s_mul_i32 s16, s16, 7
	s_sub_i32 s4, s4, s16
	v_readlane_b32 s5, v218, 33
	v_lshlrev_b32_e32 v0, 7, v97
	s_mul_i32 s4, s5, s4
	v_and_b32_e32 v0, 0x2f80, v0
	s_add_i32 s4, s4, s39
	s_waitcnt vmcnt(0)
	v_add_u32_e32 v153, 0, v0
	v_add_u32_e32 v155, s10, v0
	v_add_u32_e32 v2, s4, v6
	v_mov_b64_e32 v[0:1], s[70:71]
	v_lshlrev_b32_e32 v154, 4, v8
	v_mad_i64_i32 v[100:101], s[4:5], v2, s19, v[0:1]
	v_mad_i64_i32 v[102:103], s[4:5], v9, s19, v[0:1]
	v_mov_b32_e32 v0, 0
	v_lshl_add_u32 v131, v7, 7, 0
	v_xor_b32_e32 v156, 32, v154
	v_xor_b32_e32 v157, 64, v154
	v_xor_b32_e32 v158, 0x60, v154
	s_mov_b32 s15, 0
	v_mov_b32_e32 v1, v0
	v_mov_b32_e32 v2, v0
	v_mov_b32_e32 v3, v0
	v_mov_b32_e32 v4, v0
	v_mov_b32_e32 v5, v0
	v_mov_b32_e32 v6, v0
	v_mov_b32_e32 v7, v0
	v_mov_b32_e32 v8, v0
	v_mov_b32_e32 v9, v0
	v_mov_b32_e32 v10, v0
	v_mov_b32_e32 v11, v0
	v_mov_b32_e32 v12, v0
	v_mov_b32_e32 v13, v0
	v_mov_b32_e32 v14, v0
	v_mov_b32_e32 v15, v0
	v_mov_b32_e32 v16, v0
	v_mov_b32_e32 v17, v0
	v_mov_b32_e32 v18, v0
	v_mov_b32_e32 v19, v0
	v_mov_b32_e32 v20, v0
	v_mov_b32_e32 v21, v0
	v_mov_b32_e32 v22, v0
	v_mov_b32_e32 v23, v0
	v_mov_b32_e32 v24, v0
	v_mov_b32_e32 v25, v0
	v_mov_b32_e32 v26, v0
	v_mov_b32_e32 v27, v0
	v_mov_b32_e32 v28, v0
	v_mov_b32_e32 v29, v0
	v_mov_b32_e32 v30, v0
	v_mov_b32_e32 v31, v0
	v_mov_b32_e32 v32, v0
	v_mov_b32_e32 v33, v0
	v_mov_b32_e32 v34, v0
	v_mov_b32_e32 v35, v0
	v_mov_b32_e32 v36, v0
	v_mov_b32_e32 v37, v0
	v_mov_b32_e32 v38, v0
	v_mov_b32_e32 v39, v0
	v_mov_b32_e32 v40, v0
	v_mov_b32_e32 v41, v0
	v_mov_b32_e32 v42, v0
	v_mov_b32_e32 v43, v0
	v_mov_b32_e32 v44, v0
	v_mov_b32_e32 v45, v0
	v_mov_b32_e32 v46, v0
	v_mov_b32_e32 v47, v0
	v_mov_b32_e32 v48, v0
	s_waitcnt vmcnt(0)
; template <int EPI, int MI>
; DI void gemm_tile(const GemmDesc& g, int tm, int tn, char* smem) {
;     ...
;   f32x16 acc[MI][2];
; #pragma unroll
;   for (int a = 0; a < MI; ++a)
; #pragma unroll
;     for (int b = 0; b < 2; ++b)
; #pragma unroll
;       for (int i = 0; i < 16; ++i) acc[a][b][i] = 0.f;
;   const int srow = tid >> 3;
;   const int schunk = (tid & 7) ^ ((srow & 7) ^ ((srow >> 3) & 3));
;     ...
;   const int rowA = wm * (32 * MI) + r, rowB = wn * 64 + r;
;   const int hk = hh ^ ((r & 7) ^ ((r >> 3) & 3));
;     ...
;   G_GLDS(0, 0);
;   asm volatile("s_waitcnt vmcnt(0)" ::: "memory");
;   __syncthreads();
;   for (int kt = 0; kt < nk; kt += 2) {
;     if (kt + 1 < nk) G_GLDS(kt + 1, 1);
;     G_COMPUTE(0);
;     asm volatile("s_waitcnt vmcnt(0)" ::: "memory");
;     __syncthreads();
;     if (kt + 1 < nk) {
;       if (kt + 2 < nk) G_GLDS(kt + 2, 0);
;       G_COMPUTE(1);
;       asm volatile("s_waitcnt vmcnt(0)" ::: "memory");
;       __syncthreads();
;     }
;   }
	v_mov_b32_e32 v49, v0
	v_mov_b32_e32 v50, v0
	v_mov_b32_e32 v51, v0
	v_mov_b32_e32 v52, v0
	v_mov_b32_e32 v53, v0
	v_mov_b32_e32 v54, v0
	v_mov_b32_e32 v55, v0
	v_mov_b32_e32 v56, v0
	v_mov_b32_e32 v57, v0
	v_mov_b32_e32 v58, v0
	v_mov_b32_e32 v59, v0
	v_mov_b32_e32 v60, v0
	v_mov_b32_e32 v61, v0
	v_mov_b32_e32 v62, v0
	v_mov_b32_e32 v63, v0
	v_mov_b32_e32 v64, v0
	v_mov_b32_e32 v65, v0
	v_mov_b32_e32 v66, v0
	v_mov_b32_e32 v67, v0
	v_mov_b32_e32 v68, v0
	v_mov_b32_e32 v69, v0
	v_mov_b32_e32 v70, v0
	v_mov_b32_e32 v71, v0
	v_mov_b32_e32 v72, v0
	v_mov_b32_e32 v73, v0
	v_mov_b32_e32 v74, v0
	v_mov_b32_e32 v75, v0
	v_mov_b32_e32 v76, v0
	v_mov_b32_e32 v77, v0
	v_mov_b32_e32 v78, v0
	v_mov_b32_e32 v79, v0
	v_mov_b32_e32 v80, v0
	v_mov_b32_e32 v81, v0
	v_mov_b32_e32 v82, v0
	v_mov_b32_e32 v83, v0
	v_mov_b32_e32 v84, v0
	v_mov_b32_e32 v85, v0
	v_mov_b32_e32 v86, v0
	v_mov_b32_e32 v87, v0
	v_mov_b32_e32 v88, v0
	v_mov_b32_e32 v89, v0
	v_mov_b32_e32 v90, v0
	v_mov_b32_e32 v91, v0
	v_mov_b32_e32 v92, v0
	v_mov_b32_e32 v93, v0
	v_mov_b32_e32 v94, v0
	v_mov_b32_e32 v95, v0
	v_add_u32_e32 v162, v131, v154
	v_add_u32_e32 v163, v131, v156
	v_add_u32_e32 v164, v131, v157
	v_add_u32_e32 v165, v131, v158
	v_add_u32_e32 v166, v153, v154
	v_add_u32_e32 v167, v153, v156
	v_add_u32_e32 v168, v153, v157
	v_add_u32_e32 v169, v153, v158
	v_add_u32_e32 v170, v155, v154
	v_add_u32_e32 v171, v155, v156
	v_add_u32_e32 v172, v155, v157
	v_add_u32_e32 v173, v155, v158
	v_lshl_add_u64 v[252:253], v[100:101], 0, v[98:99]
	v_lshl_add_u64 v[254:255], v[102:103], 0, v[98:99]
	v_readfirstlane_b32 s100, v121
	s_mov_b64 s[4:5], 0x80
	s_waitcnt vmcnt(0) lgkmcnt(0)
	s_barrier
	s_mov_b64 s[16:17], 0x5872080
	s_add_u32 m0, s100, 0x6000
	v_lshl_add_u64 v[106:107], v[252:253], 0, s[16:17]
	global_load_lds_dwordx4 v[106:107], off
	s_mov_b64 s[16:17], 0x589e080
	s_add_u32 m0, s100, 0x7000
	v_lshl_add_u64 v[106:107], v[252:253], 0, s[16:17]
	global_load_lds_dwordx4 v[106:107], off
	s_mov_b64 s[16:17], 0x58ca080
	s_add_u32 m0, s100, 0x8000
	v_lshl_add_u64 v[106:107], v[252:253], 0, s[16:17]
	global_load_lds_dwordx4 v[106:107], off
	s_mov_b64 s[16:17], 0x58f6080
	s_add_u32 m0, s100, 0x9000
	v_lshl_add_u64 v[106:107], v[252:253], 0, s[16:17]
	global_load_lds_dwordx4 v[106:107], off
	s_mov_b64 s[16:17], 0x5922080
	s_add_u32 m0, s100, 0xa000
	v_lshl_add_u64 v[106:107], v[252:253], 0, s[16:17]
	global_load_lds_dwordx4 v[106:107], off
	s_mov_b64 s[16:17], 0x594e080
	s_add_u32 m0, s100, 0xb000
	v_lshl_add_u64 v[106:107], v[252:253], 0, s[16:17]
	global_load_lds_dwordx4 v[106:107], off
	v_lshl_add_u64 v[252:253], v[252:253], 0, s[4:5]
	ds_read_b128 v[236:239], v166 offset:49152
	ds_read_b128 v[240:243], v166 offset:53248
	ds_read_b128 v[224:227], v162
	ds_read_b128 v[228:231], v162 offset:4096
	s_mov_b32 s15, 0
.Lge_loop:
	ds_read_b128 v[232:235], v162 offset:8192
	s_waitcnt lgkmcnt(2)
	v_mfma_f32_32x32x16_bf16 v[80:95], v[224:227], v[236:239], v[80:95]
	v_mfma_f32_32x32x16_bf16 v[64:79], v[224:227], v[240:243], v[64:79]
	s_mov_b64 s[16:17], 0x1b80080
	s_add_u32 m0, s100, 0x10000
	v_lshl_add_u64 v[106:107], v[254:255], 0, s[16:17]
	global_load_lds_dwordx4 v[106:107], off
	s_mov_b64 s[16:17], 0x1bac080
	s_add_u32 m0, s100, 0x11000
	v_lshl_add_u64 v[106:107], v[254:255], 0, s[16:17]
	global_load_lds_dwordx4 v[106:107], off
	ds_read_b128 v[244:247], v167 offset:49152
	ds_read_b128 v[248:251], v167 offset:53248
	ds_read_b128 v[224:227], v163
	s_waitcnt lgkmcnt(4)
	v_mfma_f32_32x32x16_bf16 v[48:63], v[228:231], v[236:239], v[48:63]
	v_mfma_f32_32x32x16_bf16 v[32:47], v[228:231], v[240:243], v[32:47]
	s_mov_b64 s[16:17], 0x1bd8080
	s_add_u32 m0, s100, 0x12000
	v_lshl_add_u64 v[106:107], v[254:255], 0, s[16:17]
	global_load_lds_dwordx4 v[106:107], off
	s_mov_b64 s[16:17], 0x1c04080
	s_add_u32 m0, s100, 0x13000
	v_lshl_add_u64 v[106:107], v[254:255], 0, s[16:17]
	global_load_lds_dwordx4 v[106:107], off
	v_lshl_add_u64 v[254:255], v[254:255], 0, s[4:5]
	ds_read_b128 v[228:231], v163 offset:4096
	s_waitcnt lgkmcnt(4)
	v_mfma_f32_32x32x16_bf16 v[16:31], v[232:235], v[236:239], v[16:31]
	v_mfma_f32_32x32x16_bf16 v[0:15], v[232:235], v[240:243], v[0:15]
	ds_read_b128 v[232:235], v163 offset:8192
	s_waitcnt lgkmcnt(2)
	v_mfma_f32_32x32x16_bf16 v[80:95], v[224:227], v[244:247], v[80:95]
	v_mfma_f32_32x32x16_bf16 v[64:79], v[224:227], v[248:251], v[64:79]
	ds_read_b128 v[236:239], v168 offset:49152
	ds_read_b128 v[240:243], v168 offset:53248
	ds_read_b128 v[224:227], v164
	s_waitcnt lgkmcnt(4)
	v_mfma_f32_32x32x16_bf16 v[48:63], v[228:231], v[244:247], v[48:63]
	v_mfma_f32_32x32x16_bf16 v[32:47], v[228:231], v[248:251], v[32:47]
	ds_read_b128 v[228:231], v164 offset:4096
	s_waitcnt lgkmcnt(4)
	v_mfma_f32_32x32x16_bf16 v[16:31], v[232:235], v[244:247], v[16:31]
	v_mfma_f32_32x32x16_bf16 v[0:15], v[232:235], v[248:251], v[0:15]
	ds_read_b128 v[232:235], v164 offset:8192
	s_waitcnt lgkmcnt(2)
	v_mfma_f32_32x32x16_bf16 v[80:95], v[224:227], v[236:239], v[80:95]
	v_mfma_f32_32x32x16_bf16 v[64:79], v[224:227], v[240:243], v[64:79]
	ds_read_b128 v[244:247], v169 offset:49152
	ds_read_b128 v[248:251], v169 offset:53248
	ds_read_b128 v[224:227], v165
	s_waitcnt lgkmcnt(4)
	v_mfma_f32_32x32x16_bf16 v[48:63], v[228:231], v[236:239], v[48:63]
	v_mfma_f32_32x32x16_bf16 v[32:47], v[228:231], v[240:243], v[32:47]
	ds_read_b128 v[228:231], v165 offset:4096
	s_waitcnt lgkmcnt(4)
	v_mfma_f32_32x32x16_bf16 v[16:31], v[232:235], v[236:239], v[16:31]
	v_mfma_f32_32x32x16_bf16 v[0:15], v[232:235], v[240:243], v[0:15]
	ds_read_b128 v[232:235], v165 offset:8192
	s_waitcnt lgkmcnt(2)
	v_mfma_f32_32x32x16_bf16 v[80:95], v[224:227], v[244:247], v[80:95]
	v_mfma_f32_32x32x16_bf16 v[64:79], v[224:227], v[248:251], v[64:79]
	s_waitcnt lgkmcnt(0)
	s_waitcnt vmcnt(0)
	s_barrier
	s_cmp_eq_u32 s15, 42
	s_cbranch_scc1 .Lge_noearly
	s_mov_b64 s[16:17], 0x5872080
	s_mov_b32 m0, s100
	v_lshl_add_u64 v[106:107], v[252:253], 0, s[16:17]
	global_load_lds_dwordx4 v[106:107], off
	s_mov_b64 s[16:17], 0x589e080
	s_add_u32 m0, s100, 0x1000
	v_lshl_add_u64 v[106:107], v[252:253], 0, s[16:17]
	global_load_lds_dwordx4 v[106:107], off
	s_mov_b64 s[16:17], 0x58ca080
	s_add_u32 m0, s100, 0x2000
	v_lshl_add_u64 v[106:107], v[252:253], 0, s[16:17]
	global_load_lds_dwordx4 v[106:107], off
	s_mov_b64 s[16:17], 0x58f6080
	s_add_u32 m0, s100, 0x3000
	v_lshl_add_u64 v[106:107], v[252:253], 0, s[16:17]
	global_load_lds_dwordx4 v[106:107], off
	s_mov_b64 s[16:17], 0x5922080
	s_add_u32 m0, s100, 0x4000
	v_lshl_add_u64 v[106:107], v[252:253], 0, s[16:17]
	global_load_lds_dwordx4 v[106:107], off
	s_mov_b64 s[16:17], 0x594e080
	s_add_u32 m0, s100, 0x5000
	v_lshl_add_u64 v[106:107], v[252:253], 0, s[16:17]
	global_load_lds_dwordx4 v[106:107], off
	v_lshl_add_u64 v[252:253], v[252:253], 0, s[4:5]
; template <int EPI, int MI>
; DI void gemm_tile(const GemmDesc& g, int tm, int tn, char* smem) {
;     ...
;   const int rowA = wm * (32 * MI) + r, rowB = wn * 64 + r;
;   const int hk = hh ^ ((r & 7) ^ ((r >> 3) & 3));
;     ...
;   G_GLDS(0, 0);
;   asm volatile("s_waitcnt vmcnt(0)" ::: "memory");
;   __syncthreads();
;   for (int kt = 0; kt < nk; kt += 2) {
;     if (kt + 1 < nk) G_GLDS(kt + 1, 1);
;     G_COMPUTE(0);
;     asm volatile("s_waitcnt vmcnt(0)" ::: "memory");
;     __syncthreads();
;     if (kt + 1 < nk) {
;       if (kt + 2 < nk) G_GLDS(kt + 2, 0);
;       G_COMPUTE(1);
;       asm volatile("s_waitcnt vmcnt(0)" ::: "memory");
;       __syncthreads();
;     }
;   }
.Lge_noearly:
	ds_read_b128 v[236:239], v170
	ds_read_b128 v[240:243], v170 offset:4096
	ds_read_b128 v[224:227], v162 offset:24576
	v_mfma_f32_32x32x16_bf16 v[48:63], v[228:231], v[244:247], v[48:63]
	v_mfma_f32_32x32x16_bf16 v[32:47], v[228:231], v[248:251], v[32:47]
	ds_read_b128 v[228:231], v162 offset:28672
	v_mfma_f32_32x32x16_bf16 v[16:31], v[232:235], v[244:247], v[16:31]
	v_mfma_f32_32x32x16_bf16 v[0:15], v[232:235], v[248:251], v[0:15]
	s_cmp_eq_u32 s15, 42
	s_cbranch_scc1 .Lge_last
	ds_read_b128 v[232:235], v162 offset:32768
	s_waitcnt lgkmcnt(2)
	v_mfma_f32_32x32x16_bf16 v[80:95], v[224:227], v[236:239], v[80:95]
	v_mfma_f32_32x32x16_bf16 v[64:79], v[224:227], v[240:243], v[64:79]
	s_mov_b64 s[16:17], 0x1b80080
	s_add_u32 m0, s100, 0xc000
	v_lshl_add_u64 v[106:107], v[254:255], 0, s[16:17]
	global_load_lds_dwordx4 v[106:107], off
	s_mov_b64 s[16:17], 0x1bac080
	s_add_u32 m0, s100, 0xd000
	v_lshl_add_u64 v[106:107], v[254:255], 0, s[16:17]
	global_load_lds_dwordx4 v[106:107], off
	ds_read_b128 v[244:247], v171
	ds_read_b128 v[248:251], v171 offset:4096
	ds_read_b128 v[224:227], v163 offset:24576
	s_waitcnt lgkmcnt(4)
	v_mfma_f32_32x32x16_bf16 v[48:63], v[228:231], v[236:239], v[48:63]
	v_mfma_f32_32x32x16_bf16 v[32:47], v[228:231], v[240:243], v[32:47]
	s_mov_b64 s[16:17], 0x1bd8080
	s_add_u32 m0, s100, 0xe000
	v_lshl_add_u64 v[106:107], v[254:255], 0, s[16:17]
	global_load_lds_dwordx4 v[106:107], off
	s_mov_b64 s[16:17], 0x1c04080
	s_add_u32 m0, s100, 0xf000
	v_lshl_add_u64 v[106:107], v[254:255], 0, s[16:17]
	global_load_lds_dwordx4 v[106:107], off
	v_lshl_add_u64 v[254:255], v[254:255], 0, s[4:5]
	ds_read_b128 v[228:231], v163 offset:28672
	s_waitcnt lgkmcnt(4)
	v_mfma_f32_32x32x16_bf16 v[16:31], v[232:235], v[236:239], v[16:31]
	v_mfma_f32_32x32x16_bf16 v[0:15], v[232:235], v[240:243], v[0:15]
	ds_read_b128 v[232:235], v163 offset:32768
	s_waitcnt lgkmcnt(2)
	v_mfma_f32_32x32x16_bf16 v[80:95], v[224:227], v[244:247], v[80:95]
	v_mfma_f32_32x32x16_bf16 v[64:79], v[224:227], v[248:251], v[64:79]
	ds_read_b128 v[236:239], v172
	ds_read_b128 v[240:243], v172 offset:4096
	ds_read_b128 v[224:227], v164 offset:24576
	s_waitcnt lgkmcnt(4)
	v_mfma_f32_32x32x16_bf16 v[48:63], v[228:231], v[244:247], v[48:63]
	v_mfma_f32_32x32x16_bf16 v[32:47], v[228:231], v[248:251], v[32:47]
	ds_read_b128 v[228:231], v164 offset:28672
	s_waitcnt lgkmcnt(4)
	v_mfma_f32_32x32x16_bf16 v[16:31], v[232:235], v[244:247], v[16:31]
	v_mfma_f32_32x32x16_bf16 v[0:15], v[232:235], v[248:251], v[0:15]
	ds_read_b128 v[232:235], v164 offset:32768
	s_waitcnt lgkmcnt(2)
	v_mfma_f32_32x32x16_bf16 v[80:95], v[224:227], v[236:239], v[80:95]
	v_mfma_f32_32x32x16_bf16 v[64:79], v[224:227], v[240:243], v[64:79]
	ds_read_b128 v[244:247], v173
	ds_read_b128 v[248:251], v173 offset:4096
	ds_read_b128 v[224:227], v165 offset:24576
	s_waitcnt lgkmcnt(4)
	v_mfma_f32_32x32x16_bf16 v[48:63], v[228:231], v[236:239], v[48:63]
	v_mfma_f32_32x32x16_bf16 v[32:47], v[228:231], v[240:243], v[32:47]
	ds_read_b128 v[228:231], v165 offset:28672
	s_waitcnt lgkmcnt(4)
	v_mfma_f32_32x32x16_bf16 v[16:31], v[232:235], v[236:239], v[16:31]
	v_mfma_f32_32x32x16_bf16 v[0:15], v[232:235], v[240:243], v[0:15]
	ds_read_b128 v[232:235], v165 offset:32768
	s_waitcnt lgkmcnt(2)
	v_mfma_f32_32x32x16_bf16 v[80:95], v[224:227], v[244:247], v[80:95]
	v_mfma_f32_32x32x16_bf16 v[64:79], v[224:227], v[248:251], v[64:79]
	s_waitcnt lgkmcnt(0)
	s_waitcnt vmcnt(0)
	s_barrier
	s_mov_b64 s[16:17], 0x5872080
	s_add_u32 m0, s100, 0x6000
	v_lshl_add_u64 v[106:107], v[252:253], 0, s[16:17]
	global_load_lds_dwordx4 v[106:107], off
	s_mov_b64 s[16:17], 0x589e080
	s_add_u32 m0, s100, 0x7000
	v_lshl_add_u64 v[106:107], v[252:253], 0, s[16:17]
	global_load_lds_dwordx4 v[106:107], off
	s_mov_b64 s[16:17], 0x58ca080
	s_add_u32 m0, s100, 0x8000
	v_lshl_add_u64 v[106:107], v[252:253], 0, s[16:17]
	global_load_lds_dwordx4 v[106:107], off
	s_mov_b64 s[16:17], 0x58f6080
	s_add_u32 m0, s100, 0x9000
	v_lshl_add_u64 v[106:107], v[252:253], 0, s[16:17]
	global_load_lds_dwordx4 v[106:107], off
	s_mov_b64 s[16:17], 0x5922080
	s_add_u32 m0, s100, 0xa000
	v_lshl_add_u64 v[106:107], v[252:253], 0, s[16:17]
	global_load_lds_dwordx4 v[106:107], off
	s_mov_b64 s[16:17], 0x594e080
	s_add_u32 m0, s100, 0xb000
	v_lshl_add_u64 v[106:107], v[252:253], 0, s[16:17]
	global_load_lds_dwordx4 v[106:107], off
	v_lshl_add_u64 v[252:253], v[252:253], 0, s[4:5]
	ds_read_b128 v[236:239], v166 offset:49152
	ds_read_b128 v[240:243], v166 offset:53248
	ds_read_b128 v[224:227], v162
	v_mfma_f32_32x32x16_bf16 v[48:63], v[228:231], v[244:247], v[48:63]
	v_mfma_f32_32x32x16_bf16 v[32:47], v[228:231], v[248:251], v[32:47]
	ds_read_b128 v[228:231], v162 offset:4096
	v_mfma_f32_32x32x16_bf16 v[16:31], v[232:235], v[244:247], v[16:31]
	v_mfma_f32_32x32x16_bf16 v[0:15], v[232:235], v[248:251], v[0:15]
	s_add_u32 s15, s15, 2
	s_branch .Lge_loop
